# speedup vs baseline: 1.0060x; 1.0033x over previous
; template <bool ROWSS, class AL, class EPI>
; DI void gemm8(unsigned char* smem, const AL& al, const bf16_t* __restrict__ Bt, int K, int m0, int n0, const EPI& epi) {
;   const int ptid = PTID(), lane = ptid & 63, w = __builtin_amdgcn_readfirstlane(ptid >> 6), wm = w >> 1, wn = w & 1, fr = lane & 15, fq = lane >> 4;
;   f32x4 acc[4][8];
; #pragma unroll
;   for (int a = 0; a < 4; ++a)
; #pragma unroll
;     for (int b = 0; b < 8; ++b) acc[a][b] = (f32x4){0.f, 0.f, 0.f, 0.f};
;   const int sb_ = lane * 16, swz_ = sb_ ^ (((sb_ >> 9) & 1) << 5);
;   const int Rb = w * 16 + (swz_ >> 6), C0 = (swz_ & 63) >> 1;
;   const bf16_t* bp0 = Bt + (size_t)(n0 + Rb) * K + C0; const bf16_t* bp1 = bp0 + (size_t)128 * K;
;   float ss0 = 0.f, ss1 = 0.f;
;   const int nt = K >> 5;
;   const int frag = (fr * 64 + fq * 16) ^ (((fr >> 3) & 1) << 5);
;   const int aoff = wm * 4096 + frag, boff = 16384 + wn * 8192 + frag;
;     ...
;   if constexpr (ROWSS) {
;   G8_ISSUE(0); G8_ISSUE(1); G8_ISSUE(2);
;   for (int t = 0; t < nt; ++t) {
;     if (t + 2 < nt) asm volatile("s_waitcnt vmcnt(8)" ::: "memory");
;     else if (t + 1 < nt) asm volatile("s_waitcnt vmcnt(4)" ::: "memory");
;     else asm volatile("s_waitcnt vmcnt(0)" ::: "memory");
;     __builtin_amdgcn_s_barrier();
;     asm volatile("" ::: "memory");
;     const unsigned char* sa = smem + (t & 3) * 32768 + aoff;
;     const unsigned char* sb = smem + (t & 3) * 32768 + boff;
;     bf16x8 af0, af1, bfr[8];
;     af0 = *(const bf16x8*)(sa);
; #pragma unroll
;     for (int n = 0; n < 8; ++n) bfr[n] = *(const bf16x8*)(sb + n * 1024);
;     af1 = *(const bf16x8*)(sa + 1024);
;     __builtin_amdgcn_sched_barrier(0);
;     if (t + 3 < nt) G8_ISSUE(t + 3);
;     __builtin_amdgcn_sched_barrier(0);
; #pragma unroll
;     for (int n = 0; n < 8; ++n) acc[0][n] = MFMA16(bfr[n], af0, acc[0][n]);
; #pragma unroll
;     for (int n = 0; n < 8; ++n) acc[1][n] = MFMA16(bfr[n], af1, acc[1][n]);
;     __builtin_amdgcn_sched_barrier(0);
;     af0 = *(const bf16x8*)(sa + 2048); af1 = *(const bf16x8*)(sa + 3072);
;     __builtin_amdgcn_sched_barrier(0);
; #pragma unroll
;     for (int n = 0; n < 8; ++n) acc[2][n] = MFMA16(bfr[n], af0, acc[2][n]);
; #pragma unroll
;     for (int n = 0; n < 8; ++n) acc[3][n] = MFMA16(bfr[n], af1, acc[3][n]);
;     __builtin_amdgcn_sched_barrier(0);
;     if (ROWSS) {
;       float v[8];
.LBB0_342:
	s_mul_hi_i32 s2, s74, 0x55555556
	s_lshr_b32 s3, s2, 31
	s_add_i32 s2, s2, s3
	v_mov_b32_e32 v132, v204
	s_lshl_b32 s8, s2, 8
	s_mul_i32 s2, s2, 3
	s_sub_i32 s2, s74, s2
	v_readfirstlane_b32 s75, v132
	s_ashr_i32 s5, s75, 6
	v_bfe_u32 v3, v132, 2, 4
	s_lshl_b32 s4, s2, 8
	v_and_b32_e32 v2, 32, v132
	v_lshl_or_b32 v134, s5, 4, v3
	v_lshlrev_b32_e32 v15, 4, v132
	v_bitop3_b32 v144, v15, v2, 48 bitop3:0x6c
	v_add_u32_e32 v2, s4, v134
	v_mad_i64_i32 v[2:3], s[2:3], v2, s7, v[142:143]
	v_lshl_add_u64 v[2:3], v[2:3], 0, v[144:145]
	s_mov_b64 s[2:3], 0x18000
	s_lshl_b32 s9, s5, 10
	v_add_u32_e32 v6, s8, v134
	v_lshl_add_u64 v[8:9], v[2:3], 0, s[2:3]
	s_add_i32 s76, s9, 0
	v_mad_i64_i32 v[4:5], s[2:3], v6, s7, v[146:147]
	v_add_u32_e32 v6, 0x80, v6
	v_lshl_add_u64 v[4:5], v[4:5], 0, v[144:145]
	s_mov_b32 m0, s76
	v_mad_i64_i32 v[6:7], s[2:3], v6, s7, v[146:147]
	s_add_i32 s78, s76, 0x2000
	global_load_lds_dwordx4 v[4:5], off
	v_lshl_add_u64 v[6:7], v[6:7], 0, v[144:145]
	s_mov_b32 m0, s78
	s_add_i32 s79, s76, 0x4000
	global_load_lds_dwordx4 v[6:7], off
	s_mov_b32 m0, s79
	s_add_i32 s77, s76, 0x6000
	global_load_lds_dwordx4 v[2:3], off
	s_mov_b32 m0, s77
	s_add_i32 s60, s76, 0x8000
	global_load_lds_dwordx4 v[8:9], off
	v_lshl_add_u64 v[8:9], v[4:5], 0, 64
	s_mov_b32 m0, s60
	s_add_i32 s61, s76, 0xa000
	global_load_lds_dwordx4 v[8:9], off
	v_lshl_add_u64 v[8:9], v[6:7], 0, 64
	s_mov_b32 m0, s61
	s_add_i32 s62, s76, 0xc000
	global_load_lds_dwordx4 v[8:9], off
	v_lshl_add_u64 v[8:9], v[2:3], 0, 64
	s_mov_b32 m0, s62
	s_mov_b64 s[2:3], 0x18040
	s_add_i32 s63, s76, 0xe000
	global_load_lds_dwordx4 v[8:9], off
	v_lshl_add_u64 v[8:9], v[2:3], 0, s[2:3]
	s_mov_b32 m0, s63
	s_add_i32 s9, s11, s9
	global_load_lds_dwordx4 v[8:9], off
	v_lshl_add_u64 v[8:9], v[4:5], 0, s[18:19]
	s_mov_b32 m0, s9
	s_mov_b64 s[2:3], 0x18080
	global_load_lds_dwordx4 v[8:9], off
	v_lshl_add_u64 v[8:9], v[6:7], 0, s[18:19]
	s_add_i32 m0, s9, 0x2000
	s_and_b32 s33, s5, 1
	global_load_lds_dwordx4 v[8:9], off
	v_lshl_add_u64 v[8:9], v[2:3], 0, s[18:19]
	s_add_i32 m0, s9, 0x4000
	s_ashr_i32 s5, s75, 7
	global_load_lds_dwordx4 v[8:9], off
	v_lshl_add_u64 v[8:9], v[2:3], 0, s[2:3]
	s_add_i32 m0, s9, 0x6000
	v_and_b32_e32 v133, 15, v132
	global_load_lds_dwordx4 v[8:9], off
	v_lshlrev_b32_e32 v9, 2, v132
	s_lshl_b32 s80, s5, 12
	v_lshlrev_b32_e32 v8, 6, v133
	v_and_b32_e32 v135, 48, v132
	v_and_b32_e32 v9, 32, v9
	s_lshl_b32 s14, s33, 13
	v_bitop3_b32 v144, v8, v9, v135 bitop3:0x36
	s_add_i32 s2, s80, 0
	v_add_u32_e32 v8, s2, v144
	s_add_i32 s2, s14, 0
	s_waitcnt vmcnt(8)
	s_barrier
	v_add_u32_e32 v10, s2, v144
	ds_read_b128 v[16:19], v10 offset:16384
	ds_read_b128 v[20:23], v10 offset:17408
	ds_read_b128 v[24:27], v10 offset:18432
	ds_read_b128 v[28:31], v10 offset:19456
	ds_read_b128 v[32:35], v10 offset:20480
	ds_read_b128 v[36:39], v10 offset:21504
	ds_read_b128 v[40:43], v10 offset:22528
	ds_read_b128 v[44:47], v10 offset:23552
	ds_read_b128 v[48:51], v8
	ds_read_b128 v[52:55], v8 offset:1024
	s_add_i32 s2, s76, 0x18000
	v_lshl_add_u64 v[12:13], v[4:5], 0, s[20:21]
	s_mov_b32 m0, s2
	s_add_i32 s3, s76, 0x1a000
	global_load_lds_dwordx4 v[12:13], off
	v_lshl_add_u64 v[12:13], v[6:7], 0, s[20:21]
	s_mov_b32 m0, s3
	s_add_i32 s58, s76, 0x1c000
	global_load_lds_dwordx4 v[12:13], off
	v_lshl_add_u64 v[12:13], v[2:3], 0, s[20:21]
	s_mov_b32 m0, s58
	s_mov_b64 s[30:31], 0x180c0
	s_add_i32 s59, s76, 0x1e000
	global_load_lds_dwordx4 v[12:13], off
	v_lshl_add_u64 v[12:13], v[2:3], 0, s[30:31]
	s_mov_b32 m0, s59
	s_nop 0
	global_load_lds_dwordx4 v[12:13], off
	s_waitcnt lgkmcnt(0)
	v_mfma_f32_16x16x32_bf16 v[56:59], v[16:19], v[48:51], 0
	v_mfma_f32_16x16x32_bf16 v[60:63], v[20:23], v[48:51], 0
	v_mfma_f32_16x16x32_bf16 v[64:67], v[24:27], v[48:51], 0
	v_mfma_f32_16x16x32_bf16 v[68:71], v[28:31], v[48:51], 0
	v_mfma_f32_16x16x32_bf16 v[72:75], v[32:35], v[48:51], 0
	v_mfma_f32_16x16x32_bf16 v[76:79], v[36:39], v[48:51], 0
	v_mfma_f32_16x16x32_bf16 v[80:83], v[40:43], v[48:51], 0
	v_mfma_f32_16x16x32_bf16 v[48:51], v[44:47], v[48:51], 0
	v_mfma_f32_16x16x32_bf16 v[84:87], v[16:19], v[52:55], 0
	v_mfma_f32_16x16x32_bf16 v[88:91], v[20:23], v[52:55], 0
	v_mfma_f32_16x16x32_bf16 v[92:95], v[24:27], v[52:55], 0
	v_mfma_f32_16x16x32_bf16 v[96:99], v[28:31], v[52:55], 0
	v_mfma_f32_16x16x32_bf16 v[100:103], v[32:35], v[52:55], 0
	v_mfma_f32_16x16x32_bf16 v[104:107], v[36:39], v[52:55], 0
	v_mfma_f32_16x16x32_bf16 v[108:111], v[40:43], v[52:55], 0
	v_mfma_f32_16x16x32_bf16 v[52:55], v[44:47], v[52:55], 0
	ds_read_b128 v[112:115], v8 offset:2048
	ds_read_b128 v[116:119], v8 offset:3072
	s_waitcnt lgkmcnt(0)
	v_mfma_f32_16x16x32_bf16 v[120:123], v[16:19], v[112:115], 0
	v_mfma_f32_16x16x32_bf16 v[124:127], v[20:23], v[112:115], 0
	v_mfma_f32_16x16x32_bf16 v[128:131], v[24:27], v[112:115], 0
	v_mfma_f32_16x16x32_bf16 v[136:139], v[28:31], v[112:115], 0
	v_mfma_f32_16x16x32_bf16 v[148:151], v[32:35], v[112:115], 0
	v_mfma_f32_16x16x32_bf16 v[152:155], v[36:39], v[112:115], 0
	v_mfma_f32_16x16x32_bf16 v[156:159], v[40:43], v[112:115], 0
	v_mfma_f32_16x16x32_bf16 v[112:115], v[44:47], v[112:115], 0
	v_mfma_f32_16x16x32_bf16 v[16:19], v[16:19], v[116:119], 0
	v_mfma_f32_16x16x32_bf16 v[20:23], v[20:23], v[116:119], 0
	v_mfma_f32_16x16x32_bf16 v[24:27], v[24:27], v[116:119], 0
	v_mfma_f32_16x16x32_bf16 v[28:31], v[28:31], v[116:119], 0
	v_mfma_f32_16x16x32_bf16 v[32:35], v[32:35], v[116:119], 0
	v_mfma_f32_16x16x32_bf16 v[36:39], v[36:39], v[116:119], 0
	v_mfma_f32_16x16x32_bf16 v[40:43], v[40:43], v[116:119], 0
	v_mfma_f32_16x16x32_bf16 v[44:47], v[44:47], v[116:119], 0
	v_add_u32_e32 v9, 0, v15
	ds_read_b128 v[116:119], v9
	ds_read_b128 v[160:163], v9 offset:8192
	s_waitcnt vmcnt(8)
	s_barrier
; DI void unpack8(uint4 u, float* v) { v[0] = bflo(u.x); v[1] = bfhi(u.x); v[2] = bflo(u.y); v[3] = bfhi(u.y); v[4] = bflo(u.z); v[5] = bfhi(u.z); v[6] = bflo(u.w); v[7] = bfhi(u.w); }
; #define MFMA16(a, b, c) __builtin_amdgcn_mfma_f32_16x16x32_bf16((a), (b), (c), 0, 0, 0)
; template <bool ROWSS, class AL, class EPI>
; DI void gemm8(unsigned char* smem, const AL& al, const bf16_t* __restrict__ Bt, int K, int m0, int n0, const EPI& epi) {
;     ...
;     const unsigned char* sa = smem + (t & 3) * 32768 + aoff;
;     const unsigned char* sb = smem + (t & 3) * 32768 + boff;
;     bf16x8 af0, af1, bfr[8];
;     af0 = *(const bf16x8*)(sa);
; #pragma unroll
;     for (int n = 0; n < 8; ++n) bfr[n] = *(const bf16x8*)(sb + n * 1024);
;     af1 = *(const bf16x8*)(sa + 1024);
;     __builtin_amdgcn_sched_barrier(0);
;     if (t + 3 < nt) G8_ISSUE(t + 3);
;     __builtin_amdgcn_sched_barrier(0);
; #pragma unroll
;     for (int n = 0; n < 8; ++n) acc[0][n] = MFMA16(bfr[n], af0, acc[0][n]);
; #pragma unroll
;     for (int n = 0; n < 8; ++n) acc[1][n] = MFMA16(bfr[n], af1, acc[1][n]);
;     __builtin_amdgcn_sched_barrier(0);
;     af0 = *(const bf16x8*)(sa + 2048); af1 = *(const bf16x8*)(sa + 3072);
;     __builtin_amdgcn_sched_barrier(0);
; #pragma unroll
;     for (int n = 0; n < 8; ++n) acc[2][n] = MFMA16(bfr[n], af0, acc[2][n]);
; #pragma unroll
;     for (int n = 0; n < 8; ++n) acc[3][n] = MFMA16(bfr[n], af1, acc[3][n]);
;     __builtin_amdgcn_sched_barrier(0);
;     if (ROWSS) {
;       float v[8];
;       unpack8(*(const uint4*)(smem + (t & 3) * 32768 + ptid * 16), v);
; #pragma unroll
;       for (int j = 0; j < 8; ++j) ss0 += v[j] * v[j];
;       unpack8(*(const uint4*)(smem + (t & 3) * 32768 + ptid * 16 + 8192), v);
; #pragma unroll
;       for (int j = 0; j < 8; ++j) ss1 += v[j] * v[j];
	s_waitcnt lgkmcnt(0)
	v_lshlrev_b32_e32 v12, 16, v116
	v_lshlrev_b32_e32 v13, 16, v160
	v_and_b32_e32 v141, 0xffff0000, v160
	v_and_b32_e32 v140, 0xffff0000, v116
	v_pk_mul_f32 v[12:13], v[12:13], v[12:13]
	v_lshlrev_b32_e32 v171, 16, v161
	v_lshlrev_b32_e32 v170, 16, v117
	v_pk_fma_f32 v[12:13], v[140:141], v[140:141], v[12:13]
	v_and_b32_e32 v161, 0xffff0000, v161
	v_and_b32_e32 v160, 0xffff0000, v117
	v_pk_fma_f32 v[12:13], v[170:171], v[170:171], v[12:13]
	v_lshlrev_b32_e32 v117, 16, v162
	v_lshlrev_b32_e32 v116, 16, v118
	v_pk_fma_f32 v[12:13], v[160:161], v[160:161], v[12:13]
	v_and_b32_e32 v173, 0xffff0000, v162
	v_and_b32_e32 v172, 0xffff0000, v118
	v_pk_fma_f32 v[12:13], v[116:117], v[116:117], v[12:13]
	v_lshlrev_b32_e32 v175, 16, v163
	v_lshlrev_b32_e32 v174, 16, v119
	v_pk_fma_f32 v[12:13], v[172:173], v[172:173], v[12:13]
	v_and_b32_e32 v163, 0xffff0000, v163
	v_and_b32_e32 v162, 0xffff0000, v119
	v_pk_fma_f32 v[12:13], v[174:175], v[174:175], v[12:13]
	s_nop 0
	v_pk_fma_f32 v[12:13], v[162:163], v[162:163], v[12:13]
	ds_read_b128 v[116:119], v8 offset:32768
	ds_read_b128 v[160:163], v10 offset:49152
	ds_read_b128 v[170:173], v10 offset:50176
	ds_read_b128 v[174:177], v10 offset:51200
	ds_read_b128 v[178:181], v10 offset:52224
	ds_read_b128 v[182:185], v10 offset:53248
	ds_read_b128 v[186:189], v10 offset:54272
	ds_read_b128 v[190:193], v10 offset:55296
	ds_read_b128 v[194:197], v10 offset:56320
	ds_read_b128 v[198:201], v8 offset:33792
	s_mov_b32 m0, s76
	v_lshl_add_u64 v[140:141], v[4:5], 0, s[22:23]
	global_load_lds_dwordx4 v[140:141], off
	v_lshl_add_u64 v[140:141], v[6:7], 0, s[22:23]
	s_mov_b32 m0, s78
	s_mov_b64 s[30:31], 0x18100
	global_load_lds_dwordx4 v[140:141], off
	v_lshl_add_u64 v[140:141], v[2:3], 0, s[22:23]
	s_mov_b32 m0, s79
	s_nop 0
	global_load_lds_dwordx4 v[140:141], off
	v_lshl_add_u64 v[140:141], v[2:3], 0, s[30:31]
	s_mov_b32 m0, s77
	s_nop 0
	global_load_lds_dwordx4 v[140:141], off
	s_waitcnt lgkmcnt(0)
	v_mfma_f32_16x16x32_bf16 v[56:59], v[160:163], v[116:119], v[56:59]
	v_mfma_f32_16x16x32_bf16 v[60:63], v[170:173], v[116:119], v[60:63]
	v_mfma_f32_16x16x32_bf16 v[64:67], v[174:177], v[116:119], v[64:67]
	v_mfma_f32_16x16x32_bf16 v[68:71], v[178:181], v[116:119], v[68:71]
	v_mfma_f32_16x16x32_bf16 v[72:75], v[182:185], v[116:119], v[72:75]
	v_mfma_f32_16x16x32_bf16 v[76:79], v[186:189], v[116:119], v[76:79]
	v_mfma_f32_16x16x32_bf16 v[80:83], v[190:193], v[116:119], v[80:83]
	v_mfma_f32_16x16x32_bf16 v[48:51], v[194:197], v[116:119], v[48:51]
	ds_read_b128 v[116:119], v8 offset:34816
	v_mfma_f32_16x16x32_bf16 v[84:87], v[160:163], v[198:201], v[84:87]
	v_mfma_f32_16x16x32_bf16 v[88:91], v[170:173], v[198:201], v[88:91]
	v_mfma_f32_16x16x32_bf16 v[92:95], v[174:177], v[198:201], v[92:95]
	v_mfma_f32_16x16x32_bf16 v[96:99], v[178:181], v[198:201], v[96:99]
	v_mfma_f32_16x16x32_bf16 v[100:103], v[182:185], v[198:201], v[100:103]
	v_mfma_f32_16x16x32_bf16 v[104:107], v[186:189], v[198:201], v[104:107]
	v_mfma_f32_16x16x32_bf16 v[108:111], v[190:193], v[198:201], v[108:111]
	v_mfma_f32_16x16x32_bf16 v[52:55], v[194:197], v[198:201], v[52:55]
	ds_read_b128 v[198:201], v8 offset:35840
	s_waitcnt lgkmcnt(1)
	v_mfma_f32_16x16x32_bf16 v[120:123], v[160:163], v[116:119], v[120:123]
	v_mfma_f32_16x16x32_bf16 v[124:127], v[170:173], v[116:119], v[124:127]
	v_mfma_f32_16x16x32_bf16 v[128:131], v[174:177], v[116:119], v[128:131]
	v_mfma_f32_16x16x32_bf16 v[136:139], v[178:181], v[116:119], v[136:139]
	v_mfma_f32_16x16x32_bf16 v[112:115], v[194:197], v[116:119], v[112:115]
	s_waitcnt lgkmcnt(0)
	v_mfma_f32_16x16x32_bf16 v[16:19], v[160:163], v[198:201], v[16:19]
	v_mfma_f32_16x16x32_bf16 v[20:23], v[170:173], v[198:201], v[20:23]
	v_mfma_f32_16x16x32_bf16 v[24:27], v[174:177], v[198:201], v[24:27]
	v_mfma_f32_16x16x32_bf16 v[28:31], v[178:181], v[198:201], v[28:31]
	v_mfma_f32_16x16x32_bf16 v[32:35], v[182:185], v[198:201], v[32:35]
	v_mfma_f32_16x16x32_bf16 v[36:39], v[186:189], v[198:201], v[36:39]
	v_mfma_f32_16x16x32_bf16 v[40:43], v[190:193], v[198:201], v[40:43]
	v_mfma_f32_16x16x32_bf16 v[44:47], v[194:197], v[198:201], v[44:47]
	v_mfma_f32_16x16x32_bf16 v[148:151], v[182:185], v[116:119], v[148:151]
	v_mfma_f32_16x16x32_bf16 v[152:155], v[186:189], v[116:119], v[152:155]
	v_mfma_f32_16x16x32_bf16 v[156:159], v[190:193], v[116:119], v[156:159]
	ds_read_b128 v[116:119], v9 offset:32768
	ds_read_b128 v[160:163], v9 offset:40960
	s_add_i32 s9, s11, s80
	s_waitcnt vmcnt(8)
	s_barrier
; DI void unpack8(uint4 u, float* v) { v[0] = bflo(u.x); v[1] = bfhi(u.x); v[2] = bflo(u.y); v[3] = bfhi(u.y); v[4] = bflo(u.z); v[5] = bfhi(u.z); v[6] = bflo(u.w); v[7] = bfhi(u.w); }
; #define MFMA16(a, b, c) __builtin_amdgcn_mfma_f32_16x16x32_bf16((a), (b), (c), 0, 0, 0)
; template <bool ROWSS, class AL, class EPI>
; DI void gemm8(unsigned char* smem, const AL& al, const bf16_t* __restrict__ Bt, int K, int m0, int n0, const EPI& epi) {
;     ...
;   for (int t = 0; t < nt; ++t) {
;     if (t + 2 < nt) asm volatile("s_waitcnt vmcnt(8)" ::: "memory");
;     else if (t + 1 < nt) asm volatile("s_waitcnt vmcnt(4)" ::: "memory");
;     else asm volatile("s_waitcnt vmcnt(0)" ::: "memory");
;     __builtin_amdgcn_s_barrier();
;     asm volatile("" ::: "memory");
;     const unsigned char* sa = smem + (t & 3) * 32768 + aoff;
;     const unsigned char* sb = smem + (t & 3) * 32768 + boff;
;     bf16x8 af0, af1, bfr[8];
;     af0 = *(const bf16x8*)(sa);
; #pragma unroll
;     for (int n = 0; n < 8; ++n) bfr[n] = *(const bf16x8*)(sb + n * 1024);
;     af1 = *(const bf16x8*)(sa + 1024);
;     __builtin_amdgcn_sched_barrier(0);
;     if (t + 3 < nt) G8_ISSUE(t + 3);
;     __builtin_amdgcn_sched_barrier(0);
; #pragma unroll
;     for (int n = 0; n < 8; ++n) acc[0][n] = MFMA16(bfr[n], af0, acc[0][n]);
; #pragma unroll
;     for (int n = 0; n < 8; ++n) acc[1][n] = MFMA16(bfr[n], af1, acc[1][n]);
;     __builtin_amdgcn_sched_barrier(0);
;     af0 = *(const bf16x8*)(sa + 2048); af1 = *(const bf16x8*)(sa + 3072);
;     __builtin_amdgcn_sched_barrier(0);
; #pragma unroll
;     for (int n = 0; n < 8; ++n) acc[2][n] = MFMA16(bfr[n], af0, acc[2][n]);
; #pragma unroll
;     for (int n = 0; n < 8; ++n) acc[3][n] = MFMA16(bfr[n], af1, acc[3][n]);
;     __builtin_amdgcn_sched_barrier(0);
;     if (ROWSS) {
;       float v[8];
;       unpack8(*(const uint4*)(smem + (t & 3) * 32768 + ptid * 16), v);
; #pragma unroll
;       for (int j = 0; j < 8; ++j) ss0 += v[j] * v[j];
;       unpack8(*(const uint4*)(smem + (t & 3) * 32768 + ptid * 16 + 8192), v);
; #pragma unroll
;       for (int j = 0; j < 8; ++j) ss1 += v[j] * v[j];
	s_waitcnt lgkmcnt(0)
	v_lshlrev_b32_e32 v140, 16, v116
	v_lshlrev_b32_e32 v141, 16, v160
	v_and_b32_e32 v171, 0xffff0000, v160
	v_and_b32_e32 v170, 0xffff0000, v116
	v_pk_fma_f32 v[12:13], v[140:141], v[140:141], v[12:13]
	v_lshlrev_b32_e32 v173, 16, v161
	v_lshlrev_b32_e32 v172, 16, v117
	v_pk_fma_f32 v[12:13], v[170:171], v[170:171], v[12:13]
	v_and_b32_e32 v161, 0xffff0000, v161
	v_and_b32_e32 v160, 0xffff0000, v117
	v_pk_fma_f32 v[12:13], v[172:173], v[172:173], v[12:13]
	v_lshlrev_b32_e32 v117, 16, v162
	v_lshlrev_b32_e32 v116, 16, v118
	v_pk_fma_f32 v[12:13], v[160:161], v[160:161], v[12:13]
	v_and_b32_e32 v175, 0xffff0000, v162
	v_and_b32_e32 v174, 0xffff0000, v118
	v_pk_fma_f32 v[12:13], v[116:117], v[116:117], v[12:13]
	v_lshlrev_b32_e32 v177, 16, v163
	v_lshlrev_b32_e32 v176, 16, v119
	v_pk_fma_f32 v[12:13], v[174:175], v[174:175], v[12:13]
	v_and_b32_e32 v163, 0xffff0000, v163
	v_and_b32_e32 v162, 0xffff0000, v119
	v_pk_fma_f32 v[12:13], v[176:177], v[176:177], v[12:13]
	v_add_u32_e32 v11, s9, v144
	s_add_i32 s9, s11, s14
	v_pk_fma_f32 v[140:141], v[162:163], v[162:163], v[12:13]
	v_add_u32_e32 v14, s9, v144
	ds_read_b128 v[116:119], v11
	ds_read_b128 v[160:163], v14 offset:16384
	ds_read_b128 v[170:173], v14 offset:17408
	ds_read_b128 v[174:177], v14 offset:18432
	ds_read_b128 v[178:181], v14 offset:19456
	ds_read_b128 v[182:185], v14 offset:20480
	ds_read_b128 v[186:189], v14 offset:21504
	ds_read_b128 v[190:193], v14 offset:22528
	ds_read_b128 v[194:197], v14 offset:23552
	ds_read_b128 v[198:201], v11 offset:1024
	s_mov_b32 m0, s60
	v_lshl_add_u64 v[12:13], v[4:5], 0, s[24:25]
	global_load_lds_dwordx4 v[12:13], off
	v_lshl_add_u64 v[12:13], v[6:7], 0, s[24:25]
	s_mov_b32 m0, s61
	s_mov_b64 s[30:31], 0x18140
	global_load_lds_dwordx4 v[12:13], off
	v_lshl_add_u64 v[12:13], v[2:3], 0, s[24:25]
	s_mov_b32 m0, s62
	s_nop 0
	global_load_lds_dwordx4 v[12:13], off
	v_lshl_add_u64 v[12:13], v[2:3], 0, s[30:31]
	s_mov_b32 m0, s63
	s_nop 0
	global_load_lds_dwordx4 v[12:13], off
	s_waitcnt lgkmcnt(0)
	v_mfma_f32_16x16x32_bf16 v[56:59], v[160:163], v[116:119], v[56:59]
	v_mfma_f32_16x16x32_bf16 v[60:63], v[170:173], v[116:119], v[60:63]
	v_mfma_f32_16x16x32_bf16 v[68:71], v[178:181], v[116:119], v[68:71]
	v_mfma_f32_16x16x32_bf16 v[72:75], v[182:185], v[116:119], v[72:75]
	v_mfma_f32_16x16x32_bf16 v[76:79], v[186:189], v[116:119], v[76:79]
	v_mfma_f32_16x16x32_bf16 v[80:83], v[190:193], v[116:119], v[80:83]
	v_mfma_f32_16x16x32_bf16 v[48:51], v[194:197], v[116:119], v[48:51]
	v_mfma_f32_16x16x32_bf16 v[84:87], v[160:163], v[198:201], v[84:87]
	v_mfma_f32_16x16x32_bf16 v[88:91], v[170:173], v[198:201], v[88:91]
	v_mfma_f32_16x16x32_bf16 v[92:95], v[174:177], v[198:201], v[92:95]
	v_mfma_f32_16x16x32_bf16 v[96:99], v[178:181], v[198:201], v[96:99]
	v_mfma_f32_16x16x32_bf16 v[100:103], v[182:185], v[198:201], v[100:103]
	v_mfma_f32_16x16x32_bf16 v[104:107], v[186:189], v[198:201], v[104:107]
	v_mfma_f32_16x16x32_bf16 v[108:111], v[190:193], v[198:201], v[108:111]
	v_mfma_f32_16x16x32_bf16 v[52:55], v[194:197], v[198:201], v[52:55]
	v_mfma_f32_16x16x32_bf16 v[206:209], v[174:177], v[116:119], v[64:67]
	s_nop 2
	ds_read_b128 v[64:67], v11 offset:2048
	ds_read_b128 v[116:119], v11 offset:3072
	s_waitcnt lgkmcnt(0)
	v_mfma_f32_16x16x32_bf16 v[120:123], v[160:163], v[64:67], v[120:123]
	v_mfma_f32_16x16x32_bf16 v[124:127], v[170:173], v[64:67], v[124:127]
	v_mfma_f32_16x16x32_bf16 v[128:131], v[174:177], v[64:67], v[128:131]
	v_mfma_f32_16x16x32_bf16 v[136:139], v[178:181], v[64:67], v[136:139]
	v_mfma_f32_16x16x32_bf16 v[112:115], v[194:197], v[64:67], v[112:115]
	v_mfma_f32_16x16x32_bf16 v[16:19], v[160:163], v[116:119], v[16:19]
	v_mfma_f32_16x16x32_bf16 v[20:23], v[170:173], v[116:119], v[20:23]
	v_mfma_f32_16x16x32_bf16 v[24:27], v[174:177], v[116:119], v[24:27]
	v_mfma_f32_16x16x32_bf16 v[28:31], v[178:181], v[116:119], v[28:31]
	v_mfma_f32_16x16x32_bf16 v[32:35], v[182:185], v[116:119], v[32:35]
	v_mfma_f32_16x16x32_bf16 v[36:39], v[186:189], v[116:119], v[36:39]
	v_mfma_f32_16x16x32_bf16 v[40:43], v[190:193], v[116:119], v[40:43]
	v_mfma_f32_16x16x32_bf16 v[44:47], v[194:197], v[116:119], v[44:47]
	v_mfma_f32_16x16x32_bf16 v[148:151], v[182:185], v[64:67], v[148:151]
	v_mfma_f32_16x16x32_bf16 v[152:155], v[186:189], v[64:67], v[152:155]
	v_mfma_f32_16x16x32_bf16 v[156:159], v[190:193], v[64:67], v[156:159]
	v_add_u32_e32 v13, s11, v15
	ds_read_b128 v[64:67], v13
	ds_read_b128 v[116:119], v13 offset:8192
	s_add_i32 s9, 0, 0x18000
	s_add_i32 s30, s9, s80
	s_waitcnt vmcnt(8)
	s_waitcnt lgkmcnt(0)
	v_lshlrev_b32_e32 v160, 16, v64
	v_lshlrev_b32_e32 v161, 16, v116
	v_and_b32_e32 v163, 0xffff0000, v116
	v_and_b32_e32 v162, 0xffff0000, v64
	v_lshlrev_b32_e32 v170, 16, v65
	v_and_b32_e32 v116, 0xffff0000, v65
	v_lshlrev_b32_e32 v65, 16, v118
	v_lshlrev_b32_e32 v64, 16, v66
	v_and_b32_e32 v173, 0xffff0000, v118
	v_and_b32_e32 v172, 0xffff0000, v66
	v_lshlrev_b32_e32 v174, 16, v67
	v_and_b32_e32 v118, 0xffff0000, v67
	v_pk_fma_f32 v[66:67], v[160:161], v[160:161], v[140:141]
	v_lshlrev_b32_e32 v171, 16, v117
	v_pk_fma_f32 v[66:67], v[162:163], v[162:163], v[66:67]
	v_and_b32_e32 v117, 0xffff0000, v117
	v_pk_fma_f32 v[66:67], v[170:171], v[170:171], v[66:67]
	v_lshlrev_b32_e32 v175, 16, v119
	v_pk_fma_f32 v[66:67], v[116:117], v[116:117], v[66:67]
	v_and_b32_e32 v119, 0xffff0000, v119
	v_pk_fma_f32 v[64:65], v[64:65], v[64:65], v[66:67]
	s_barrier
; DI void unpack8(uint4 u, float* v) { v[0] = bflo(u.x); v[1] = bfhi(u.x); v[2] = bflo(u.y); v[3] = bfhi(u.y); v[4] = bflo(u.z); v[5] = bfhi(u.z); v[6] = bflo(u.w); v[7] = bfhi(u.w); }
; #define MFMA16(a, b, c) __builtin_amdgcn_mfma_f32_16x16x32_bf16((a), (b), (c), 0, 0, 0)
; template <bool ROWSS, class AL, class EPI>
; DI void gemm8(unsigned char* smem, const AL& al, const bf16_t* __restrict__ Bt, int K, int m0, int n0, const EPI& epi) {
;     ...
;   for (int t = 0; t < nt; ++t) {
;     if (t + 2 < nt) asm volatile("s_waitcnt vmcnt(8)" ::: "memory");
;     else if (t + 1 < nt) asm volatile("s_waitcnt vmcnt(4)" ::: "memory");
;     else asm volatile("s_waitcnt vmcnt(0)" ::: "memory");
;     __builtin_amdgcn_s_barrier();
;     asm volatile("" ::: "memory");
;     const unsigned char* sa = smem + (t & 3) * 32768 + aoff;
;     const unsigned char* sb = smem + (t & 3) * 32768 + boff;
;     bf16x8 af0, af1, bfr[8];
;     af0 = *(const bf16x8*)(sa);
; #pragma unroll
;     for (int n = 0; n < 8; ++n) bfr[n] = *(const bf16x8*)(sb + n * 1024);
;     af1 = *(const bf16x8*)(sa + 1024);
;     __builtin_amdgcn_sched_barrier(0);
;     if (t + 3 < nt) G8_ISSUE(t + 3);
;     __builtin_amdgcn_sched_barrier(0);
; #pragma unroll
;     for (int n = 0; n < 8; ++n) acc[0][n] = MFMA16(bfr[n], af0, acc[0][n]);
; #pragma unroll
;     for (int n = 0; n < 8; ++n) acc[1][n] = MFMA16(bfr[n], af1, acc[1][n]);
;     __builtin_amdgcn_sched_barrier(0);
;     af0 = *(const bf16x8*)(sa + 2048); af1 = *(const bf16x8*)(sa + 3072);
;     __builtin_amdgcn_sched_barrier(0);
; #pragma unroll
;     for (int n = 0; n < 8; ++n) acc[2][n] = MFMA16(bfr[n], af0, acc[2][n]);
; #pragma unroll
;     for (int n = 0; n < 8; ++n) acc[3][n] = MFMA16(bfr[n], af1, acc[3][n]);
;     __builtin_amdgcn_sched_barrier(0);
;     if (ROWSS) {
;       float v[8];
;       unpack8(*(const uint4*)(smem + (t & 3) * 32768 + ptid * 16), v);
; #pragma unroll
;       for (int j = 0; j < 8; ++j) ss0 += v[j] * v[j];
;       unpack8(*(const uint4*)(smem + (t & 3) * 32768 + ptid * 16 + 8192), v);
; #pragma unroll
;       for (int j = 0; j < 8; ++j) ss1 += v[j] * v[j];
	v_pk_fma_f32 v[64:65], v[172:173], v[172:173], v[64:65]
	v_add_u32_e32 v66, s30, v144
	v_pk_fma_f32 v[64:65], v[174:175], v[174:175], v[64:65]
	s_add_i32 s14, s9, s14
	v_pk_fma_f32 v[64:65], v[118:119], v[118:119], v[64:65]
	v_add_u32_e32 v12, s14, v144
	ds_read_b128 v[116:119], v66
	ds_read_b128 v[160:163], v12 offset:16384
	ds_read_b128 v[170:173], v12 offset:17408
	ds_read_b128 v[174:177], v12 offset:18432
	ds_read_b128 v[178:181], v12 offset:19456
	ds_read_b128 v[182:185], v12 offset:20480
	ds_read_b128 v[186:189], v12 offset:21504
	ds_read_b128 v[190:193], v12 offset:22528
	ds_read_b128 v[194:197], v12 offset:23552
	ds_read_b128 v[198:201], v66 offset:1024
	s_add_i32 s80, s76, 0x10000
	v_lshl_add_u64 v[140:141], v[4:5], 0, s[26:27]
	s_mov_b32 m0, s80
	s_add_i32 s82, s76, 0x12000
	global_load_lds_dwordx4 v[140:141], off
	v_lshl_add_u64 v[140:141], v[6:7], 0, s[26:27]
	s_mov_b32 m0, s82
	s_add_i32 s83, s76, 0x14000
	global_load_lds_dwordx4 v[140:141], off
	v_lshl_add_u64 v[140:141], v[2:3], 0, s[26:27]
	s_mov_b32 m0, s83
	s_mov_b64 s[30:31], 0x18180
	s_add_i32 s84, s76, 0x16000
	global_load_lds_dwordx4 v[140:141], off
	v_lshl_add_u64 v[140:141], v[2:3], 0, s[30:31]
	s_mov_b32 m0, s84
	s_nop 0
	global_load_lds_dwordx4 v[140:141], off
	s_waitcnt lgkmcnt(0)
	v_mfma_f32_16x16x32_bf16 v[56:59], v[160:163], v[116:119], v[56:59]
	v_mfma_f32_16x16x32_bf16 v[60:63], v[170:173], v[116:119], v[60:63]
	v_mfma_f32_16x16x32_bf16 v[68:71], v[178:181], v[116:119], v[68:71]
	v_mfma_f32_16x16x32_bf16 v[72:75], v[182:185], v[116:119], v[72:75]
	v_mfma_f32_16x16x32_bf16 v[76:79], v[186:189], v[116:119], v[76:79]
	v_mfma_f32_16x16x32_bf16 v[80:83], v[190:193], v[116:119], v[80:83]
	v_mfma_f32_16x16x32_bf16 v[48:51], v[194:197], v[116:119], v[48:51]
	v_mfma_f32_16x16x32_bf16 v[84:87], v[160:163], v[198:201], v[84:87]
	v_mfma_f32_16x16x32_bf16 v[88:91], v[170:173], v[198:201], v[88:91]
	v_mfma_f32_16x16x32_bf16 v[92:95], v[174:177], v[198:201], v[92:95]
	v_mfma_f32_16x16x32_bf16 v[96:99], v[178:181], v[198:201], v[96:99]
	v_mfma_f32_16x16x32_bf16 v[100:103], v[182:185], v[198:201], v[100:103]
	v_mfma_f32_16x16x32_bf16 v[104:107], v[186:189], v[198:201], v[104:107]
	v_mfma_f32_16x16x32_bf16 v[108:111], v[190:193], v[198:201], v[108:111]
	v_mfma_f32_16x16x32_bf16 v[52:55], v[194:197], v[198:201], v[52:55]
	v_mfma_f32_16x16x32_bf16 v[206:209], v[174:177], v[116:119], v[206:209]
	ds_read_b128 v[116:119], v66 offset:2048
	ds_read_b128 v[198:201], v66 offset:3072
	s_waitcnt lgkmcnt(0)
	v_mfma_f32_16x16x32_bf16 v[120:123], v[160:163], v[116:119], v[120:123]
	v_mfma_f32_16x16x32_bf16 v[124:127], v[170:173], v[116:119], v[124:127]
	v_mfma_f32_16x16x32_bf16 v[128:131], v[174:177], v[116:119], v[128:131]
	v_mfma_f32_16x16x32_bf16 v[112:115], v[194:197], v[116:119], v[112:115]
	v_mfma_f32_16x16x32_bf16 v[16:19], v[160:163], v[198:201], v[16:19]
	v_mfma_f32_16x16x32_bf16 v[20:23], v[170:173], v[198:201], v[20:23]
	v_mfma_f32_16x16x32_bf16 v[24:27], v[174:177], v[198:201], v[24:27]
	v_mfma_f32_16x16x32_bf16 v[28:31], v[178:181], v[198:201], v[28:31]
	v_mfma_f32_16x16x32_bf16 v[32:35], v[182:185], v[198:201], v[32:35]
	v_mfma_f32_16x16x32_bf16 v[36:39], v[186:189], v[198:201], v[36:39]
	v_mfma_f32_16x16x32_bf16 v[40:43], v[190:193], v[198:201], v[40:43]
	v_mfma_f32_16x16x32_bf16 v[44:47], v[194:197], v[198:201], v[44:47]
	v_mfma_f32_16x16x32_bf16 v[138:141], v[178:181], v[116:119], v[136:139]
	v_mfma_f32_16x16x32_bf16 v[148:151], v[182:185], v[116:119], v[148:151]
	v_mfma_f32_16x16x32_bf16 v[152:155], v[186:189], v[116:119], v[152:155]
	v_mfma_f32_16x16x32_bf16 v[156:159], v[190:193], v[116:119], v[156:159]
	v_add_u32_e32 v136, s9, v15
	ds_read_b128 v[116:119], v136
	ds_read_b128 v[160:163], v136 offset:8192
	s_waitcnt vmcnt(8)
	s_barrier
	s_waitcnt lgkmcnt(0)
	v_lshlrev_b32_e32 v170, 16, v116
	v_lshlrev_b32_e32 v171, 16, v160
	v_and_b32_e32 v173, 0xffff0000, v160
	v_and_b32_e32 v172, 0xffff0000, v116
	v_pk_fma_f32 v[64:65], v[170:171], v[170:171], v[64:65]
	v_lshlrev_b32_e32 v175, 16, v161
	v_lshlrev_b32_e32 v174, 16, v117
	v_pk_fma_f32 v[64:65], v[172:173], v[172:173], v[64:65]
	v_and_b32_e32 v161, 0xffff0000, v161
	v_and_b32_e32 v160, 0xffff0000, v117
	v_pk_fma_f32 v[64:65], v[174:175], v[174:175], v[64:65]
	v_lshlrev_b32_e32 v117, 16, v162
	v_lshlrev_b32_e32 v116, 16, v118
	v_pk_fma_f32 v[64:65], v[160:161], v[160:161], v[64:65]
	v_and_b32_e32 v177, 0xffff0000, v162
	v_and_b32_e32 v176, 0xffff0000, v118
	v_pk_fma_f32 v[64:65], v[116:117], v[116:117], v[64:65]
	v_lshlrev_b32_e32 v179, 16, v163
	v_lshlrev_b32_e32 v178, 16, v119
	v_pk_fma_f32 v[64:65], v[176:177], v[176:177], v[64:65]
	v_and_b32_e32 v163, 0xffff0000, v163
	v_and_b32_e32 v162, 0xffff0000, v119
	v_pk_fma_f32 v[64:65], v[178:179], v[178:179], v[64:65]
	s_nop 0
	v_pk_fma_f32 v[64:65], v[162:163], v[162:163], v[64:65]
	ds_read_b128 v[116:119], v8
	ds_read_b128 v[160:163], v10 offset:16384
	ds_read_b128 v[170:173], v10 offset:17408
	ds_read_b128 v[174:177], v10 offset:18432
	ds_read_b128 v[178:181], v10 offset:19456
	ds_read_b128 v[182:185], v10 offset:20480
	ds_read_b128 v[186:189], v10 offset:21504
	ds_read_b128 v[190:193], v10 offset:22528
	ds_read_b128 v[194:197], v10 offset:23552
	ds_read_b128 v[198:201], v8 offset:1024
	s_mov_b32 m0, s2
	v_lshl_add_u64 v[202:203], v[4:5], 0, s[38:39]
	global_load_lds_dwordx4 v[202:203], off
	v_lshl_add_u64 v[202:203], v[6:7], 0, s[38:39]
	s_mov_b32 m0, s3
	s_mov_b64 s[30:31], 0x181c0
	global_load_lds_dwordx4 v[202:203], off
	v_lshl_add_u64 v[202:203], v[2:3], 0, s[38:39]
	s_mov_b32 m0, s58
	s_nop 0
	global_load_lds_dwordx4 v[202:203], off
	v_lshl_add_u64 v[202:203], v[2:3], 0, s[30:31]
	s_mov_b32 m0, s59
	s_nop 0
	global_load_lds_dwordx4 v[202:203], off
	s_waitcnt lgkmcnt(0)
; DI void unpack8(uint4 u, float* v) { v[0] = bflo(u.x); v[1] = bfhi(u.x); v[2] = bflo(u.y); v[3] = bfhi(u.y); v[4] = bflo(u.z); v[5] = bfhi(u.z); v[6] = bflo(u.w); v[7] = bfhi(u.w); }
; #define MFMA16(a, b, c) __builtin_amdgcn_mfma_f32_16x16x32_bf16((a), (b), (c), 0, 0, 0)
; template <bool ROWSS, class AL, class EPI>
; DI void gemm8(unsigned char* smem, const AL& al, const bf16_t* __restrict__ Bt, int K, int m0, int n0, const EPI& epi) {
;     ...
;   for (int t = 0; t < nt; ++t) {
;     if (t + 2 < nt) asm volatile("s_waitcnt vmcnt(8)" ::: "memory");
;     else if (t + 1 < nt) asm volatile("s_waitcnt vmcnt(4)" ::: "memory");
;     else asm volatile("s_waitcnt vmcnt(0)" ::: "memory");
;     __builtin_amdgcn_s_barrier();
;     asm volatile("" ::: "memory");
;     const unsigned char* sa = smem + (t & 3) * 32768 + aoff;
;     const unsigned char* sb = smem + (t & 3) * 32768 + boff;
;     bf16x8 af0, af1, bfr[8];
;     af0 = *(const bf16x8*)(sa);
; #pragma unroll
;     for (int n = 0; n < 8; ++n) bfr[n] = *(const bf16x8*)(sb + n * 1024);
;     af1 = *(const bf16x8*)(sa + 1024);
;     __builtin_amdgcn_sched_barrier(0);
;     if (t + 3 < nt) G8_ISSUE(t + 3);
;     __builtin_amdgcn_sched_barrier(0);
; #pragma unroll
;     for (int n = 0; n < 8; ++n) acc[0][n] = MFMA16(bfr[n], af0, acc[0][n]);
; #pragma unroll
;     for (int n = 0; n < 8; ++n) acc[1][n] = MFMA16(bfr[n], af1, acc[1][n]);
;     __builtin_amdgcn_sched_barrier(0);
;     af0 = *(const bf16x8*)(sa + 2048); af1 = *(const bf16x8*)(sa + 3072);
;     __builtin_amdgcn_sched_barrier(0);
; #pragma unroll
;     for (int n = 0; n < 8; ++n) acc[2][n] = MFMA16(bfr[n], af0, acc[2][n]);
; #pragma unroll
;     for (int n = 0; n < 8; ++n) acc[3][n] = MFMA16(bfr[n], af1, acc[3][n]);
;     __builtin_amdgcn_sched_barrier(0);
;     if (ROWSS) {
;       float v[8];
;       unpack8(*(const uint4*)(smem + (t & 3) * 32768 + ptid * 16), v);
; #pragma unroll
;       for (int j = 0; j < 8; ++j) ss0 += v[j] * v[j];
;       unpack8(*(const uint4*)(smem + (t & 3) * 32768 + ptid * 16 + 8192), v);
; #pragma unroll
;       for (int j = 0; j < 8; ++j) ss1 += v[j] * v[j];
	v_mfma_f32_16x16x32_bf16 v[56:59], v[160:163], v[116:119], v[56:59]
	v_mfma_f32_16x16x32_bf16 v[60:63], v[170:173], v[116:119], v[60:63]
	v_mfma_f32_16x16x32_bf16 v[68:71], v[178:181], v[116:119], v[68:71]
	v_mfma_f32_16x16x32_bf16 v[72:75], v[182:185], v[116:119], v[72:75]
	v_mfma_f32_16x16x32_bf16 v[76:79], v[186:189], v[116:119], v[76:79]
	v_mfma_f32_16x16x32_bf16 v[80:83], v[190:193], v[116:119], v[80:83]
	v_mfma_f32_16x16x32_bf16 v[48:51], v[194:197], v[116:119], v[48:51]
	v_mfma_f32_16x16x32_bf16 v[84:87], v[160:163], v[198:201], v[84:87]
	v_mfma_f32_16x16x32_bf16 v[88:91], v[170:173], v[198:201], v[88:91]
	v_mfma_f32_16x16x32_bf16 v[92:95], v[174:177], v[198:201], v[92:95]
	v_mfma_f32_16x16x32_bf16 v[96:99], v[178:181], v[198:201], v[96:99]
	v_mfma_f32_16x16x32_bf16 v[100:103], v[182:185], v[198:201], v[100:103]
	v_mfma_f32_16x16x32_bf16 v[104:107], v[186:189], v[198:201], v[104:107]
	v_mfma_f32_16x16x32_bf16 v[108:111], v[190:193], v[198:201], v[108:111]
	v_mfma_f32_16x16x32_bf16 v[52:55], v[194:197], v[198:201], v[52:55]
	v_mfma_f32_16x16x32_bf16 v[206:209], v[174:177], v[116:119], v[206:209]
	ds_read_b128 v[116:119], v8 offset:2048
	ds_read_b128 v[198:201], v8 offset:3072
	s_waitcnt lgkmcnt(0)
	v_mfma_f32_16x16x32_bf16 v[120:123], v[160:163], v[116:119], v[120:123]
	v_mfma_f32_16x16x32_bf16 v[124:127], v[170:173], v[116:119], v[124:127]
	v_mfma_f32_16x16x32_bf16 v[128:131], v[174:177], v[116:119], v[128:131]
	v_mfma_f32_16x16x32_bf16 v[112:115], v[194:197], v[116:119], v[112:115]
	v_mfma_f32_16x16x32_bf16 v[16:19], v[160:163], v[198:201], v[16:19]
	v_mfma_f32_16x16x32_bf16 v[20:23], v[170:173], v[198:201], v[20:23]
	v_mfma_f32_16x16x32_bf16 v[24:27], v[174:177], v[198:201], v[24:27]
	v_mfma_f32_16x16x32_bf16 v[28:31], v[178:181], v[198:201], v[28:31]
	v_mfma_f32_16x16x32_bf16 v[32:35], v[182:185], v[198:201], v[32:35]
	v_mfma_f32_16x16x32_bf16 v[36:39], v[186:189], v[198:201], v[36:39]
	v_mfma_f32_16x16x32_bf16 v[40:43], v[190:193], v[198:201], v[40:43]
	v_mfma_f32_16x16x32_bf16 v[44:47], v[194:197], v[198:201], v[44:47]
	v_mfma_f32_16x16x32_bf16 v[138:141], v[178:181], v[116:119], v[138:141]
	v_mfma_f32_16x16x32_bf16 v[148:151], v[182:185], v[116:119], v[148:151]
	v_mfma_f32_16x16x32_bf16 v[152:155], v[186:189], v[116:119], v[152:155]
	v_mfma_f32_16x16x32_bf16 v[156:159], v[190:193], v[116:119], v[156:159]
	ds_read_b128 v[116:119], v9
	ds_read_b128 v[160:163], v9 offset:8192
	s_waitcnt vmcnt(8)
	s_barrier
	s_waitcnt lgkmcnt(0)
	v_lshlrev_b32_e32 v170, 16, v116
	v_lshlrev_b32_e32 v171, 16, v160
	v_and_b32_e32 v173, 0xffff0000, v160
	v_and_b32_e32 v172, 0xffff0000, v116
	v_pk_fma_f32 v[64:65], v[170:171], v[170:171], v[64:65]
	v_lshlrev_b32_e32 v175, 16, v161
	v_lshlrev_b32_e32 v174, 16, v117
	v_pk_fma_f32 v[64:65], v[172:173], v[172:173], v[64:65]
	v_and_b32_e32 v161, 0xffff0000, v161
	v_and_b32_e32 v160, 0xffff0000, v117
	v_pk_fma_f32 v[64:65], v[174:175], v[174:175], v[64:65]
	v_lshlrev_b32_e32 v117, 16, v162
	v_lshlrev_b32_e32 v116, 16, v118
	v_pk_fma_f32 v[64:65], v[160:161], v[160:161], v[64:65]
	v_and_b32_e32 v177, 0xffff0000, v162
	v_and_b32_e32 v176, 0xffff0000, v118
	v_pk_fma_f32 v[64:65], v[116:117], v[116:117], v[64:65]
	v_lshlrev_b32_e32 v179, 16, v163
	v_lshlrev_b32_e32 v178, 16, v119
	v_pk_fma_f32 v[64:65], v[176:177], v[176:177], v[64:65]
	v_and_b32_e32 v163, 0xffff0000, v163
	v_and_b32_e32 v162, 0xffff0000, v119
	v_pk_fma_f32 v[64:65], v[178:179], v[178:179], v[64:65]
	s_nop 0
	v_pk_fma_f32 v[64:65], v[162:163], v[162:163], v[64:65]
	ds_read_b128 v[116:119], v8 offset:32768
	ds_read_b128 v[160:163], v10 offset:49152
	ds_read_b128 v[170:173], v10 offset:50176
	ds_read_b128 v[174:177], v10 offset:51200
	ds_read_b128 v[178:181], v10 offset:52224
	ds_read_b128 v[182:185], v10 offset:53248
	ds_read_b128 v[186:189], v10 offset:54272
	ds_read_b128 v[190:193], v10 offset:55296
	ds_read_b128 v[194:197], v10 offset:56320
	ds_read_b128 v[198:201], v8 offset:33792
	s_mov_b32 m0, s76
	v_lshl_add_u64 v[202:203], v[4:5], 0, s[40:41]
	global_load_lds_dwordx4 v[202:203], off
	v_lshl_add_u64 v[202:203], v[6:7], 0, s[40:41]
	s_mov_b32 m0, s78
	s_mov_b64 s[30:31], 0x18200
	global_load_lds_dwordx4 v[202:203], off
	v_lshl_add_u64 v[202:203], v[2:3], 0, s[40:41]
	s_mov_b32 m0, s79
	s_nop 0
	global_load_lds_dwordx4 v[202:203], off
	v_lshl_add_u64 v[202:203], v[2:3], 0, s[30:31]
	s_mov_b32 m0, s77
	s_nop 0
	global_load_lds_dwordx4 v[202:203], off
	s_waitcnt lgkmcnt(0)
	v_mfma_f32_16x16x32_bf16 v[56:59], v[160:163], v[116:119], v[56:59]
	v_mfma_f32_16x16x32_bf16 v[60:63], v[170:173], v[116:119], v[60:63]
	v_mfma_f32_16x16x32_bf16 v[68:71], v[178:181], v[116:119], v[68:71]
	v_mfma_f32_16x16x32_bf16 v[72:75], v[182:185], v[116:119], v[72:75]
	v_mfma_f32_16x16x32_bf16 v[76:79], v[186:189], v[116:119], v[76:79]
	v_mfma_f32_16x16x32_bf16 v[80:83], v[190:193], v[116:119], v[80:83]
	v_mfma_f32_16x16x32_bf16 v[48:51], v[194:197], v[116:119], v[48:51]
	v_mfma_f32_16x16x32_bf16 v[84:87], v[160:163], v[198:201], v[84:87]
	v_mfma_f32_16x16x32_bf16 v[88:91], v[170:173], v[198:201], v[88:91]
	v_mfma_f32_16x16x32_bf16 v[92:95], v[174:177], v[198:201], v[92:95]
	v_mfma_f32_16x16x32_bf16 v[96:99], v[178:181], v[198:201], v[96:99]
	v_mfma_f32_16x16x32_bf16 v[100:103], v[182:185], v[198:201], v[100:103]
	v_mfma_f32_16x16x32_bf16 v[104:107], v[186:189], v[198:201], v[104:107]
	v_mfma_f32_16x16x32_bf16 v[108:111], v[190:193], v[198:201], v[108:111]
	v_mfma_f32_16x16x32_bf16 v[52:55], v[194:197], v[198:201], v[52:55]
	v_mfma_f32_16x16x32_bf16 v[206:209], v[174:177], v[116:119], v[206:209]
	ds_read_b128 v[116:119], v8 offset:34816
	ds_read_b128 v[198:201], v8 offset:35840
	s_waitcnt lgkmcnt(0)
	v_mfma_f32_16x16x32_bf16 v[120:123], v[160:163], v[116:119], v[120:123]
	v_mfma_f32_16x16x32_bf16 v[124:127], v[170:173], v[116:119], v[124:127]
	v_mfma_f32_16x16x32_bf16 v[128:131], v[174:177], v[116:119], v[128:131]
	v_mfma_f32_16x16x32_bf16 v[112:115], v[194:197], v[116:119], v[112:115]
	v_mfma_f32_16x16x32_bf16 v[16:19], v[160:163], v[198:201], v[16:19]
	v_mfma_f32_16x16x32_bf16 v[20:23], v[170:173], v[198:201], v[20:23]
	v_mfma_f32_16x16x32_bf16 v[24:27], v[174:177], v[198:201], v[24:27]
	v_mfma_f32_16x16x32_bf16 v[28:31], v[178:181], v[198:201], v[28:31]
	v_mfma_f32_16x16x32_bf16 v[32:35], v[182:185], v[198:201], v[32:35]
	v_mfma_f32_16x16x32_bf16 v[36:39], v[186:189], v[198:201], v[36:39]
	v_mfma_f32_16x16x32_bf16 v[40:43], v[190:193], v[198:201], v[40:43]
	v_mfma_f32_16x16x32_bf16 v[44:47], v[194:197], v[198:201], v[44:47]
	v_mfma_f32_16x16x32_bf16 v[138:141], v[178:181], v[116:119], v[138:141]
	v_mfma_f32_16x16x32_bf16 v[148:151], v[182:185], v[116:119], v[148:151]
	v_mfma_f32_16x16x32_bf16 v[152:155], v[186:189], v[116:119], v[152:155]
	v_mfma_f32_16x16x32_bf16 v[156:159], v[190:193], v[116:119], v[156:159]
	ds_read_b128 v[116:119], v9 offset:32768
	ds_read_b128 v[160:163], v9 offset:40960
	s_waitcnt vmcnt(8)
	s_barrier
; DI void unpack8(uint4 u, float* v) { v[0] = bflo(u.x); v[1] = bfhi(u.x); v[2] = bflo(u.y); v[3] = bfhi(u.y); v[4] = bflo(u.z); v[5] = bfhi(u.z); v[6] = bflo(u.w); v[7] = bfhi(u.w); }
; #define MFMA16(a, b, c) __builtin_amdgcn_mfma_f32_16x16x32_bf16((a), (b), (c), 0, 0, 0)
; template <bool ROWSS, class AL, class EPI>
; DI void gemm8(unsigned char* smem, const AL& al, const bf16_t* __restrict__ Bt, int K, int m0, int n0, const EPI& epi) {
;     ...
;   for (int t = 0; t < nt; ++t) {
;     if (t + 2 < nt) asm volatile("s_waitcnt vmcnt(8)" ::: "memory");
;     else if (t + 1 < nt) asm volatile("s_waitcnt vmcnt(4)" ::: "memory");
;     else asm volatile("s_waitcnt vmcnt(0)" ::: "memory");
;     __builtin_amdgcn_s_barrier();
;     asm volatile("" ::: "memory");
;     const unsigned char* sa = smem + (t & 3) * 32768 + aoff;
;     const unsigned char* sb = smem + (t & 3) * 32768 + boff;
;     bf16x8 af0, af1, bfr[8];
;     af0 = *(const bf16x8*)(sa);
; #pragma unroll
;     for (int n = 0; n < 8; ++n) bfr[n] = *(const bf16x8*)(sb + n * 1024);
;     af1 = *(const bf16x8*)(sa + 1024);
;     __builtin_amdgcn_sched_barrier(0);
;     if (t + 3 < nt) G8_ISSUE(t + 3);
;     __builtin_amdgcn_sched_barrier(0);
; #pragma unroll
;     for (int n = 0; n < 8; ++n) acc[0][n] = MFMA16(bfr[n], af0, acc[0][n]);
; #pragma unroll
;     for (int n = 0; n < 8; ++n) acc[1][n] = MFMA16(bfr[n], af1, acc[1][n]);
;     __builtin_amdgcn_sched_barrier(0);
;     af0 = *(const bf16x8*)(sa + 2048); af1 = *(const bf16x8*)(sa + 3072);
;     __builtin_amdgcn_sched_barrier(0);
; #pragma unroll
;     for (int n = 0; n < 8; ++n) acc[2][n] = MFMA16(bfr[n], af0, acc[2][n]);
; #pragma unroll
;     for (int n = 0; n < 8; ++n) acc[3][n] = MFMA16(bfr[n], af1, acc[3][n]);
;     __builtin_amdgcn_sched_barrier(0);
;     if (ROWSS) {
;       float v[8];
;       unpack8(*(const uint4*)(smem + (t & 3) * 32768 + ptid * 16), v);
; #pragma unroll
;       for (int j = 0; j < 8; ++j) ss0 += v[j] * v[j];
;       unpack8(*(const uint4*)(smem + (t & 3) * 32768 + ptid * 16 + 8192), v);
; #pragma unroll
;       for (int j = 0; j < 8; ++j) ss1 += v[j] * v[j];
	s_waitcnt lgkmcnt(0)
	v_lshlrev_b32_e32 v170, 16, v116
	v_lshlrev_b32_e32 v171, 16, v160
	v_and_b32_e32 v173, 0xffff0000, v160
	v_and_b32_e32 v172, 0xffff0000, v116
	v_pk_fma_f32 v[64:65], v[170:171], v[170:171], v[64:65]
	v_lshlrev_b32_e32 v175, 16, v161
	v_lshlrev_b32_e32 v174, 16, v117
	v_pk_fma_f32 v[64:65], v[172:173], v[172:173], v[64:65]
	v_and_b32_e32 v161, 0xffff0000, v161
	v_and_b32_e32 v160, 0xffff0000, v117
	v_pk_fma_f32 v[64:65], v[174:175], v[174:175], v[64:65]
	v_lshlrev_b32_e32 v117, 16, v162
	v_lshlrev_b32_e32 v116, 16, v118
	v_pk_fma_f32 v[64:65], v[160:161], v[160:161], v[64:65]
	v_and_b32_e32 v177, 0xffff0000, v162
	v_and_b32_e32 v176, 0xffff0000, v118
	v_pk_fma_f32 v[64:65], v[116:117], v[116:117], v[64:65]
	v_lshlrev_b32_e32 v179, 16, v163
	v_lshlrev_b32_e32 v178, 16, v119
	v_pk_fma_f32 v[64:65], v[176:177], v[176:177], v[64:65]
	v_and_b32_e32 v163, 0xffff0000, v163
	v_and_b32_e32 v162, 0xffff0000, v119
	v_pk_fma_f32 v[64:65], v[178:179], v[178:179], v[64:65]
	s_nop 0
	v_pk_fma_f32 v[64:65], v[162:163], v[162:163], v[64:65]
	ds_read_b128 v[116:119], v11
	ds_read_b128 v[160:163], v14 offset:16384
	ds_read_b128 v[170:173], v14 offset:17408
	ds_read_b128 v[174:177], v14 offset:18432
	ds_read_b128 v[178:181], v14 offset:19456
	ds_read_b128 v[182:185], v14 offset:20480
	ds_read_b128 v[186:189], v14 offset:21504
	ds_read_b128 v[190:193], v14 offset:22528
	ds_read_b128 v[194:197], v14 offset:23552
	ds_read_b128 v[198:201], v11 offset:1024
	s_mov_b32 m0, s60
	v_lshl_add_u64 v[202:203], v[4:5], 0, s[44:45]
	global_load_lds_dwordx4 v[202:203], off
	v_lshl_add_u64 v[202:203], v[6:7], 0, s[44:45]
	s_mov_b32 m0, s61
	s_mov_b64 s[30:31], 0x18240
	global_load_lds_dwordx4 v[202:203], off
	v_lshl_add_u64 v[202:203], v[2:3], 0, s[44:45]
	s_mov_b32 m0, s62
	s_nop 0
	global_load_lds_dwordx4 v[202:203], off
	v_lshl_add_u64 v[202:203], v[2:3], 0, s[30:31]
	s_mov_b32 m0, s63
	s_nop 0
	global_load_lds_dwordx4 v[202:203], off
	s_waitcnt lgkmcnt(0)
	v_mfma_f32_16x16x32_bf16 v[56:59], v[160:163], v[116:119], v[56:59]
	v_mfma_f32_16x16x32_bf16 v[60:63], v[170:173], v[116:119], v[60:63]
	v_mfma_f32_16x16x32_bf16 v[68:71], v[178:181], v[116:119], v[68:71]
	v_mfma_f32_16x16x32_bf16 v[72:75], v[182:185], v[116:119], v[72:75]
	v_mfma_f32_16x16x32_bf16 v[76:79], v[186:189], v[116:119], v[76:79]
	v_mfma_f32_16x16x32_bf16 v[80:83], v[190:193], v[116:119], v[80:83]
	v_mfma_f32_16x16x32_bf16 v[48:51], v[194:197], v[116:119], v[48:51]
	v_mfma_f32_16x16x32_bf16 v[84:87], v[160:163], v[198:201], v[84:87]
	v_mfma_f32_16x16x32_bf16 v[88:91], v[170:173], v[198:201], v[88:91]
	v_mfma_f32_16x16x32_bf16 v[92:95], v[174:177], v[198:201], v[92:95]
	v_mfma_f32_16x16x32_bf16 v[96:99], v[178:181], v[198:201], v[96:99]
	v_mfma_f32_16x16x32_bf16 v[100:103], v[182:185], v[198:201], v[100:103]
	v_mfma_f32_16x16x32_bf16 v[104:107], v[186:189], v[198:201], v[104:107]
	v_mfma_f32_16x16x32_bf16 v[108:111], v[190:193], v[198:201], v[108:111]
	v_mfma_f32_16x16x32_bf16 v[52:55], v[194:197], v[198:201], v[52:55]
	v_mfma_f32_16x16x32_bf16 v[206:209], v[174:177], v[116:119], v[206:209]
	ds_read_b128 v[116:119], v11 offset:2048
	ds_read_b128 v[198:201], v11 offset:3072
	s_waitcnt lgkmcnt(0)
	v_mfma_f32_16x16x32_bf16 v[120:123], v[160:163], v[116:119], v[120:123]
	v_mfma_f32_16x16x32_bf16 v[124:127], v[170:173], v[116:119], v[124:127]
	v_mfma_f32_16x16x32_bf16 v[128:131], v[174:177], v[116:119], v[128:131]
	v_mfma_f32_16x16x32_bf16 v[112:115], v[194:197], v[116:119], v[112:115]
	v_mfma_f32_16x16x32_bf16 v[16:19], v[160:163], v[198:201], v[16:19]
	v_mfma_f32_16x16x32_bf16 v[20:23], v[170:173], v[198:201], v[20:23]
	v_mfma_f32_16x16x32_bf16 v[24:27], v[174:177], v[198:201], v[24:27]
	v_mfma_f32_16x16x32_bf16 v[28:31], v[178:181], v[198:201], v[28:31]
	v_mfma_f32_16x16x32_bf16 v[32:35], v[182:185], v[198:201], v[32:35]
	v_mfma_f32_16x16x32_bf16 v[36:39], v[186:189], v[198:201], v[36:39]
	v_mfma_f32_16x16x32_bf16 v[40:43], v[190:193], v[198:201], v[40:43]
	v_mfma_f32_16x16x32_bf16 v[44:47], v[194:197], v[198:201], v[44:47]
	v_mfma_f32_16x16x32_bf16 v[138:141], v[178:181], v[116:119], v[138:141]
	v_mfma_f32_16x16x32_bf16 v[148:151], v[182:185], v[116:119], v[148:151]
	v_mfma_f32_16x16x32_bf16 v[152:155], v[186:189], v[116:119], v[152:155]
	v_mfma_f32_16x16x32_bf16 v[156:159], v[190:193], v[116:119], v[156:159]
	ds_read_b128 v[116:119], v13 offset:8192
	ds_read_b128 v[160:163], v13
	s_waitcnt vmcnt(8)
	s_barrier
; DI void unpack8(uint4 u, float* v) { v[0] = bflo(u.x); v[1] = bfhi(u.x); v[2] = bflo(u.y); v[3] = bfhi(u.y); v[4] = bflo(u.z); v[5] = bfhi(u.z); v[6] = bflo(u.w); v[7] = bfhi(u.w); }
; #define MFMA16(a, b, c) __builtin_amdgcn_mfma_f32_16x16x32_bf16((a), (b), (c), 0, 0, 0)
; template <bool ROWSS, class AL, class EPI>
; DI void gemm8(unsigned char* smem, const AL& al, const bf16_t* __restrict__ Bt, int K, int m0, int n0, const EPI& epi) {
;     ...
;   for (int t = 0; t < nt; ++t) {
;     if (t + 2 < nt) asm volatile("s_waitcnt vmcnt(8)" ::: "memory");
;     else if (t + 1 < nt) asm volatile("s_waitcnt vmcnt(4)" ::: "memory");
;     else asm volatile("s_waitcnt vmcnt(0)" ::: "memory");
;     __builtin_amdgcn_s_barrier();
;     asm volatile("" ::: "memory");
;     const unsigned char* sa = smem + (t & 3) * 32768 + aoff;
;     const unsigned char* sb = smem + (t & 3) * 32768 + boff;
;     bf16x8 af0, af1, bfr[8];
;     af0 = *(const bf16x8*)(sa);
; #pragma unroll
;     for (int n = 0; n < 8; ++n) bfr[n] = *(const bf16x8*)(sb + n * 1024);
;     af1 = *(const bf16x8*)(sa + 1024);
;     __builtin_amdgcn_sched_barrier(0);
;     if (t + 3 < nt) G8_ISSUE(t + 3);
;     __builtin_amdgcn_sched_barrier(0);
; #pragma unroll
;     for (int n = 0; n < 8; ++n) acc[0][n] = MFMA16(bfr[n], af0, acc[0][n]);
; #pragma unroll
;     for (int n = 0; n < 8; ++n) acc[1][n] = MFMA16(bfr[n], af1, acc[1][n]);
;     __builtin_amdgcn_sched_barrier(0);
;     af0 = *(const bf16x8*)(sa + 2048); af1 = *(const bf16x8*)(sa + 3072);
;     __builtin_amdgcn_sched_barrier(0);
; #pragma unroll
;     for (int n = 0; n < 8; ++n) acc[2][n] = MFMA16(bfr[n], af0, acc[2][n]);
; #pragma unroll
;     for (int n = 0; n < 8; ++n) acc[3][n] = MFMA16(bfr[n], af1, acc[3][n]);
;     __builtin_amdgcn_sched_barrier(0);
;     if (ROWSS) {
;       float v[8];
;       unpack8(*(const uint4*)(smem + (t & 3) * 32768 + ptid * 16), v);
; #pragma unroll
;       for (int j = 0; j < 8; ++j) ss0 += v[j] * v[j];
;       unpack8(*(const uint4*)(smem + (t & 3) * 32768 + ptid * 16 + 8192), v);
; #pragma unroll
;       for (int j = 0; j < 8; ++j) ss1 += v[j] * v[j];
	s_waitcnt lgkmcnt(0)
	v_lshlrev_b32_e32 v171, 16, v116
	v_lshlrev_b32_e32 v170, 16, v160
	v_and_b32_e32 v173, 0xffff0000, v116
	v_and_b32_e32 v172, 0xffff0000, v160
	v_pk_fma_f32 v[64:65], v[170:171], v[170:171], v[64:65]
	v_lshlrev_b32_e32 v175, 16, v117
	v_lshlrev_b32_e32 v174, 16, v161
	v_pk_fma_f32 v[64:65], v[172:173], v[172:173], v[64:65]
	v_and_b32_e32 v117, 0xffff0000, v117
	v_and_b32_e32 v116, 0xffff0000, v161
	v_pk_fma_f32 v[64:65], v[174:175], v[174:175], v[64:65]
	v_lshlrev_b32_e32 v203, 16, v118
	v_lshlrev_b32_e32 v202, 16, v162
	v_and_b32_e32 v211, 0xffff0000, v118
	v_and_b32_e32 v210, 0xffff0000, v162
	v_lshlrev_b32_e32 v213, 16, v119
	v_lshlrev_b32_e32 v212, 16, v163
	v_and_b32_e32 v215, 0xffff0000, v119
	v_and_b32_e32 v214, 0xffff0000, v163
	v_pk_fma_f32 v[64:65], v[116:117], v[116:117], v[64:65]
	ds_read_b128 v[116:119], v12 offset:16384
	ds_read_b128 v[160:163], v12 offset:17408
	ds_read_b128 v[170:173], v12 offset:18432
	ds_read_b128 v[174:177], v12 offset:19456
	ds_read_b128 v[178:181], v12 offset:20480
	ds_read_b128 v[182:185], v12 offset:21504
	ds_read_b128 v[186:189], v12 offset:22528
	ds_read_b128 v[190:193], v12 offset:23552
	ds_read_b128 v[194:197], v66
	ds_read_b128 v[198:201], v66 offset:1024
	v_pk_fma_f32 v[64:65], v[202:203], v[202:203], v[64:65]
	s_nop 0
	v_pk_fma_f32 v[64:65], v[210:211], v[210:211], v[64:65]
	s_nop 0
	v_pk_fma_f32 v[64:65], v[212:213], v[212:213], v[64:65]
	s_nop 0
	v_pk_fma_f32 v[64:65], v[214:215], v[214:215], v[64:65]
	s_mov_b32 m0, s80
	v_lshl_add_u64 v[202:203], v[4:5], 0, s[50:51]
	global_load_lds_dwordx4 v[202:203], off
	v_lshl_add_u64 v[202:203], v[6:7], 0, s[50:51]
	s_mov_b32 m0, s82
	s_mov_b64 s[30:31], 0x18280
	global_load_lds_dwordx4 v[202:203], off
	v_lshl_add_u64 v[202:203], v[2:3], 0, s[50:51]
	s_mov_b32 m0, s83
	s_nop 0
	global_load_lds_dwordx4 v[202:203], off
	v_lshl_add_u64 v[202:203], v[2:3], 0, s[30:31]
	s_mov_b32 m0, s84
	s_nop 0
	global_load_lds_dwordx4 v[202:203], off
	s_waitcnt lgkmcnt(0)
	v_mfma_f32_16x16x32_bf16 v[56:59], v[116:119], v[194:197], v[56:59]
	v_mfma_f32_16x16x32_bf16 v[60:63], v[160:163], v[194:197], v[60:63]
	v_mfma_f32_16x16x32_bf16 v[68:71], v[174:177], v[194:197], v[68:71]
	v_mfma_f32_16x16x32_bf16 v[72:75], v[178:181], v[194:197], v[72:75]
	v_mfma_f32_16x16x32_bf16 v[76:79], v[182:185], v[194:197], v[76:79]
	v_mfma_f32_16x16x32_bf16 v[80:83], v[186:189], v[194:197], v[80:83]
	v_mfma_f32_16x16x32_bf16 v[48:51], v[190:193], v[194:197], v[48:51]
	v_mfma_f32_16x16x32_bf16 v[84:87], v[116:119], v[198:201], v[84:87]
	v_mfma_f32_16x16x32_bf16 v[88:91], v[160:163], v[198:201], v[88:91]
	v_mfma_f32_16x16x32_bf16 v[92:95], v[170:173], v[198:201], v[92:95]
	v_mfma_f32_16x16x32_bf16 v[96:99], v[174:177], v[198:201], v[96:99]
	v_mfma_f32_16x16x32_bf16 v[100:103], v[178:181], v[198:201], v[100:103]
	v_mfma_f32_16x16x32_bf16 v[104:107], v[182:185], v[198:201], v[104:107]
	v_mfma_f32_16x16x32_bf16 v[108:111], v[186:189], v[198:201], v[108:111]
	v_mfma_f32_16x16x32_bf16 v[52:55], v[190:193], v[198:201], v[52:55]
	v_mfma_f32_16x16x32_bf16 v[206:209], v[170:173], v[194:197], v[206:209]
	ds_read_b128 v[194:197], v66 offset:2048
	ds_read_b128 v[198:201], v66 offset:3072
	s_waitcnt lgkmcnt(0)
	v_mfma_f32_16x16x32_bf16 v[120:123], v[116:119], v[194:197], v[120:123]
	v_mfma_f32_16x16x32_bf16 v[124:127], v[160:163], v[194:197], v[124:127]
	v_mfma_f32_16x16x32_bf16 v[128:131], v[170:173], v[194:197], v[128:131]
	v_mfma_f32_16x16x32_bf16 v[112:115], v[190:193], v[194:197], v[112:115]
	v_mfma_f32_16x16x32_bf16 v[16:19], v[116:119], v[198:201], v[16:19]
	v_mfma_f32_16x16x32_bf16 v[20:23], v[160:163], v[198:201], v[20:23]
	v_mfma_f32_16x16x32_bf16 v[24:27], v[170:173], v[198:201], v[24:27]
	v_mfma_f32_16x16x32_bf16 v[28:31], v[174:177], v[198:201], v[28:31]
	v_mfma_f32_16x16x32_bf16 v[32:35], v[178:181], v[198:201], v[32:35]
	v_mfma_f32_16x16x32_bf16 v[36:39], v[182:185], v[198:201], v[36:39]
	v_mfma_f32_16x16x32_bf16 v[40:43], v[186:189], v[198:201], v[40:43]
	v_mfma_f32_16x16x32_bf16 v[44:47], v[190:193], v[198:201], v[44:47]
	v_mfma_f32_16x16x32_bf16 v[138:141], v[174:177], v[194:197], v[138:141]
	v_mfma_f32_16x16x32_bf16 v[148:151], v[178:181], v[194:197], v[148:151]
	v_mfma_f32_16x16x32_bf16 v[152:155], v[182:185], v[194:197], v[152:155]
	v_mfma_f32_16x16x32_bf16 v[156:159], v[186:189], v[194:197], v[156:159]
	ds_read_b128 v[116:119], v136 offset:8192
	ds_read_b128 v[160:163], v136
	s_waitcnt vmcnt(8)
	s_barrier
; DI void unpack8(uint4 u, float* v) { v[0] = bflo(u.x); v[1] = bfhi(u.x); v[2] = bflo(u.y); v[3] = bfhi(u.y); v[4] = bflo(u.z); v[5] = bfhi(u.z); v[6] = bflo(u.w); v[7] = bfhi(u.w); }
; #define MFMA16(a, b, c) __builtin_amdgcn_mfma_f32_16x16x32_bf16((a), (b), (c), 0, 0, 0)
; template <bool ROWSS, class AL, class EPI>
; DI void gemm8(unsigned char* smem, const AL& al, const bf16_t* __restrict__ Bt, int K, int m0, int n0, const EPI& epi) {
;     ...
;   for (int t = 0; t < nt; ++t) {
;     if (t + 2 < nt) asm volatile("s_waitcnt vmcnt(8)" ::: "memory");
;     else if (t + 1 < nt) asm volatile("s_waitcnt vmcnt(4)" ::: "memory");
;     else asm volatile("s_waitcnt vmcnt(0)" ::: "memory");
;     __builtin_amdgcn_s_barrier();
;     asm volatile("" ::: "memory");
;     const unsigned char* sa = smem + (t & 3) * 32768 + aoff;
;     const unsigned char* sb = smem + (t & 3) * 32768 + boff;
;     bf16x8 af0, af1, bfr[8];
;     af0 = *(const bf16x8*)(sa);
; #pragma unroll
;     for (int n = 0; n < 8; ++n) bfr[n] = *(const bf16x8*)(sb + n * 1024);
;     af1 = *(const bf16x8*)(sa + 1024);
;     __builtin_amdgcn_sched_barrier(0);
;     if (t + 3 < nt) G8_ISSUE(t + 3);
;     __builtin_amdgcn_sched_barrier(0);
; #pragma unroll
;     for (int n = 0; n < 8; ++n) acc[0][n] = MFMA16(bfr[n], af0, acc[0][n]);
; #pragma unroll
;     for (int n = 0; n < 8; ++n) acc[1][n] = MFMA16(bfr[n], af1, acc[1][n]);
;     __builtin_amdgcn_sched_barrier(0);
;     af0 = *(const bf16x8*)(sa + 2048); af1 = *(const bf16x8*)(sa + 3072);
;     __builtin_amdgcn_sched_barrier(0);
; #pragma unroll
;     for (int n = 0; n < 8; ++n) acc[2][n] = MFMA16(bfr[n], af0, acc[2][n]);
; #pragma unroll
;     for (int n = 0; n < 8; ++n) acc[3][n] = MFMA16(bfr[n], af1, acc[3][n]);
;     __builtin_amdgcn_sched_barrier(0);
;     if (ROWSS) {
;       float v[8];
;       unpack8(*(const uint4*)(smem + (t & 3) * 32768 + ptid * 16), v);
; #pragma unroll
;       for (int j = 0; j < 8; ++j) ss0 += v[j] * v[j];
;       unpack8(*(const uint4*)(smem + (t & 3) * 32768 + ptid * 16 + 8192), v);
; #pragma unroll
;       for (int j = 0; j < 8; ++j) ss1 += v[j] * v[j];
	s_waitcnt lgkmcnt(0)
	v_lshlrev_b32_e32 v171, 16, v116
	v_lshlrev_b32_e32 v170, 16, v160
	v_and_b32_e32 v173, 0xffff0000, v116
	v_and_b32_e32 v172, 0xffff0000, v160
	v_pk_fma_f32 v[64:65], v[170:171], v[170:171], v[64:65]
	v_lshlrev_b32_e32 v175, 16, v117
	v_lshlrev_b32_e32 v174, 16, v161
	v_pk_fma_f32 v[64:65], v[172:173], v[172:173], v[64:65]
	v_and_b32_e32 v117, 0xffff0000, v117
	v_and_b32_e32 v116, 0xffff0000, v161
	v_pk_fma_f32 v[64:65], v[174:175], v[174:175], v[64:65]
	v_lshlrev_b32_e32 v203, 16, v118
	v_lshlrev_b32_e32 v202, 16, v162
	v_and_b32_e32 v211, 0xffff0000, v118
	v_and_b32_e32 v210, 0xffff0000, v162
	v_lshlrev_b32_e32 v213, 16, v119
	v_lshlrev_b32_e32 v212, 16, v163
	v_and_b32_e32 v215, 0xffff0000, v119
	v_and_b32_e32 v214, 0xffff0000, v163
	v_pk_fma_f32 v[64:65], v[116:117], v[116:117], v[64:65]
	ds_read_b128 v[116:119], v10 offset:16384
	ds_read_b128 v[160:163], v10 offset:17408
	ds_read_b128 v[170:173], v10 offset:18432
	ds_read_b128 v[174:177], v10 offset:19456
	ds_read_b128 v[178:181], v10 offset:20480
	ds_read_b128 v[182:185], v10 offset:21504
	ds_read_b128 v[186:189], v10 offset:22528
	ds_read_b128 v[190:193], v10 offset:23552
	ds_read_b128 v[194:197], v8
	ds_read_b128 v[198:201], v8 offset:1024
	v_pk_fma_f32 v[64:65], v[202:203], v[202:203], v[64:65]
	s_nop 0
	v_pk_fma_f32 v[64:65], v[210:211], v[210:211], v[64:65]
	s_nop 0
	v_pk_fma_f32 v[64:65], v[212:213], v[212:213], v[64:65]
	s_nop 0
	v_pk_fma_f32 v[64:65], v[214:215], v[214:215], v[64:65]
	s_mov_b32 m0, s2
	v_lshl_add_u64 v[4:5], v[4:5], 0, s[52:53]
	global_load_lds_dwordx4 v[4:5], off
	v_lshl_add_u64 v[4:5], v[6:7], 0, s[52:53]
	s_mov_b32 m0, s3
	s_mov_b64 s[2:3], 0x182c0
	global_load_lds_dwordx4 v[4:5], off
	v_lshl_add_u64 v[4:5], v[2:3], 0, s[52:53]
	s_mov_b32 m0, s58
	v_lshl_add_u64 v[2:3], v[2:3], 0, s[2:3]
	global_load_lds_dwordx4 v[4:5], off
	s_mov_b32 m0, s59
	s_nop 0
	global_load_lds_dwordx4 v[2:3], off
	s_waitcnt lgkmcnt(0)
	v_mfma_f32_16x16x32_bf16 v[2:5], v[116:119], v[194:197], v[56:59]
	v_mfma_f32_16x16x32_bf16 v[56:59], v[160:163], v[194:197], v[60:63]
	v_mfma_f32_16x16x32_bf16 v[60:63], v[170:173], v[194:197], v[206:209]
	v_mfma_f32_16x16x32_bf16 v[68:71], v[174:177], v[194:197], v[68:71]
	v_mfma_f32_16x16x32_bf16 v[72:75], v[178:181], v[194:197], v[72:75]
	v_mfma_f32_16x16x32_bf16 v[76:79], v[182:185], v[194:197], v[76:79]
	v_mfma_f32_16x16x32_bf16 v[80:83], v[186:189], v[194:197], v[80:83]
	v_mfma_f32_16x16x32_bf16 v[48:51], v[190:193], v[194:197], v[48:51]
	ds_read_b128 v[194:197], v8 offset:2048
	v_mfma_f32_16x16x32_bf16 v[84:87], v[116:119], v[198:201], v[84:87]
	v_mfma_f32_16x16x32_bf16 v[88:91], v[160:163], v[198:201], v[88:91]
	v_mfma_f32_16x16x32_bf16 v[92:95], v[170:173], v[198:201], v[92:95]
	v_mfma_f32_16x16x32_bf16 v[96:99], v[174:177], v[198:201], v[96:99]
	v_mfma_f32_16x16x32_bf16 v[100:103], v[178:181], v[198:201], v[100:103]
	v_mfma_f32_16x16x32_bf16 v[104:107], v[182:185], v[198:201], v[104:107]
	v_mfma_f32_16x16x32_bf16 v[108:111], v[186:189], v[198:201], v[108:111]
	v_mfma_f32_16x16x32_bf16 v[52:55], v[190:193], v[198:201], v[52:55]
	ds_read_b128 v[198:201], v8 offset:3072
	s_waitcnt lgkmcnt(1)
	v_mfma_f32_16x16x32_bf16 v[120:123], v[116:119], v[194:197], v[120:123]
	v_mfma_f32_16x16x32_bf16 v[124:127], v[160:163], v[194:197], v[124:127]
	v_mfma_f32_16x16x32_bf16 v[112:115], v[190:193], v[194:197], v[112:115]
	s_waitcnt lgkmcnt(0)
	v_mfma_f32_16x16x32_bf16 v[16:19], v[116:119], v[198:201], v[16:19]
	v_mfma_f32_16x16x32_bf16 v[20:23], v[160:163], v[198:201], v[20:23]
	v_mfma_f32_16x16x32_bf16 v[24:27], v[170:173], v[198:201], v[24:27]
	v_mfma_f32_16x16x32_bf16 v[28:31], v[174:177], v[198:201], v[28:31]
	v_mfma_f32_16x16x32_bf16 v[32:35], v[178:181], v[198:201], v[32:35]
	v_mfma_f32_16x16x32_bf16 v[36:39], v[182:185], v[198:201], v[36:39]
	v_mfma_f32_16x16x32_bf16 v[40:43], v[186:189], v[198:201], v[40:43]
	v_mfma_f32_16x16x32_bf16 v[44:47], v[190:193], v[198:201], v[44:47]
	v_mfma_f32_16x16x32_bf16 v[206:209], v[170:173], v[194:197], v[128:131]
	v_mfma_f32_16x16x32_bf16 v[138:141], v[174:177], v[194:197], v[138:141]
	v_mfma_f32_16x16x32_bf16 v[148:151], v[178:181], v[194:197], v[148:151]
	v_mfma_f32_16x16x32_bf16 v[152:155], v[182:185], v[194:197], v[152:155]
	v_mfma_f32_16x16x32_bf16 v[156:159], v[186:189], v[194:197], v[156:159]
	ds_read_b128 v[116:119], v9 offset:8192
	ds_read_b128 v[128:131], v9
	s_waitcnt vmcnt(8)
	s_barrier
; DI void unpack8(uint4 u, float* v) { v[0] = bflo(u.x); v[1] = bfhi(u.x); v[2] = bflo(u.y); v[3] = bfhi(u.y); v[4] = bflo(u.z); v[5] = bfhi(u.z); v[6] = bflo(u.w); v[7] = bfhi(u.w); }
; #define MFMA16(a, b, c) __builtin_amdgcn_mfma_f32_16x16x32_bf16((a), (b), (c), 0, 0, 0)
; template <bool ROWSS, class AL, class EPI>
; DI void gemm8(unsigned char* smem, const AL& al, const bf16_t* __restrict__ Bt, int K, int m0, int n0, const EPI& epi) {
;     ...
;   for (int t = 0; t < nt; ++t) {
;     if (t + 2 < nt) asm volatile("s_waitcnt vmcnt(8)" ::: "memory");
;     else if (t + 1 < nt) asm volatile("s_waitcnt vmcnt(4)" ::: "memory");
;     else asm volatile("s_waitcnt vmcnt(0)" ::: "memory");
;     __builtin_amdgcn_s_barrier();
;     asm volatile("" ::: "memory");
;     const unsigned char* sa = smem + (t & 3) * 32768 + aoff;
;     const unsigned char* sb = smem + (t & 3) * 32768 + boff;
;     bf16x8 af0, af1, bfr[8];
;     af0 = *(const bf16x8*)(sa);
; #pragma unroll
;     for (int n = 0; n < 8; ++n) bfr[n] = *(const bf16x8*)(sb + n * 1024);
;     af1 = *(const bf16x8*)(sa + 1024);
;     __builtin_amdgcn_sched_barrier(0);
;     if (t + 3 < nt) G8_ISSUE(t + 3);
;     __builtin_amdgcn_sched_barrier(0);
; #pragma unroll
;     for (int n = 0; n < 8; ++n) acc[0][n] = MFMA16(bfr[n], af0, acc[0][n]);
; #pragma unroll
;     for (int n = 0; n < 8; ++n) acc[1][n] = MFMA16(bfr[n], af1, acc[1][n]);
;     __builtin_amdgcn_sched_barrier(0);
;     af0 = *(const bf16x8*)(sa + 2048); af1 = *(const bf16x8*)(sa + 3072);
;     __builtin_amdgcn_sched_barrier(0);
; #pragma unroll
;     for (int n = 0; n < 8; ++n) acc[2][n] = MFMA16(bfr[n], af0, acc[2][n]);
; #pragma unroll
;     for (int n = 0; n < 8; ++n) acc[3][n] = MFMA16(bfr[n], af1, acc[3][n]);
;     __builtin_amdgcn_sched_barrier(0);
;     if (ROWSS) {
;       float v[8];
;       unpack8(*(const uint4*)(smem + (t & 3) * 32768 + ptid * 16), v);
; #pragma unroll
;       for (int j = 0; j < 8; ++j) ss0 += v[j] * v[j];
;       unpack8(*(const uint4*)(smem + (t & 3) * 32768 + ptid * 16 + 8192), v);
; #pragma unroll
;       for (int j = 0; j < 8; ++j) ss1 += v[j] * v[j];
	s_waitcnt lgkmcnt(0)
	v_lshlrev_b32_e32 v7, 16, v116
	v_lshlrev_b32_e32 v6, 16, v128
	v_and_b32_e32 v161, 0xffff0000, v116
	v_and_b32_e32 v160, 0xffff0000, v128
	v_pk_fma_f32 v[6:7], v[6:7], v[6:7], v[64:65]
	v_lshlrev_b32_e32 v163, 16, v117
	v_lshlrev_b32_e32 v162, 16, v129
	v_pk_fma_f32 v[6:7], v[160:161], v[160:161], v[6:7]
	v_and_b32_e32 v117, 0xffff0000, v117
	v_and_b32_e32 v116, 0xffff0000, v129
	v_pk_fma_f32 v[6:7], v[162:163], v[162:163], v[6:7]
	v_lshlrev_b32_e32 v129, 16, v118
	v_and_b32_e32 v203, 0xffff0000, v118
	v_lshlrev_b32_e32 v211, 16, v119
	v_and_b32_e32 v213, 0xffff0000, v119
	v_pk_fma_f32 v[6:7], v[116:117], v[116:117], v[6:7]
	ds_read_b128 v[116:119], v10 offset:49152
	ds_read_b128 v[160:163], v10 offset:50176
	ds_read_b128 v[170:173], v10 offset:51200
	ds_read_b128 v[174:177], v10 offset:52224
	ds_read_b128 v[178:181], v10 offset:53248
	ds_read_b128 v[182:185], v10 offset:54272
	ds_read_b128 v[186:189], v10 offset:55296
	ds_read_b128 v[190:193], v10 offset:56320
	ds_read_b128 v[194:197], v8 offset:32768
	ds_read_b128 v[198:201], v8 offset:33792
	v_lshlrev_b32_e32 v128, 16, v130
	v_and_b32_e32 v202, 0xffff0000, v130
	v_pk_fma_f32 v[6:7], v[128:129], v[128:129], v[6:7]
	v_lshlrev_b32_e32 v210, 16, v131
	v_pk_fma_f32 v[6:7], v[202:203], v[202:203], v[6:7]
	v_and_b32_e32 v212, 0xffff0000, v131
	v_pk_fma_f32 v[6:7], v[210:211], v[210:211], v[6:7]
	s_nop 0
	v_pk_fma_f32 v[130:131], v[212:213], v[212:213], v[6:7]
	s_waitcnt lgkmcnt(0)
	v_mfma_f32_16x16x32_bf16 v[2:5], v[116:119], v[194:197], v[2:5]
	v_mfma_f32_16x16x32_bf16 v[56:59], v[160:163], v[194:197], v[56:59]
	v_mfma_f32_16x16x32_bf16 v[60:63], v[170:173], v[194:197], v[60:63]
	v_mfma_f32_16x16x32_bf16 v[68:71], v[174:177], v[194:197], v[68:71]
	v_mfma_f32_16x16x32_bf16 v[72:75], v[178:181], v[194:197], v[72:75]
	v_mfma_f32_16x16x32_bf16 v[76:79], v[182:185], v[194:197], v[76:79]
	v_mfma_f32_16x16x32_bf16 v[80:83], v[186:189], v[194:197], v[80:83]
	v_mfma_f32_16x16x32_bf16 v[48:51], v[190:193], v[194:197], v[48:51]
	ds_read_b128 v[194:197], v8 offset:34816
	v_mfma_f32_16x16x32_bf16 v[84:87], v[116:119], v[198:201], v[84:87]
	v_mfma_f32_16x16x32_bf16 v[88:91], v[160:163], v[198:201], v[88:91]
	v_mfma_f32_16x16x32_bf16 v[92:95], v[170:173], v[198:201], v[92:95]
	v_mfma_f32_16x16x32_bf16 v[96:99], v[174:177], v[198:201], v[96:99]
	v_mfma_f32_16x16x32_bf16 v[100:103], v[178:181], v[198:201], v[100:103]
	v_mfma_f32_16x16x32_bf16 v[104:107], v[182:185], v[198:201], v[104:107]
	v_mfma_f32_16x16x32_bf16 v[108:111], v[186:189], v[198:201], v[108:111]
	v_mfma_f32_16x16x32_bf16 v[52:55], v[190:193], v[198:201], v[52:55]
	ds_read_b128 v[198:201], v8 offset:35840
	s_waitcnt lgkmcnt(1)
	v_mfma_f32_16x16x32_bf16 v[120:123], v[116:119], v[194:197], v[120:123]
	v_mfma_f32_16x16x32_bf16 v[124:127], v[160:163], v[194:197], v[124:127]
	v_mfma_f32_16x16x32_bf16 v[112:115], v[190:193], v[194:197], v[112:115]
	s_waitcnt lgkmcnt(0)
	v_mfma_f32_16x16x32_bf16 v[16:19], v[116:119], v[198:201], v[16:19]
	v_mfma_f32_16x16x32_bf16 v[20:23], v[160:163], v[198:201], v[20:23]
	v_mfma_f32_16x16x32_bf16 v[24:27], v[170:173], v[198:201], v[24:27]
	v_mfma_f32_16x16x32_bf16 v[28:31], v[174:177], v[198:201], v[28:31]
	v_mfma_f32_16x16x32_bf16 v[32:35], v[178:181], v[198:201], v[32:35]
	v_mfma_f32_16x16x32_bf16 v[36:39], v[182:185], v[198:201], v[36:39]
	v_mfma_f32_16x16x32_bf16 v[40:43], v[186:189], v[198:201], v[40:43]
	v_mfma_f32_16x16x32_bf16 v[44:47], v[190:193], v[198:201], v[44:47]
	v_mfma_f32_16x16x32_bf16 v[206:209], v[170:173], v[194:197], v[206:209]
	v_mfma_f32_16x16x32_bf16 v[138:141], v[174:177], v[194:197], v[138:141]
	v_mfma_f32_16x16x32_bf16 v[148:151], v[178:181], v[194:197], v[148:151]
	v_mfma_f32_16x16x32_bf16 v[152:155], v[182:185], v[194:197], v[152:155]
	v_mfma_f32_16x16x32_bf16 v[156:159], v[186:189], v[194:197], v[156:159]
	ds_read_b128 v[116:119], v9 offset:32768
	ds_read_b128 v[6:9], v9 offset:40960
	s_waitcnt vmcnt(4)
	s_barrier
	s_waitcnt lgkmcnt(0)
	v_lshlrev_b32_e32 v10, 16, v116
	v_and_b32_e32 v15, 0xffff0000, v116
	v_lshlrev_b32_e32 v116, 16, v6
	v_and_b32_e32 v6, 0xffff0000, v6
	v_fma_f32 v144, v116, v116, v131
	v_lshlrev_b32_e32 v64, 16, v117
	v_and_b32_e32 v65, 0xffff0000, v117
	v_lshlrev_b32_e32 v117, 16, v7
	v_fmac_f32_e32 v144, v6, v6
	v_and_b32_e32 v7, 0xffff0000, v7
	v_fmac_f32_e32 v144, v117, v117
	v_lshlrev_b32_e32 v67, 16, v118
	v_and_b32_e32 v128, 0xffff0000, v118
	v_lshlrev_b32_e32 v118, 16, v8
	v_fmac_f32_e32 v144, v7, v7
	v_and_b32_e32 v8, 0xffff0000, v8
	v_fmac_f32_e32 v144, v118, v118
	v_lshlrev_b32_e32 v129, 16, v119
	v_and_b32_e32 v137, 0xffff0000, v119
	v_lshlrev_b32_e32 v119, 16, v9
	v_fmac_f32_e32 v144, v8, v8
	v_and_b32_e32 v9, 0xffff0000, v9
	v_fmac_f32_e32 v144, v119, v119
	v_fmac_f32_e32 v144, v9, v9
	ds_read_b128 v[6:9], v14 offset:16384
	ds_read_b128 v[116:119], v14 offset:17408
	ds_read_b128 v[160:163], v14 offset:18432
	ds_read_b128 v[170:173], v14 offset:19456
	ds_read_b128 v[174:177], v14 offset:20480
	ds_read_b128 v[178:181], v14 offset:21504
	ds_read_b128 v[182:185], v14 offset:22528
	ds_read_b128 v[186:189], v14 offset:23552
	ds_read_b128 v[190:193], v11
	ds_read_b128 v[194:197], v11 offset:1024
	v_fmac_f32_e32 v130, v10, v10
	v_fmac_f32_e32 v130, v15, v15
	v_fmac_f32_e32 v130, v64, v64
	v_fmac_f32_e32 v130, v65, v65
	v_fmac_f32_e32 v130, v67, v67
	v_fmac_f32_e32 v130, v128, v128
	v_fmac_f32_e32 v130, v129, v129
	v_fmac_f32_e32 v130, v137, v137
	s_waitcnt lgkmcnt(0)
; DI void unpack8(uint4 u, float* v) { v[0] = bflo(u.x); v[1] = bfhi(u.x); v[2] = bflo(u.y); v[3] = bfhi(u.y); v[4] = bflo(u.z); v[5] = bfhi(u.z); v[6] = bflo(u.w); v[7] = bfhi(u.w); }
; #define MFMA16(a, b, c) __builtin_amdgcn_mfma_f32_16x16x32_bf16((a), (b), (c), 0, 0, 0)
; template <bool ROWSS, class AL, class EPI>
; DI void gemm8(unsigned char* smem, const AL& al, const bf16_t* __restrict__ Bt, int K, int m0, int n0, const EPI& epi) {
;     ...
; #pragma unroll
;     for (int n = 0; n < 8; ++n) acc[2][n] = MFMA16(bfr[n], af0, acc[2][n]);
; #pragma unroll
;     for (int n = 0; n < 8; ++n) acc[3][n] = MFMA16(bfr[n], af1, acc[3][n]);
;     __builtin_amdgcn_sched_barrier(0);
;     if (ROWSS) {
;       float v[8];
;       unpack8(*(const uint4*)(smem + (t & 3) * 32768 + ptid * 16), v);
; #pragma unroll
;       for (int j = 0; j < 8; ++j) ss0 += v[j] * v[j];
;       unpack8(*(const uint4*)(smem + (t & 3) * 32768 + ptid * 16 + 8192), v);
; #pragma unroll
;       for (int j = 0; j < 8; ++j) ss1 += v[j] * v[j];
	v_mfma_f32_16x16x32_bf16 v[2:5], v[6:9], v[190:193], v[2:5]
	v_mfma_f32_16x16x32_bf16 v[56:59], v[116:119], v[190:193], v[56:59]
	v_mfma_f32_16x16x32_bf16 v[60:63], v[160:163], v[190:193], v[60:63]
	v_mfma_f32_16x16x32_bf16 v[68:71], v[170:173], v[190:193], v[68:71]
	v_mfma_f32_16x16x32_bf16 v[72:75], v[174:177], v[190:193], v[72:75]
	v_mfma_f32_16x16x32_bf16 v[76:79], v[178:181], v[190:193], v[76:79]
	v_mfma_f32_16x16x32_bf16 v[80:83], v[182:185], v[190:193], v[80:83]
	v_mfma_f32_16x16x32_bf16 v[48:51], v[186:189], v[190:193], v[48:51]
	v_mfma_f32_16x16x32_bf16 v[84:87], v[6:9], v[194:197], v[84:87]
	v_mfma_f32_16x16x32_bf16 v[88:91], v[116:119], v[194:197], v[88:91]
	v_mfma_f32_16x16x32_bf16 v[92:95], v[160:163], v[194:197], v[92:95]
	v_mfma_f32_16x16x32_bf16 v[96:99], v[170:173], v[194:197], v[96:99]
	v_mfma_f32_16x16x32_bf16 v[100:103], v[174:177], v[194:197], v[100:103]
	v_mfma_f32_16x16x32_bf16 v[104:107], v[178:181], v[194:197], v[104:107]
	v_mfma_f32_16x16x32_bf16 v[108:111], v[182:185], v[194:197], v[108:111]
	v_mfma_f32_16x16x32_bf16 v[190:193], v[186:189], v[194:197], v[52:55]
	s_nop 2
	ds_read_b128 v[52:55], v11 offset:2048
	ds_read_b128 v[194:197], v11 offset:3072
	s_waitcnt lgkmcnt(0)
	v_mfma_f32_16x16x32_bf16 v[120:123], v[6:9], v[52:55], v[120:123]
	v_mfma_f32_16x16x32_bf16 v[124:127], v[116:119], v[52:55], v[124:127]
	v_mfma_f32_16x16x32_bf16 v[112:115], v[186:189], v[52:55], v[112:115]
	v_mfma_f32_16x16x32_bf16 v[116:119], v[116:119], v[194:197], v[20:23]
	v_mfma_f32_16x16x32_bf16 v[198:201], v[160:163], v[52:55], v[206:209]
	v_mfma_f32_16x16x32_bf16 v[138:141], v[170:173], v[52:55], v[138:141]
	v_mfma_f32_16x16x32_bf16 v[148:151], v[174:177], v[52:55], v[148:151]
	v_mfma_f32_16x16x32_bf16 v[152:155], v[178:181], v[52:55], v[152:155]
	v_mfma_f32_16x16x32_bf16 v[156:159], v[182:185], v[52:55], v[156:159]
	v_mfma_f32_16x16x32_bf16 v[206:209], v[6:9], v[194:197], v[16:19]
	v_mfma_f32_16x16x32_bf16 v[160:163], v[160:163], v[194:197], v[24:27]
	v_mfma_f32_16x16x32_bf16 v[170:173], v[170:173], v[194:197], v[28:31]
	v_mfma_f32_16x16x32_bf16 v[174:177], v[174:177], v[194:197], v[32:35]
	v_mfma_f32_16x16x32_bf16 v[178:181], v[178:181], v[194:197], v[36:39]
	v_mfma_f32_16x16x32_bf16 v[182:185], v[182:185], v[194:197], v[40:43]
	v_mfma_f32_16x16x32_bf16 v[186:189], v[186:189], v[194:197], v[44:47]
	ds_read_b128 v[6:9], v13
	ds_read_b128 v[14:17], v13 offset:8192
	s_waitcnt vmcnt(0)
	s_barrier
; DI void unpack8(uint4 u, float* v) { v[0] = bflo(u.x); v[1] = bfhi(u.x); v[2] = bflo(u.y); v[3] = bfhi(u.y); v[4] = bflo(u.z); v[5] = bfhi(u.z); v[6] = bflo(u.w); v[7] = bfhi(u.w); }
; #define MFMA16(a, b, c) __builtin_amdgcn_mfma_f32_16x16x32_bf16((a), (b), (c), 0, 0, 0)
; template <bool ROWSS, class AL, class EPI>
; DI void gemm8(unsigned char* smem, const AL& al, const bf16_t* __restrict__ Bt, int K, int m0, int n0, const EPI& epi) {
;     ...
; #pragma unroll
;     for (int n = 0; n < 8; ++n) acc[2][n] = MFMA16(bfr[n], af0, acc[2][n]);
; #pragma unroll
;     for (int n = 0; n < 8; ++n) acc[3][n] = MFMA16(bfr[n], af1, acc[3][n]);
;     __builtin_amdgcn_sched_barrier(0);
;     if (ROWSS) {
;       float v[8];
;       unpack8(*(const uint4*)(smem + (t & 3) * 32768 + ptid * 16), v);
; #pragma unroll
;       for (int j = 0; j < 8; ++j) ss0 += v[j] * v[j];
;       unpack8(*(const uint4*)(smem + (t & 3) * 32768 + ptid * 16 + 8192), v);
; #pragma unroll
;       for (int j = 0; j < 8; ++j) ss1 += v[j] * v[j];
;     ...
;   __syncthreads();
;   float* rowss = (float*)(smem + G8_ROWSS_OFF);
;   if (ROWSS) {
;     ss0 += __shfl_xor(ss0, 1); ss0 += __shfl_xor(ss0, 2);
;     ss1 += __shfl_xor(ss1, 1); ss1 += __shfl_xor(ss1, 2);
;     if ((lane & 3) == 0) { rowss[Rb] = ss0; rowss[Rb + 128] = ss1; }
	ds_read_b128 v[194:197], v12 offset:16384
	ds_read_b128 v[210:213], v12 offset:17408
	ds_read_b128 v[214:217], v12 offset:18432
	ds_read_b128 v[218:221], v12 offset:19456
	ds_read_b128 v[222:225], v12 offset:20480
	ds_read_b128 v[226:229], v12 offset:21504
	ds_read_b128 v[230:233], v12 offset:22528
	ds_read_b128 v[234:237], v12 offset:23552
	ds_read_b128 v[30:33], v66
	ds_read_b128 v[238:241], v66 offset:1024
	s_waitcnt lgkmcnt(0)
	v_lshlrev_b32_e32 v10, 16, v6
	v_and_b32_e32 v6, 0xffff0000, v6
	v_lshlrev_b32_e32 v19, 16, v14
	v_fmac_f32_e32 v130, v10, v10
	v_lshlrev_b32_e32 v11, 16, v7
	v_and_b32_e32 v14, 0xffff0000, v14
	v_fmac_f32_e32 v144, v19, v19
	v_fmac_f32_e32 v130, v6, v6
	v_and_b32_e32 v7, 0xffff0000, v7
	v_lshlrev_b32_e32 v20, 16, v15
	v_fmac_f32_e32 v144, v14, v14
	v_fmac_f32_e32 v130, v11, v11
	v_lshlrev_b32_e32 v13, 16, v8
	v_and_b32_e32 v15, 0xffff0000, v15
	v_fmac_f32_e32 v144, v20, v20
	v_fmac_f32_e32 v130, v7, v7
	v_and_b32_e32 v8, 0xffff0000, v8
	v_lshlrev_b32_e32 v21, 16, v16
	v_fmac_f32_e32 v144, v15, v15
	v_fmac_f32_e32 v130, v13, v13
	v_lshlrev_b32_e32 v18, 16, v9
	v_and_b32_e32 v16, 0xffff0000, v16
	v_fmac_f32_e32 v144, v21, v21
	v_fmac_f32_e32 v130, v8, v8
	v_and_b32_e32 v9, 0xffff0000, v9
	v_lshlrev_b32_e32 v22, 16, v17
	v_fmac_f32_e32 v144, v16, v16
	v_fmac_f32_e32 v130, v18, v18
	v_and_b32_e32 v17, 0xffff0000, v17
	v_fmac_f32_e32 v144, v22, v22
	v_fmac_f32_e32 v130, v9, v9
	v_fmac_f32_e32 v144, v17, v17
	v_mfma_f32_16x16x32_bf16 v[2:5], v[194:197], v[30:33], v[2:5]
	v_mfma_f32_16x16x32_bf16 v[6:9], v[210:213], v[30:33], v[56:59]
	v_mfma_f32_16x16x32_bf16 v[10:13], v[214:217], v[30:33], v[60:63]
	v_mfma_f32_16x16x32_bf16 v[14:17], v[218:221], v[30:33], v[68:71]
	v_mfma_f32_16x16x32_bf16 v[18:21], v[222:225], v[30:33], v[72:75]
	v_mfma_f32_16x16x32_bf16 v[22:25], v[226:229], v[30:33], v[76:79]
	v_mfma_f32_16x16x32_bf16 v[26:29], v[230:233], v[30:33], v[80:83]
	v_mfma_f32_16x16x32_bf16 v[30:33], v[234:237], v[30:33], v[48:51]
	v_mfma_f32_16x16x32_bf16 v[34:37], v[194:197], v[238:241], v[84:87]
	v_mfma_f32_16x16x32_bf16 v[38:41], v[210:213], v[238:241], v[88:91]
	v_mfma_f32_16x16x32_bf16 v[42:45], v[214:217], v[238:241], v[92:95]
	v_mfma_f32_16x16x32_bf16 v[46:49], v[218:221], v[238:241], v[96:99]
	v_mfma_f32_16x16x32_bf16 v[50:53], v[222:225], v[238:241], v[100:103]
	v_mfma_f32_16x16x32_bf16 v[54:57], v[226:229], v[238:241], v[104:107]
	v_mfma_f32_16x16x32_bf16 v[58:61], v[230:233], v[238:241], v[108:111]
	v_mfma_f32_16x16x32_bf16 v[62:65], v[234:237], v[238:241], v[190:193]
	ds_read_b128 v[94:97], v66 offset:2048
	s_nop 1
	ds_read_b128 v[190:193], v66 offset:3072
	s_waitcnt lgkmcnt(0)
	v_mfma_f32_16x16x32_bf16 v[66:69], v[194:197], v[94:97], v[120:123]
	v_mfma_f32_16x16x32_bf16 v[70:73], v[210:213], v[94:97], v[124:127]
	v_mfma_f32_16x16x32_bf16 v[74:77], v[214:217], v[94:97], v[198:201]
	v_mfma_f32_16x16x32_bf16 v[78:81], v[218:221], v[94:97], v[138:141]
	v_mfma_f32_16x16x32_bf16 v[82:85], v[222:225], v[94:97], v[148:151]
	v_mfma_f32_16x16x32_bf16 v[86:89], v[226:229], v[94:97], v[152:155]
	v_mfma_f32_16x16x32_bf16 v[90:93], v[230:233], v[94:97], v[156:159]
	v_mfma_f32_16x16x32_bf16 v[94:97], v[234:237], v[94:97], v[112:115]
	v_mfma_f32_16x16x32_bf16 v[98:101], v[194:197], v[190:193], v[206:209]
	v_mfma_f32_16x16x32_bf16 v[102:105], v[210:213], v[190:193], v[116:119]
	v_mfma_f32_16x16x32_bf16 v[106:109], v[214:217], v[190:193], v[160:163]
	v_mfma_f32_16x16x32_bf16 v[110:113], v[218:221], v[190:193], v[170:173]
	v_mfma_f32_16x16x32_bf16 v[114:117], v[222:225], v[190:193], v[174:177]
	v_mfma_f32_16x16x32_bf16 v[118:121], v[226:229], v[190:193], v[178:181]
	v_mfma_f32_16x16x32_bf16 v[122:125], v[230:233], v[190:193], v[182:185]
	v_mfma_f32_16x16x32_bf16 v[126:129], v[234:237], v[190:193], v[186:189]
	ds_read_b128 v[138:141], v136
	ds_read_b128 v[148:151], v136 offset:8192
	v_cmp_lt_i32_e32 vcc, v165, v166
	s_waitcnt vmcnt(0) lgkmcnt(0)
	s_barrier
	v_lshlrev_b32_e32 v131, 16, v138
	v_and_b32_e32 v136, 0xffff0000, v138
	v_fmac_f32_e32 v130, v131, v131
	v_lshlrev_b32_e32 v137, 16, v139
	v_fmac_f32_e32 v130, v136, v136
	v_and_b32_e32 v138, 0xffff0000, v139
	v_fmac_f32_e32 v130, v137, v137
	v_lshlrev_b32_e32 v139, 16, v140
	v_fmac_f32_e32 v130, v138, v138
	v_and_b32_e32 v140, 0xffff0000, v140
	v_lshlrev_b32_e32 v153, 16, v148
	v_fmac_f32_e32 v130, v139, v139
	v_lshlrev_b32_e32 v152, 16, v141
	v_and_b32_e32 v148, 0xffff0000, v148
	v_fmac_f32_e32 v144, v153, v153
	v_fmac_f32_e32 v130, v140, v140
	v_and_b32_e32 v141, 0xffff0000, v141
	v_lshlrev_b32_e32 v154, 16, v149
	v_fmac_f32_e32 v144, v148, v148
	v_fmac_f32_e32 v130, v152, v152
	v_cndmask_b32_e32 v131, v164, v165, vcc
	v_and_b32_e32 v149, 0xffff0000, v149
	v_fmac_f32_e32 v144, v154, v154
	v_fmac_f32_e32 v130, v141, v141
	v_lshlrev_b32_e32 v131, 2, v131
	v_lshlrev_b32_e32 v155, 16, v150
	v_fmac_f32_e32 v144, v149, v149
	ds_bpermute_b32 v136, v131, v130
	v_and_b32_e32 v150, 0xffff0000, v150
	v_fmac_f32_e32 v144, v155, v155
	v_lshlrev_b32_e32 v156, 16, v151
	v_fmac_f32_e32 v144, v150, v150
	v_and_b32_e32 v151, 0xffff0000, v151
	v_fmac_f32_e32 v144, v156, v156
	v_fmac_f32_e32 v144, v151, v151
	s_waitcnt lgkmcnt(0)
	v_add_f32_e32 v130, v130, v136
	ds_bpermute_b32 v136, v131, v144
	v_cmp_lt_i32_e32 vcc, v167, v166
	v_and_b32_e32 v138, 3, v132
	s_waitcnt lgkmcnt(0)
	v_cndmask_b32_e32 v131, v164, v167, vcc
	v_lshlrev_b32_e32 v137, 2, v131
	v_add_f32_e32 v136, v144, v136
	ds_bpermute_b32 v131, v137, v130
	ds_bpermute_b32 v137, v137, v136
	v_cmp_eq_u32_e32 vcc, 0, v138
	s_and_saveexec_b64 s[2:3], vcc
	s_cbranch_execz .LBB0_344
	v_lshl_add_u32 v134, v134, 2, 0
	v_add_u32_e32 v134, 0x21000, v134
	s_waitcnt lgkmcnt(1)
	v_add_f32_e32 v130, v130, v131
	s_waitcnt lgkmcnt(0)
	v_add_f32_e32 v131, v136, v137
	ds_write2st64_b32 v134, v130, v131 offset1:2

; template <bool ROWSS, class AL, class EPI>
; DI void gemm8(unsigned char* smem, const AL& al, const bf16_t* __restrict__ Bt, int K, int m0, int n0, const EPI& epi) {
;     ...
;   const int sb_ = lane * 16, swz_ = sb_ ^ (((sb_ >> 9) & 1) << 5);
;   const int Rb = w * 16 + (swz_ >> 6), C0 = (swz_ & 63) >> 1;
;   const bf16_t* bp0 = Bt + (size_t)(n0 + Rb) * K + C0; const bf16_t* bp1 = bp0 + (size_t)128 * K;
;   float ss0 = 0.f, ss1 = 0.f;
;   const int nt = K >> 5;
;   const int frag = (fr * 64 + fq * 16) ^ (((fr >> 3) & 1) << 5);
;   const int aoff = wm * 4096 + frag, boff = 16384 + wn * 8192 + frag;
;     ...
;   if constexpr (ROWSS) {
;   G8_ISSUE(0); G8_ISSUE(1); G8_ISSUE(2);
;   for (int t = 0; t < nt; ++t) {
;     if (t + 2 < nt) asm volatile("s_waitcnt vmcnt(8)" ::: "memory");
;     else if (t + 1 < nt) asm volatile("s_waitcnt vmcnt(4)" ::: "memory");
;     else asm volatile("s_waitcnt vmcnt(0)" ::: "memory");
;     __builtin_amdgcn_s_barrier();
;     asm volatile("" ::: "memory");
;     const unsigned char* sa = smem + (t & 3) * 32768 + aoff;
;     const unsigned char* sb = smem + (t & 3) * 32768 + boff;
;     bf16x8 af0, af1, bfr[8];
;     af0 = *(const bf16x8*)(sa);
; #pragma unroll
;     for (int n = 0; n < 8; ++n) bfr[n] = *(const bf16x8*)(sb + n * 1024);
;     af1 = *(const bf16x8*)(sa + 1024);
;     __builtin_amdgcn_sched_barrier(0);
;     if (t + 3 < nt) G8_ISSUE(t + 3);
;     __builtin_amdgcn_sched_barrier(0);
; #pragma unroll
;     for (int n = 0; n < 8; ++n) acc[0][n] = MFMA16(bfr[n], af0, acc[0][n]);
; #pragma unroll
;     for (int n = 0; n < 8; ++n) acc[1][n] = MFMA16(bfr[n], af1, acc[1][n]);
;     __builtin_amdgcn_sched_barrier(0);
;     af0 = *(const bf16x8*)(sa + 2048); af1 = *(const bf16x8*)(sa + 3072);
;     __builtin_amdgcn_sched_barrier(0);
; #pragma unroll
;     for (int n = 0; n < 8; ++n) acc[2][n] = MFMA16(bfr[n], af0, acc[2][n]);
; #pragma unroll
;     for (int n = 0; n < 8; ++n) acc[3][n] = MFMA16(bfr[n], af1, acc[3][n]);
;     __builtin_amdgcn_sched_barrier(0);
;     if (ROWSS) {
;       float v[8];
;       unpack8(*(const uint4*)(smem + (t & 3) * 32768 + ptid * 16), v);
; #pragma unroll
;       for (int j = 0; j < 8; ++j) ss0 += v[j] * v[j];
;       unpack8(*(const uint4*)(smem + (t & 3) * 32768 + ptid * 16 + 8192), v);
; #pragma unroll
;       for (int j = 0; j < 8; ++j) ss1 += v[j] * v[j];
.LBB0_379:
	v_mov_b32_e32 v130, v204
	s_lshl_b32 s2, s92, 8
	v_readfirstlane_b32 s8, v130
	s_ashr_i32 s0, s8, 6
	v_bfe_u32 v3, v130, 2, 4
	v_lshl_or_b32 v134, s0, 4, v3
	v_add_u32_e32 v4, s2, v134
	s_lshl_b32 s3, s93, 8
	v_and_b32_e32 v2, 32, v130
	v_lshlrev_b32_e32 v13, 4, v130
	v_ashrrev_i32_e32 v5, 31, v4
	v_bitop3_b32 v132, v13, v2, 48 bitop3:0x6c
	v_add_u32_e32 v2, s3, v134
	s_lshl_b32 s1, s0, 10
	v_lshlrev_b64 v[4:5], 9, v[4:5]
	v_ashrrev_i32_e32 v3, 31, v2
	s_add_i32 s96, s1, 0
	v_lshl_add_u64 v[4:5], s[20:21], 0, v[4:5]
	v_lshlrev_b64 v[2:3], 9, v[2:3]
	v_lshl_add_u64 v[4:5], v[4:5], 0, v[132:133]
	s_mov_b32 m0, s96
	s_add_i32 s30, s96, 0x2000
	v_lshl_add_u64 v[2:3], s[22:23], 0, v[2:3]
	global_load_lds_dwordx4 v[4:5], off
	v_lshl_add_u64 v[8:9], v[4:5], 0, s[38:39]
	s_mov_b32 m0, s30
	s_add_i32 s31, s96, 0x4000
	v_lshl_add_u64 v[2:3], v[2:3], 0, v[132:133]
	global_load_lds_dwordx4 v[8:9], off
	s_mov_b32 m0, s31
	s_add_i32 s9, s96, 0x6000
	v_lshl_add_u64 v[6:7], v[2:3], 0, s[38:39]
	global_load_lds_dwordx4 v[2:3], off
	s_mov_b32 m0, s9
	s_add_i32 s4, s96, 0x8000
	global_load_lds_dwordx4 v[6:7], off
	v_lshl_add_u64 v[6:7], v[4:5], 0, 64
	s_mov_b32 m0, s4
	s_add_i32 s5, s96, 0xa000
	s_mov_b64 s[54:55], s[34:35]
	s_mov_b32 s34, s81
	global_load_lds_dwordx4 v[6:7], off
	v_lshl_add_u64 v[6:7], v[4:5], 0, s[40:41]
	s_mov_b32 m0, s5
	s_add_i32 s81, s96, 0xc000
	global_load_lds_dwordx4 v[6:7], off
	v_lshl_add_u64 v[6:7], v[2:3], 0, 64
	s_mov_b32 m0, s81
	s_add_i32 s14, s96, 0xe000
	s_add_i32 vcc_hi, 0, 0x10000
	global_load_lds_dwordx4 v[6:7], off
	v_lshl_add_u64 v[6:7], v[2:3], 0, s[40:41]
	s_mov_b32 m0, s14
	s_add_i32 s1, vcc_hi, s1
	global_load_lds_dwordx4 v[6:7], off
	v_lshl_add_u64 v[6:7], v[4:5], 0, s[44:45]
	s_mov_b32 m0, s1
	s_ashr_i32 s26, s8, 7
	global_load_lds_dwordx4 v[6:7], off
	v_lshl_add_u64 v[6:7], v[4:5], 0, s[50:51]
	s_add_i32 m0, s1, 0x2000
	v_and_b32_e32 v131, 15, v130
	global_load_lds_dwordx4 v[6:7], off
	v_lshl_add_u64 v[6:7], v[2:3], 0, s[44:45]
	s_add_i32 m0, s1, 0x4000
	s_and_b32 s33, s0, 1
	global_load_lds_dwordx4 v[6:7], off
	v_lshl_add_u64 v[6:7], v[2:3], 0, s[50:51]
	s_add_i32 m0, s1, 0x6000
	v_and_b32_e32 v132, 48, v130
	global_load_lds_dwordx4 v[6:7], off
	v_lshlrev_b32_e32 v7, 2, v130
	v_lshlrev_b32_e32 v6, 6, v131
	v_and_b32_e32 v7, 32, v7
	s_lshl_b32 vcc_lo, s26, 12
	v_bitop3_b32 v12, v6, v7, v132 bitop3:0x36
	s_lshl_b32 s97, s33, 13
	s_add_i32 s0, vcc_lo, 0
	v_add_u32_e32 v6, s0, v12
	s_add_i32 s0, s97, 0
	s_waitcnt vmcnt(8)
	s_barrier
	v_add_u32_e32 v8, s0, v12
	ds_read_b128 v[14:17], v8 offset:16384
	ds_read_b128 v[18:21], v8 offset:17408
	ds_read_b128 v[22:25], v8 offset:18432
	ds_read_b128 v[26:29], v8 offset:19456
	ds_read_b128 v[30:33], v8 offset:20480
	ds_read_b128 v[34:37], v8 offset:21504
	ds_read_b128 v[38:41], v8 offset:22528
	ds_read_b128 v[42:45], v8 offset:23552
	ds_read_b128 v[46:49], v6
	ds_read_b128 v[50:53], v6 offset:1024
	s_add_i32 s0, s96, 0x18000
	v_lshl_add_u64 v[10:11], v[4:5], 0, s[52:53]
	s_mov_b32 m0, s0
	s_add_i32 s1, s96, 0x1a000
	global_load_lds_dwordx4 v[10:11], off
	v_lshl_add_u64 v[10:11], v[4:5], 0, s[56:57]
	s_mov_b32 m0, s1
	s_add_i32 s94, s96, 0x1c000
	global_load_lds_dwordx4 v[10:11], off
	v_lshl_add_u64 v[10:11], v[2:3], 0, s[52:53]
	s_mov_b32 m0, s94
	s_add_i32 s95, s96, 0x1e000
	global_load_lds_dwordx4 v[10:11], off
	v_lshl_add_u64 v[10:11], v[2:3], 0, s[56:57]
	s_mov_b32 m0, s95
	s_nop 0
	global_load_lds_dwordx4 v[10:11], off
	s_waitcnt lgkmcnt(0)
	v_mfma_f32_16x16x32_bf16 v[54:57], v[14:17], v[46:49], 0
	v_mfma_f32_16x16x32_bf16 v[58:61], v[18:21], v[46:49], 0
	v_mfma_f32_16x16x32_bf16 v[62:65], v[22:25], v[46:49], 0
	v_mfma_f32_16x16x32_bf16 v[66:69], v[26:29], v[46:49], 0
	v_mfma_f32_16x16x32_bf16 v[70:73], v[30:33], v[46:49], 0
	v_mfma_f32_16x16x32_bf16 v[74:77], v[34:37], v[46:49], 0
	v_mfma_f32_16x16x32_bf16 v[78:81], v[38:41], v[46:49], 0
	v_mfma_f32_16x16x32_bf16 v[46:49], v[42:45], v[46:49], 0
	v_mfma_f32_16x16x32_bf16 v[82:85], v[14:17], v[50:53], 0
	v_mfma_f32_16x16x32_bf16 v[86:89], v[18:21], v[50:53], 0
	v_mfma_f32_16x16x32_bf16 v[90:93], v[22:25], v[50:53], 0
	v_mfma_f32_16x16x32_bf16 v[94:97], v[26:29], v[50:53], 0
	v_mfma_f32_16x16x32_bf16 v[98:101], v[30:33], v[50:53], 0
	v_mfma_f32_16x16x32_bf16 v[102:105], v[34:37], v[50:53], 0
	v_mfma_f32_16x16x32_bf16 v[106:109], v[38:41], v[50:53], 0
	v_mfma_f32_16x16x32_bf16 v[50:53], v[42:45], v[50:53], 0
	ds_read_b128 v[110:113], v6 offset:2048
	ds_read_b128 v[114:117], v6 offset:3072
	s_waitcnt lgkmcnt(0)
	v_mfma_f32_16x16x32_bf16 v[118:121], v[14:17], v[110:113], 0
	v_mfma_f32_16x16x32_bf16 v[122:125], v[18:21], v[110:113], 0
	v_mfma_f32_16x16x32_bf16 v[126:129], v[22:25], v[110:113], 0
	v_mfma_f32_16x16x32_bf16 v[138:141], v[26:29], v[110:113], 0
	v_mfma_f32_16x16x32_bf16 v[150:153], v[30:33], v[110:113], 0
	v_mfma_f32_16x16x32_bf16 v[154:157], v[34:37], v[110:113], 0
	v_mfma_f32_16x16x32_bf16 v[158:161], v[38:41], v[110:113], 0
	v_mfma_f32_16x16x32_bf16 v[110:113], v[42:45], v[110:113], 0
	v_mfma_f32_16x16x32_bf16 v[14:17], v[14:17], v[114:117], 0
	v_mfma_f32_16x16x32_bf16 v[18:21], v[18:21], v[114:117], 0
	v_mfma_f32_16x16x32_bf16 v[22:25], v[22:25], v[114:117], 0
	v_mfma_f32_16x16x32_bf16 v[26:29], v[26:29], v[114:117], 0
	v_mfma_f32_16x16x32_bf16 v[30:33], v[30:33], v[114:117], 0
	v_mfma_f32_16x16x32_bf16 v[34:37], v[34:37], v[114:117], 0
	v_mfma_f32_16x16x32_bf16 v[38:41], v[38:41], v[114:117], 0
	v_mfma_f32_16x16x32_bf16 v[42:45], v[42:45], v[114:117], 0
	v_add_u32_e32 v7, 0, v13
	ds_read_b128 v[114:117], v7
	s_waitcnt lgkmcnt(0)
	v_lshlrev_b32_e32 v9, 16, v114
	v_and_b32_e32 v10, 0xffff0000, v114
	v_lshlrev_b32_e32 v11, 16, v115
	v_and_b32_e32 v137, 0xffff0000, v115
	v_lshlrev_b32_e32 v142, 16, v116
	v_and_b32_e32 v143, 0xffff0000, v116
	v_lshlrev_b32_e32 v149, 16, v117
	v_and_b32_e32 v162, 0xffff0000, v117
	ds_read_b128 v[114:117], v7 offset:8192
	v_mul_f32_e32 v135, v9, v9
	v_fmac_f32_e32 v135, v10, v10
	v_fmac_f32_e32 v135, v11, v11
	v_fmac_f32_e32 v135, v137, v137
	s_waitcnt lgkmcnt(0)
	v_lshlrev_b32_e32 v9, 16, v114
	v_and_b32_e32 v114, 0xffff0000, v114
	v_mul_f32_e32 v136, v9, v9
	v_lshlrev_b32_e32 v163, 16, v115
	v_fmac_f32_e32 v136, v114, v114
	v_and_b32_e32 v115, 0xffff0000, v115
	v_fmac_f32_e32 v136, v163, v163
	v_lshlrev_b32_e32 v164, 16, v116
	v_fmac_f32_e32 v136, v115, v115
	v_and_b32_e32 v116, 0xffff0000, v116
	v_fmac_f32_e32 v136, v164, v164
	v_fmac_f32_e32 v135, v142, v142
	v_lshlrev_b32_e32 v165, 16, v117
	v_fmac_f32_e32 v136, v116, v116
	v_fmac_f32_e32 v135, v143, v143
	v_and_b32_e32 v117, 0xffff0000, v117
	v_fmac_f32_e32 v136, v165, v165
	v_fmac_f32_e32 v135, v149, v149
	s_waitcnt vmcnt(8)
	s_barrier
; DI void unpack8(uint4 u, float* v) { v[0] = bflo(u.x); v[1] = bfhi(u.x); v[2] = bflo(u.y); v[3] = bfhi(u.y); v[4] = bflo(u.z); v[5] = bfhi(u.z); v[6] = bflo(u.w); v[7] = bfhi(u.w); }
; #define MFMA16(a, b, c) __builtin_amdgcn_mfma_f32_16x16x32_bf16((a), (b), (c), 0, 0, 0)
; template <bool ROWSS, class AL, class EPI>
; DI void gemm8(unsigned char* smem, const AL& al, const bf16_t* __restrict__ Bt, int K, int m0, int n0, const EPI& epi) {
;     ...
;   for (int t = 0; t < nt; ++t) {
;     if (t + 2 < nt) asm volatile("s_waitcnt vmcnt(8)" ::: "memory");
;     else if (t + 1 < nt) asm volatile("s_waitcnt vmcnt(4)" ::: "memory");
;     else asm volatile("s_waitcnt vmcnt(0)" ::: "memory");
;     __builtin_amdgcn_s_barrier();
;     asm volatile("" ::: "memory");
;     const unsigned char* sa = smem + (t & 3) * 32768 + aoff;
;     const unsigned char* sb = smem + (t & 3) * 32768 + boff;
;     bf16x8 af0, af1, bfr[8];
;     af0 = *(const bf16x8*)(sa);
; #pragma unroll
;     for (int n = 0; n < 8; ++n) bfr[n] = *(const bf16x8*)(sb + n * 1024);
;     af1 = *(const bf16x8*)(sa + 1024);
;     __builtin_amdgcn_sched_barrier(0);
;     if (t + 3 < nt) G8_ISSUE(t + 3);
;     __builtin_amdgcn_sched_barrier(0);
; #pragma unroll
;     for (int n = 0; n < 8; ++n) acc[0][n] = MFMA16(bfr[n], af0, acc[0][n]);
; #pragma unroll
;     for (int n = 0; n < 8; ++n) acc[1][n] = MFMA16(bfr[n], af1, acc[1][n]);
;     __builtin_amdgcn_sched_barrier(0);
;     af0 = *(const bf16x8*)(sa + 2048); af1 = *(const bf16x8*)(sa + 3072);
;     __builtin_amdgcn_sched_barrier(0);
; #pragma unroll
;     for (int n = 0; n < 8; ++n) acc[2][n] = MFMA16(bfr[n], af0, acc[2][n]);
; #pragma unroll
;     for (int n = 0; n < 8; ++n) acc[3][n] = MFMA16(bfr[n], af1, acc[3][n]);
;     __builtin_amdgcn_sched_barrier(0);
;     if (ROWSS) {
;       float v[8];
;       unpack8(*(const uint4*)(smem + (t & 3) * 32768 + ptid * 16), v);
; #pragma unroll
;       for (int j = 0; j < 8; ++j) ss0 += v[j] * v[j];
;       unpack8(*(const uint4*)(smem + (t & 3) * 32768 + ptid * 16 + 8192), v);
; #pragma unroll
;       for (int j = 0; j < 8; ++j) ss1 += v[j] * v[j];
	v_fmac_f32_e32 v136, v117, v117
	v_fmac_f32_e32 v135, v162, v162
	ds_read_b128 v[114:117], v6 offset:32768
	ds_read_b128 v[162:165], v8 offset:49152
	ds_read_b128 v[166:169], v8 offset:50176
	ds_read_b128 v[170:173], v8 offset:51200
	ds_read_b128 v[174:177], v8 offset:52224
	ds_read_b128 v[178:181], v8 offset:53248
	ds_read_b128 v[182:185], v8 offset:54272
	ds_read_b128 v[186:189], v8 offset:55296
	ds_read_b128 v[190:193], v8 offset:56320
	ds_read_b128 v[194:197], v6 offset:33792
	s_mov_b32 m0, s96
	v_lshl_add_u64 v[10:11], v[4:5], 0, s[58:59]
	global_load_lds_dwordx4 v[10:11], off
	v_lshl_add_u64 v[10:11], v[4:5], 0, s[60:61]
	s_mov_b32 m0, s30
	s_nop 0
	global_load_lds_dwordx4 v[10:11], off
	v_lshl_add_u64 v[10:11], v[2:3], 0, s[58:59]
	s_mov_b32 m0, s31
	s_nop 0
	global_load_lds_dwordx4 v[10:11], off
	v_lshl_add_u64 v[10:11], v[2:3], 0, s[60:61]
	s_mov_b32 m0, s9
	s_nop 0
	global_load_lds_dwordx4 v[10:11], off
	s_waitcnt lgkmcnt(0)
	v_mfma_f32_16x16x32_bf16 v[54:57], v[162:165], v[114:117], v[54:57]
	v_mfma_f32_16x16x32_bf16 v[58:61], v[166:169], v[114:117], v[58:61]
	v_mfma_f32_16x16x32_bf16 v[62:65], v[170:173], v[114:117], v[62:65]
	v_mfma_f32_16x16x32_bf16 v[66:69], v[174:177], v[114:117], v[66:69]
	v_mfma_f32_16x16x32_bf16 v[70:73], v[178:181], v[114:117], v[70:73]
	v_mfma_f32_16x16x32_bf16 v[74:77], v[182:185], v[114:117], v[74:77]
	v_mfma_f32_16x16x32_bf16 v[78:81], v[186:189], v[114:117], v[78:81]
	v_mfma_f32_16x16x32_bf16 v[46:49], v[190:193], v[114:117], v[46:49]
	ds_read_b128 v[114:117], v6 offset:34816
	v_mfma_f32_16x16x32_bf16 v[82:85], v[162:165], v[194:197], v[82:85]
	v_mfma_f32_16x16x32_bf16 v[86:89], v[166:169], v[194:197], v[86:89]
	v_mfma_f32_16x16x32_bf16 v[90:93], v[170:173], v[194:197], v[90:93]
	v_mfma_f32_16x16x32_bf16 v[94:97], v[174:177], v[194:197], v[94:97]
	v_mfma_f32_16x16x32_bf16 v[98:101], v[178:181], v[194:197], v[98:101]
	v_mfma_f32_16x16x32_bf16 v[102:105], v[182:185], v[194:197], v[102:105]
	v_mfma_f32_16x16x32_bf16 v[106:109], v[186:189], v[194:197], v[106:109]
	v_mfma_f32_16x16x32_bf16 v[50:53], v[190:193], v[194:197], v[50:53]
	ds_read_b128 v[194:197], v6 offset:35840
	s_waitcnt lgkmcnt(1)
	v_mfma_f32_16x16x32_bf16 v[118:121], v[162:165], v[114:117], v[118:121]
	v_mfma_f32_16x16x32_bf16 v[122:125], v[166:169], v[114:117], v[122:125]
	v_mfma_f32_16x16x32_bf16 v[126:129], v[170:173], v[114:117], v[126:129]
	v_mfma_f32_16x16x32_bf16 v[138:141], v[174:177], v[114:117], v[138:141]
	v_mfma_f32_16x16x32_bf16 v[110:113], v[190:193], v[114:117], v[110:113]
	s_waitcnt lgkmcnt(0)
	v_mfma_f32_16x16x32_bf16 v[14:17], v[162:165], v[194:197], v[14:17]
	v_mfma_f32_16x16x32_bf16 v[18:21], v[166:169], v[194:197], v[18:21]
	v_mfma_f32_16x16x32_bf16 v[22:25], v[170:173], v[194:197], v[22:25]
	v_mfma_f32_16x16x32_bf16 v[26:29], v[174:177], v[194:197], v[26:29]
	v_mfma_f32_16x16x32_bf16 v[30:33], v[178:181], v[194:197], v[30:33]
	v_mfma_f32_16x16x32_bf16 v[34:37], v[182:185], v[194:197], v[34:37]
	v_mfma_f32_16x16x32_bf16 v[38:41], v[186:189], v[194:197], v[38:41]
	v_mfma_f32_16x16x32_bf16 v[42:45], v[190:193], v[194:197], v[42:45]
	v_mfma_f32_16x16x32_bf16 v[150:153], v[178:181], v[114:117], v[150:153]
	v_mfma_f32_16x16x32_bf16 v[154:157], v[182:185], v[114:117], v[154:157]
	v_mfma_f32_16x16x32_bf16 v[158:161], v[186:189], v[114:117], v[158:161]
	ds_read_b128 v[114:117], v7 offset:32768
	s_add_i32 s9, vcc_hi, vcc_lo
	s_waitcnt lgkmcnt(0)
	v_lshlrev_b32_e32 v9, 16, v114
	v_and_b32_e32 v10, 0xffff0000, v114
	v_lshlrev_b32_e32 v11, 16, v115
	v_and_b32_e32 v137, 0xffff0000, v115
	v_lshlrev_b32_e32 v142, 16, v116
	v_and_b32_e32 v143, 0xffff0000, v116
	v_lshlrev_b32_e32 v149, 16, v117
	v_and_b32_e32 v162, 0xffff0000, v117
	ds_read_b128 v[114:117], v7 offset:40960
	v_fmac_f32_e32 v135, v9, v9
	v_fmac_f32_e32 v135, v10, v10
	v_fmac_f32_e32 v135, v11, v11
	v_fmac_f32_e32 v135, v137, v137
	s_waitcnt lgkmcnt(0)
	v_lshlrev_b32_e32 v163, 16, v114
	v_and_b32_e32 v114, 0xffff0000, v114
	v_fmac_f32_e32 v136, v163, v163
	v_lshlrev_b32_e32 v164, 16, v115
	v_fmac_f32_e32 v136, v114, v114
	v_and_b32_e32 v115, 0xffff0000, v115
	v_fmac_f32_e32 v136, v164, v164
	v_lshlrev_b32_e32 v165, 16, v116
	v_fmac_f32_e32 v136, v115, v115
	v_and_b32_e32 v116, 0xffff0000, v116
	v_fmac_f32_e32 v136, v165, v165
	v_fmac_f32_e32 v135, v142, v142
	v_lshlrev_b32_e32 v166, 16, v117
	v_fmac_f32_e32 v136, v116, v116
	v_fmac_f32_e32 v135, v143, v143
	v_and_b32_e32 v117, 0xffff0000, v117
	v_fmac_f32_e32 v136, v166, v166
	v_fmac_f32_e32 v135, v149, v149
	s_waitcnt vmcnt(8)
	s_barrier
; DI void unpack8(uint4 u, float* v) { v[0] = bflo(u.x); v[1] = bfhi(u.x); v[2] = bflo(u.y); v[3] = bfhi(u.y); v[4] = bflo(u.z); v[5] = bfhi(u.z); v[6] = bflo(u.w); v[7] = bfhi(u.w); }
; #define MFMA16(a, b, c) __builtin_amdgcn_mfma_f32_16x16x32_bf16((a), (b), (c), 0, 0, 0)
; template <bool ROWSS, class AL, class EPI>
; DI void gemm8(unsigned char* smem, const AL& al, const bf16_t* __restrict__ Bt, int K, int m0, int n0, const EPI& epi) {
;     ...
;   for (int t = 0; t < nt; ++t) {
;     if (t + 2 < nt) asm volatile("s_waitcnt vmcnt(8)" ::: "memory");
;     else if (t + 1 < nt) asm volatile("s_waitcnt vmcnt(4)" ::: "memory");
;     else asm volatile("s_waitcnt vmcnt(0)" ::: "memory");
;     __builtin_amdgcn_s_barrier();
;     asm volatile("" ::: "memory");
;     const unsigned char* sa = smem + (t & 3) * 32768 + aoff;
;     const unsigned char* sb = smem + (t & 3) * 32768 + boff;
;     bf16x8 af0, af1, bfr[8];
;     af0 = *(const bf16x8*)(sa);
; #pragma unroll
;     for (int n = 0; n < 8; ++n) bfr[n] = *(const bf16x8*)(sb + n * 1024);
;     af1 = *(const bf16x8*)(sa + 1024);
;     __builtin_amdgcn_sched_barrier(0);
;     if (t + 3 < nt) G8_ISSUE(t + 3);
;     __builtin_amdgcn_sched_barrier(0);
; #pragma unroll
;     for (int n = 0; n < 8; ++n) acc[0][n] = MFMA16(bfr[n], af0, acc[0][n]);
; #pragma unroll
;     for (int n = 0; n < 8; ++n) acc[1][n] = MFMA16(bfr[n], af1, acc[1][n]);
;     __builtin_amdgcn_sched_barrier(0);
;     af0 = *(const bf16x8*)(sa + 2048); af1 = *(const bf16x8*)(sa + 3072);
;     __builtin_amdgcn_sched_barrier(0);
; #pragma unroll
;     for (int n = 0; n < 8; ++n) acc[2][n] = MFMA16(bfr[n], af0, acc[2][n]);
; #pragma unroll
;     for (int n = 0; n < 8; ++n) acc[3][n] = MFMA16(bfr[n], af1, acc[3][n]);
;     __builtin_amdgcn_sched_barrier(0);
;     if (ROWSS) {
;       float v[8];
;       unpack8(*(const uint4*)(smem + (t & 3) * 32768 + ptid * 16), v);
; #pragma unroll
;       for (int j = 0; j < 8; ++j) ss0 += v[j] * v[j];
;       unpack8(*(const uint4*)(smem + (t & 3) * 32768 + ptid * 16 + 8192), v);
; #pragma unroll
;       for (int j = 0; j < 8; ++j) ss1 += v[j] * v[j];
	v_add_u32_e32 v9, s9, v12
	s_add_i32 s9, vcc_hi, s97
	v_fmac_f32_e32 v136, v117, v117
	v_fmac_f32_e32 v135, v162, v162
	v_add_u32_e32 v11, s9, v12
	ds_read_b128 v[114:117], v9
	ds_read_b128 v[162:165], v11 offset:16384
	ds_read_b128 v[166:169], v11 offset:17408
	ds_read_b128 v[170:173], v11 offset:18432
	ds_read_b128 v[174:177], v11 offset:19456
	ds_read_b128 v[178:181], v11 offset:20480
	ds_read_b128 v[182:185], v11 offset:21504
	ds_read_b128 v[186:189], v11 offset:22528
	ds_read_b128 v[190:193], v11 offset:23552
	ds_read_b128 v[194:197], v9 offset:1024
	s_mov_b32 m0, s4
	v_lshl_add_u64 v[142:143], v[4:5], 0, s[62:63]
	global_load_lds_dwordx4 v[142:143], off
	v_lshl_add_u64 v[142:143], v[4:5], 0, s[64:65]
	s_mov_b32 m0, s5
	s_nop 0
	global_load_lds_dwordx4 v[142:143], off
	v_lshl_add_u64 v[142:143], v[2:3], 0, s[62:63]
	s_mov_b32 m0, s81
	s_nop 0
	global_load_lds_dwordx4 v[142:143], off
	v_lshl_add_u64 v[142:143], v[2:3], 0, s[64:65]
	s_mov_b32 m0, s14
	s_nop 0
	global_load_lds_dwordx4 v[142:143], off
	s_waitcnt lgkmcnt(0)
	v_mfma_f32_16x16x32_bf16 v[54:57], v[162:165], v[114:117], v[54:57]
	v_mfma_f32_16x16x32_bf16 v[58:61], v[166:169], v[114:117], v[58:61]
	v_mfma_f32_16x16x32_bf16 v[62:65], v[170:173], v[114:117], v[62:65]
	v_mfma_f32_16x16x32_bf16 v[198:201], v[174:177], v[114:117], v[66:69]
	v_mfma_f32_16x16x32_bf16 v[68:71], v[178:181], v[114:117], v[70:73]
	v_mfma_f32_16x16x32_bf16 v[72:75], v[182:185], v[114:117], v[74:77]
	v_mfma_f32_16x16x32_bf16 v[76:79], v[186:189], v[114:117], v[78:81]
	v_mfma_f32_16x16x32_bf16 v[46:49], v[190:193], v[114:117], v[46:49]
	ds_read_b128 v[114:117], v9 offset:2048
	v_mfma_f32_16x16x32_bf16 v[80:83], v[162:165], v[194:197], v[82:85]
	v_mfma_f32_16x16x32_bf16 v[84:87], v[166:169], v[194:197], v[86:89]
	v_mfma_f32_16x16x32_bf16 v[88:91], v[170:173], v[194:197], v[90:93]
	v_mfma_f32_16x16x32_bf16 v[92:95], v[174:177], v[194:197], v[94:97]
	v_mfma_f32_16x16x32_bf16 v[96:99], v[178:181], v[194:197], v[98:101]
	v_mfma_f32_16x16x32_bf16 v[100:103], v[182:185], v[194:197], v[102:105]
	v_mfma_f32_16x16x32_bf16 v[104:107], v[186:189], v[194:197], v[106:109]
	v_mfma_f32_16x16x32_bf16 v[50:53], v[190:193], v[194:197], v[50:53]
	ds_read_b128 v[194:197], v9 offset:3072
	s_waitcnt lgkmcnt(1)
	v_mfma_f32_16x16x32_bf16 v[118:121], v[162:165], v[114:117], v[118:121]
	v_mfma_f32_16x16x32_bf16 v[122:125], v[166:169], v[114:117], v[122:125]
	v_mfma_f32_16x16x32_bf16 v[126:129], v[170:173], v[114:117], v[126:129]
	v_mfma_f32_16x16x32_bf16 v[138:141], v[174:177], v[114:117], v[138:141]
	v_mfma_f32_16x16x32_bf16 v[108:111], v[190:193], v[114:117], v[110:113]
	s_waitcnt lgkmcnt(0)
	v_mfma_f32_16x16x32_bf16 v[14:17], v[162:165], v[194:197], v[14:17]
	v_mfma_f32_16x16x32_bf16 v[18:21], v[166:169], v[194:197], v[18:21]
	v_mfma_f32_16x16x32_bf16 v[22:25], v[170:173], v[194:197], v[22:25]
	v_mfma_f32_16x16x32_bf16 v[26:29], v[174:177], v[194:197], v[26:29]
	v_mfma_f32_16x16x32_bf16 v[30:33], v[178:181], v[194:197], v[30:33]
	v_mfma_f32_16x16x32_bf16 v[34:37], v[182:185], v[194:197], v[34:37]
	v_mfma_f32_16x16x32_bf16 v[38:41], v[186:189], v[194:197], v[38:41]
	v_mfma_f32_16x16x32_bf16 v[42:45], v[190:193], v[194:197], v[42:45]
	v_mfma_f32_16x16x32_bf16 v[150:153], v[178:181], v[114:117], v[150:153]
	v_mfma_f32_16x16x32_bf16 v[154:157], v[182:185], v[114:117], v[154:157]
	v_mfma_f32_16x16x32_bf16 v[158:161], v[186:189], v[114:117], v[158:161]
	v_add_u32_e32 v10, vcc_hi, v13
	ds_read_b128 v[112:115], v10
	s_add_i32 s4, 0, 0x18000
	s_add_i32 s5, s4, vcc_lo
	s_waitcnt lgkmcnt(0)
	v_lshlrev_b32_e32 v66, 16, v112
	v_and_b32_e32 v67, 0xffff0000, v112
	v_lshlrev_b32_e32 v116, 16, v113
	v_and_b32_e32 v117, 0xffff0000, v113
	v_lshlrev_b32_e32 v137, 16, v114
	v_and_b32_e32 v142, 0xffff0000, v114
	v_lshlrev_b32_e32 v143, 16, v115
	v_and_b32_e32 v149, 0xffff0000, v115
	ds_read_b128 v[112:115], v10 offset:8192
	v_fmac_f32_e32 v135, v66, v66
	s_waitcnt vmcnt(8)
	s_barrier
	s_waitcnt lgkmcnt(0)
	v_lshlrev_b32_e32 v162, 16, v112
	v_and_b32_e32 v112, 0xffff0000, v112
	v_fmac_f32_e32 v136, v162, v162
	v_lshlrev_b32_e32 v163, 16, v113
	v_fmac_f32_e32 v136, v112, v112
	v_and_b32_e32 v113, 0xffff0000, v113
	v_fmac_f32_e32 v136, v163, v163
	v_lshlrev_b32_e32 v164, 16, v114
	v_fmac_f32_e32 v136, v113, v113
	v_and_b32_e32 v114, 0xffff0000, v114
	v_fmac_f32_e32 v136, v164, v164
	v_lshlrev_b32_e32 v165, 16, v115
	v_fmac_f32_e32 v136, v114, v114
	v_and_b32_e32 v115, 0xffff0000, v115
	v_fmac_f32_e32 v136, v165, v165
	v_add_u32_e32 v66, s5, v12
	s_add_i32 s5, s4, s97
	v_fmac_f32_e32 v136, v115, v115
	v_add_u32_e32 v12, s5, v12
	ds_read_b128 v[112:115], v66
	ds_read_b128 v[162:165], v12 offset:16384
	ds_read_b128 v[166:169], v12 offset:17408
	ds_read_b128 v[170:173], v12 offset:18432
	ds_read_b128 v[174:177], v12 offset:19456
	ds_read_b128 v[178:181], v12 offset:20480
	ds_read_b128 v[182:185], v12 offset:21504
	ds_read_b128 v[186:189], v12 offset:22528
	ds_read_b128 v[190:193], v12 offset:23552
	ds_read_b128 v[194:197], v66 offset:1024
	v_fmac_f32_e32 v135, v67, v67
	v_fmac_f32_e32 v135, v116, v116
	v_fmac_f32_e32 v135, v117, v117
	v_fmac_f32_e32 v135, v137, v137
	v_fmac_f32_e32 v135, v142, v142
	v_fmac_f32_e32 v135, v143, v143
	v_fmac_f32_e32 v135, v149, v149
	s_add_i32 m0, s96, 0x10000
	v_lshl_add_u64 v[116:117], v[4:5], 0, s[66:67]
	global_load_lds_dwordx4 v[116:117], off
	v_lshl_add_u64 v[116:117], v[4:5], 0, s[74:75]
	s_add_i32 m0, s96, 0x12000
	s_nop 0
	global_load_lds_dwordx4 v[116:117], off
	v_lshl_add_u64 v[116:117], v[2:3], 0, s[66:67]
	s_add_i32 m0, s96, 0x14000
	s_nop 0
	global_load_lds_dwordx4 v[116:117], off
	v_lshl_add_u64 v[116:117], v[2:3], 0, s[74:75]
	s_add_i32 m0, s96, 0x16000
	s_nop 0
	global_load_lds_dwordx4 v[116:117], off
	s_waitcnt lgkmcnt(0)
; DI void unpack8(uint4 u, float* v) { v[0] = bflo(u.x); v[1] = bfhi(u.x); v[2] = bflo(u.y); v[3] = bfhi(u.y); v[4] = bflo(u.z); v[5] = bfhi(u.z); v[6] = bflo(u.w); v[7] = bfhi(u.w); }
; #define MFMA16(a, b, c) __builtin_amdgcn_mfma_f32_16x16x32_bf16((a), (b), (c), 0, 0, 0)
; template <bool ROWSS, class AL, class EPI>
; DI void gemm8(unsigned char* smem, const AL& al, const bf16_t* __restrict__ Bt, int K, int m0, int n0, const EPI& epi) {
;     ...
;   for (int t = 0; t < nt; ++t) {
;     if (t + 2 < nt) asm volatile("s_waitcnt vmcnt(8)" ::: "memory");
;     else if (t + 1 < nt) asm volatile("s_waitcnt vmcnt(4)" ::: "memory");
;     else asm volatile("s_waitcnt vmcnt(0)" ::: "memory");
;     __builtin_amdgcn_s_barrier();
;     asm volatile("" ::: "memory");
;     const unsigned char* sa = smem + (t & 3) * 32768 + aoff;
;     const unsigned char* sb = smem + (t & 3) * 32768 + boff;
;     bf16x8 af0, af1, bfr[8];
;     af0 = *(const bf16x8*)(sa);
; #pragma unroll
;     for (int n = 0; n < 8; ++n) bfr[n] = *(const bf16x8*)(sb + n * 1024);
;     af1 = *(const bf16x8*)(sa + 1024);
;     __builtin_amdgcn_sched_barrier(0);
;     if (t + 3 < nt) G8_ISSUE(t + 3);
;     __builtin_amdgcn_sched_barrier(0);
; #pragma unroll
;     for (int n = 0; n < 8; ++n) acc[0][n] = MFMA16(bfr[n], af0, acc[0][n]);
; #pragma unroll
;     for (int n = 0; n < 8; ++n) acc[1][n] = MFMA16(bfr[n], af1, acc[1][n]);
;     __builtin_amdgcn_sched_barrier(0);
;     af0 = *(const bf16x8*)(sa + 2048); af1 = *(const bf16x8*)(sa + 3072);
;     __builtin_amdgcn_sched_barrier(0);
; #pragma unroll
;     for (int n = 0; n < 8; ++n) acc[2][n] = MFMA16(bfr[n], af0, acc[2][n]);
; #pragma unroll
;     for (int n = 0; n < 8; ++n) acc[3][n] = MFMA16(bfr[n], af1, acc[3][n]);
;     __builtin_amdgcn_sched_barrier(0);
;     if (ROWSS) {
;       float v[8];
;       unpack8(*(const uint4*)(smem + (t & 3) * 32768 + ptid * 16), v);
; #pragma unroll
;       for (int j = 0; j < 8; ++j) ss0 += v[j] * v[j];
;       unpack8(*(const uint4*)(smem + (t & 3) * 32768 + ptid * 16 + 8192), v);
; #pragma unroll
;       for (int j = 0; j < 8; ++j) ss1 += v[j] * v[j];
	v_mfma_f32_16x16x32_bf16 v[54:57], v[162:165], v[112:115], v[54:57]
	v_mfma_f32_16x16x32_bf16 v[58:61], v[166:169], v[112:115], v[58:61]
	v_mfma_f32_16x16x32_bf16 v[62:65], v[170:173], v[112:115], v[62:65]
	v_mfma_f32_16x16x32_bf16 v[68:71], v[178:181], v[112:115], v[68:71]
	v_mfma_f32_16x16x32_bf16 v[72:75], v[182:185], v[112:115], v[72:75]
	v_mfma_f32_16x16x32_bf16 v[76:79], v[186:189], v[112:115], v[76:79]
	v_mfma_f32_16x16x32_bf16 v[46:49], v[190:193], v[112:115], v[46:49]
	v_mfma_f32_16x16x32_bf16 v[80:83], v[162:165], v[194:197], v[80:83]
	v_mfma_f32_16x16x32_bf16 v[84:87], v[166:169], v[194:197], v[84:87]
	v_mfma_f32_16x16x32_bf16 v[88:91], v[170:173], v[194:197], v[88:91]
	v_mfma_f32_16x16x32_bf16 v[92:95], v[174:177], v[194:197], v[92:95]
	v_mfma_f32_16x16x32_bf16 v[96:99], v[178:181], v[194:197], v[96:99]
	v_mfma_f32_16x16x32_bf16 v[100:103], v[182:185], v[194:197], v[100:103]
	v_mfma_f32_16x16x32_bf16 v[104:107], v[186:189], v[194:197], v[104:107]
	v_mfma_f32_16x16x32_bf16 v[50:53], v[190:193], v[194:197], v[50:53]
	v_mfma_f32_16x16x32_bf16 v[198:201], v[174:177], v[112:115], v[198:201]
	ds_read_b128 v[112:115], v66 offset:2048
	ds_read_b128 v[194:197], v66 offset:3072
	s_waitcnt lgkmcnt(0)
	v_mfma_f32_16x16x32_bf16 v[116:119], v[162:165], v[112:115], v[118:121]
	v_mfma_f32_16x16x32_bf16 v[120:123], v[166:169], v[112:115], v[122:125]
	v_mfma_f32_16x16x32_bf16 v[124:127], v[170:173], v[112:115], v[126:129]
	v_mfma_f32_16x16x32_bf16 v[138:141], v[174:177], v[112:115], v[138:141]
	v_mfma_f32_16x16x32_bf16 v[108:111], v[190:193], v[112:115], v[108:111]
	v_mfma_f32_16x16x32_bf16 v[14:17], v[162:165], v[194:197], v[14:17]
	v_mfma_f32_16x16x32_bf16 v[18:21], v[166:169], v[194:197], v[18:21]
	v_mfma_f32_16x16x32_bf16 v[22:25], v[170:173], v[194:197], v[22:25]
	v_mfma_f32_16x16x32_bf16 v[26:29], v[174:177], v[194:197], v[26:29]
	v_mfma_f32_16x16x32_bf16 v[30:33], v[178:181], v[194:197], v[30:33]
	v_mfma_f32_16x16x32_bf16 v[34:37], v[182:185], v[194:197], v[34:37]
	v_mfma_f32_16x16x32_bf16 v[38:41], v[186:189], v[194:197], v[38:41]
	v_mfma_f32_16x16x32_bf16 v[42:45], v[190:193], v[194:197], v[42:45]
	v_mfma_f32_16x16x32_bf16 v[150:153], v[178:181], v[112:115], v[150:153]
	v_mfma_f32_16x16x32_bf16 v[154:157], v[182:185], v[112:115], v[154:157]
	v_mfma_f32_16x16x32_bf16 v[158:161], v[186:189], v[112:115], v[158:161]
	v_add_u32_e32 v137, s4, v13
	ds_read_b128 v[112:115], v137
	s_waitcnt lgkmcnt(0)
	v_lshlrev_b32_e32 v13, 16, v112
	v_and_b32_e32 v67, 0xffff0000, v112
	v_lshlrev_b32_e32 v128, 16, v113
	v_and_b32_e32 v129, 0xffff0000, v113
	v_lshlrev_b32_e32 v142, 16, v114
	v_and_b32_e32 v143, 0xffff0000, v114
	v_lshlrev_b32_e32 v149, 16, v115
	v_and_b32_e32 v162, 0xffff0000, v115
	ds_read_b128 v[112:115], v137 offset:8192
	v_fmac_f32_e32 v135, v13, v13
	v_fmac_f32_e32 v135, v67, v67
	v_fmac_f32_e32 v135, v128, v128
	v_fmac_f32_e32 v135, v129, v129
	s_waitcnt lgkmcnt(0)
	v_lshlrev_b32_e32 v163, 16, v112
	v_and_b32_e32 v112, 0xffff0000, v112
	v_fmac_f32_e32 v136, v163, v163
	v_lshlrev_b32_e32 v164, 16, v113
	v_fmac_f32_e32 v136, v112, v112
	v_and_b32_e32 v113, 0xffff0000, v113
	v_fmac_f32_e32 v136, v164, v164
	v_lshlrev_b32_e32 v165, 16, v114
	v_fmac_f32_e32 v136, v113, v113
	v_and_b32_e32 v114, 0xffff0000, v114
	v_fmac_f32_e32 v136, v165, v165
	v_fmac_f32_e32 v135, v142, v142
	v_lshlrev_b32_e32 v166, 16, v115
	v_fmac_f32_e32 v136, v114, v114
	v_fmac_f32_e32 v135, v143, v143
	v_and_b32_e32 v115, 0xffff0000, v115
	v_fmac_f32_e32 v136, v166, v166
	v_fmac_f32_e32 v135, v149, v149
	s_waitcnt vmcnt(8)
	s_barrier
	v_fmac_f32_e32 v136, v115, v115
	v_fmac_f32_e32 v135, v162, v162
	ds_read_b128 v[112:115], v6
	ds_read_b128 v[162:165], v8 offset:16384
	ds_read_b128 v[166:169], v8 offset:17408
	ds_read_b128 v[170:173], v8 offset:18432
	ds_read_b128 v[174:177], v8 offset:19456
	ds_read_b128 v[178:181], v8 offset:20480
	ds_read_b128 v[182:185], v8 offset:21504
	ds_read_b128 v[186:189], v8 offset:22528
	ds_read_b128 v[190:193], v8 offset:23552
	ds_read_b128 v[194:197], v6 offset:1024
	s_mov_b32 m0, s0
	v_lshl_add_u64 v[128:129], v[4:5], 0, s[76:77]
	global_load_lds_dwordx4 v[128:129], off
	v_lshl_add_u64 v[4:5], v[4:5], 0, s[78:79]
	s_mov_b32 m0, s1
	s_nop 0
	global_load_lds_dwordx4 v[4:5], off
	v_lshl_add_u64 v[4:5], v[2:3], 0, s[76:77]
	s_mov_b32 m0, s94
	v_lshl_add_u64 v[2:3], v[2:3], 0, s[78:79]
	global_load_lds_dwordx4 v[4:5], off
	s_mov_b32 m0, s95
	s_nop 0
	global_load_lds_dwordx4 v[2:3], off
	s_waitcnt lgkmcnt(0)
	v_mfma_f32_16x16x32_bf16 v[2:5], v[162:165], v[112:115], v[54:57]
	v_mfma_f32_16x16x32_bf16 v[54:57], v[166:169], v[112:115], v[58:61]
	v_mfma_f32_16x16x32_bf16 v[58:61], v[170:173], v[112:115], v[62:65]
	v_mfma_f32_16x16x32_bf16 v[62:65], v[174:177], v[112:115], v[198:201]
	v_mfma_f32_16x16x32_bf16 v[68:71], v[178:181], v[112:115], v[68:71]
	v_mfma_f32_16x16x32_bf16 v[72:75], v[182:185], v[112:115], v[72:75]
	v_mfma_f32_16x16x32_bf16 v[76:79], v[186:189], v[112:115], v[76:79]
	v_mfma_f32_16x16x32_bf16 v[46:49], v[190:193], v[112:115], v[46:49]
	ds_read_b128 v[112:115], v6 offset:2048
	v_mfma_f32_16x16x32_bf16 v[80:83], v[162:165], v[194:197], v[80:83]
	v_mfma_f32_16x16x32_bf16 v[84:87], v[166:169], v[194:197], v[84:87]
	v_mfma_f32_16x16x32_bf16 v[88:91], v[170:173], v[194:197], v[88:91]
	v_mfma_f32_16x16x32_bf16 v[92:95], v[174:177], v[194:197], v[92:95]
	v_mfma_f32_16x16x32_bf16 v[96:99], v[178:181], v[194:197], v[96:99]
	v_mfma_f32_16x16x32_bf16 v[100:103], v[182:185], v[194:197], v[100:103]
	v_mfma_f32_16x16x32_bf16 v[104:107], v[186:189], v[194:197], v[104:107]
	v_mfma_f32_16x16x32_bf16 v[50:53], v[190:193], v[194:197], v[50:53]
	ds_read_b128 v[194:197], v6 offset:3072
	s_waitcnt lgkmcnt(1)
; DI void unpack8(uint4 u, float* v) { v[0] = bflo(u.x); v[1] = bfhi(u.x); v[2] = bflo(u.y); v[3] = bfhi(u.y); v[4] = bflo(u.z); v[5] = bfhi(u.z); v[6] = bflo(u.w); v[7] = bfhi(u.w); }
; #define MFMA16(a, b, c) __builtin_amdgcn_mfma_f32_16x16x32_bf16((a), (b), (c), 0, 0, 0)
; template <bool ROWSS, class AL, class EPI>
; DI void gemm8(unsigned char* smem, const AL& al, const bf16_t* __restrict__ Bt, int K, int m0, int n0, const EPI& epi) {
;     ...
;   for (int t = 0; t < nt; ++t) {
;     if (t + 2 < nt) asm volatile("s_waitcnt vmcnt(8)" ::: "memory");
;     else if (t + 1 < nt) asm volatile("s_waitcnt vmcnt(4)" ::: "memory");
;     else asm volatile("s_waitcnt vmcnt(0)" ::: "memory");
;     __builtin_amdgcn_s_barrier();
;     asm volatile("" ::: "memory");
;     const unsigned char* sa = smem + (t & 3) * 32768 + aoff;
;     const unsigned char* sb = smem + (t & 3) * 32768 + boff;
;     bf16x8 af0, af1, bfr[8];
;     af0 = *(const bf16x8*)(sa);
; #pragma unroll
;     for (int n = 0; n < 8; ++n) bfr[n] = *(const bf16x8*)(sb + n * 1024);
;     af1 = *(const bf16x8*)(sa + 1024);
;     __builtin_amdgcn_sched_barrier(0);
;     if (t + 3 < nt) G8_ISSUE(t + 3);
;     __builtin_amdgcn_sched_barrier(0);
; #pragma unroll
;     for (int n = 0; n < 8; ++n) acc[0][n] = MFMA16(bfr[n], af0, acc[0][n]);
; #pragma unroll
;     for (int n = 0; n < 8; ++n) acc[1][n] = MFMA16(bfr[n], af1, acc[1][n]);
;     __builtin_amdgcn_sched_barrier(0);
;     af0 = *(const bf16x8*)(sa + 2048); af1 = *(const bf16x8*)(sa + 3072);
;     __builtin_amdgcn_sched_barrier(0);
; #pragma unroll
;     for (int n = 0; n < 8; ++n) acc[2][n] = MFMA16(bfr[n], af0, acc[2][n]);
; #pragma unroll
;     for (int n = 0; n < 8; ++n) acc[3][n] = MFMA16(bfr[n], af1, acc[3][n]);
;     __builtin_amdgcn_sched_barrier(0);
;     if (ROWSS) {
;       float v[8];
;       unpack8(*(const uint4*)(smem + (t & 3) * 32768 + ptid * 16), v);
; #pragma unroll
;       for (int j = 0; j < 8; ++j) ss0 += v[j] * v[j];
;       unpack8(*(const uint4*)(smem + (t & 3) * 32768 + ptid * 16 + 8192), v);
; #pragma unroll
;       for (int j = 0; j < 8; ++j) ss1 += v[j] * v[j];
;     }
;   }
	v_mfma_f32_16x16x32_bf16 v[116:119], v[162:165], v[112:115], v[116:119]
	v_mfma_f32_16x16x32_bf16 v[120:123], v[166:169], v[112:115], v[120:123]
	v_mfma_f32_16x16x32_bf16 v[124:127], v[170:173], v[112:115], v[124:127]
	v_mfma_f32_16x16x32_bf16 v[138:141], v[174:177], v[112:115], v[138:141]
	v_mfma_f32_16x16x32_bf16 v[108:111], v[190:193], v[112:115], v[108:111]
	s_waitcnt lgkmcnt(0)
	v_mfma_f32_16x16x32_bf16 v[14:17], v[162:165], v[194:197], v[14:17]
	v_mfma_f32_16x16x32_bf16 v[18:21], v[166:169], v[194:197], v[18:21]
	v_mfma_f32_16x16x32_bf16 v[22:25], v[170:173], v[194:197], v[22:25]
	v_mfma_f32_16x16x32_bf16 v[26:29], v[174:177], v[194:197], v[26:29]
	v_mfma_f32_16x16x32_bf16 v[30:33], v[178:181], v[194:197], v[30:33]
	v_mfma_f32_16x16x32_bf16 v[34:37], v[182:185], v[194:197], v[34:37]
	v_mfma_f32_16x16x32_bf16 v[38:41], v[186:189], v[194:197], v[38:41]
	v_mfma_f32_16x16x32_bf16 v[42:45], v[190:193], v[194:197], v[42:45]
	v_mfma_f32_16x16x32_bf16 v[150:153], v[178:181], v[112:115], v[150:153]
	v_mfma_f32_16x16x32_bf16 v[154:157], v[182:185], v[112:115], v[154:157]
	v_mfma_f32_16x16x32_bf16 v[158:161], v[186:189], v[112:115], v[158:161]
	ds_read_b128 v[112:115], v7
	s_waitcnt lgkmcnt(0)
	v_lshlrev_b32_e32 v13, 16, v112
	v_and_b32_e32 v67, 0xffff0000, v112
	v_lshlrev_b32_e32 v128, 16, v113
	v_and_b32_e32 v129, 0xffff0000, v113
	v_lshlrev_b32_e32 v142, 16, v114
	v_and_b32_e32 v143, 0xffff0000, v114
	v_lshlrev_b32_e32 v149, 16, v115
	v_and_b32_e32 v162, 0xffff0000, v115
	ds_read_b128 v[112:115], v7 offset:8192
	v_fmac_f32_e32 v135, v13, v13
	v_fmac_f32_e32 v135, v67, v67
	v_fmac_f32_e32 v135, v128, v128
	v_fmac_f32_e32 v135, v129, v129
	s_waitcnt lgkmcnt(0)
	v_lshlrev_b32_e32 v163, 16, v112
	v_and_b32_e32 v112, 0xffff0000, v112
	v_fmac_f32_e32 v136, v163, v163
	v_lshlrev_b32_e32 v164, 16, v113
	v_fmac_f32_e32 v136, v112, v112
	v_and_b32_e32 v113, 0xffff0000, v113
	v_fmac_f32_e32 v136, v164, v164
	v_lshlrev_b32_e32 v165, 16, v114
	v_fmac_f32_e32 v136, v113, v113
	v_and_b32_e32 v114, 0xffff0000, v114
	v_fmac_f32_e32 v136, v165, v165
	v_fmac_f32_e32 v135, v142, v142
	v_lshlrev_b32_e32 v166, 16, v115
	v_fmac_f32_e32 v136, v114, v114
	v_fmac_f32_e32 v135, v143, v143
	v_and_b32_e32 v115, 0xffff0000, v115
	v_fmac_f32_e32 v136, v166, v166
	v_fmac_f32_e32 v135, v149, v149
	s_waitcnt vmcnt(8)
	s_barrier
	v_fmac_f32_e32 v136, v115, v115
	v_fmac_f32_e32 v135, v162, v162
	ds_read_b128 v[112:115], v6 offset:32768
	ds_read_b128 v[162:165], v8 offset:49152
	ds_read_b128 v[166:169], v8 offset:50176
	ds_read_b128 v[170:173], v8 offset:51200
	ds_read_b128 v[174:177], v8 offset:52224
	ds_read_b128 v[178:181], v8 offset:53248
	ds_read_b128 v[182:185], v8 offset:54272
	ds_read_b128 v[186:189], v8 offset:55296
	ds_read_b128 v[190:193], v8 offset:56320
	ds_read_b128 v[194:197], v6 offset:33792
	s_waitcnt lgkmcnt(0)
	v_mfma_f32_16x16x32_bf16 v[2:5], v[162:165], v[112:115], v[2:5]
	v_mfma_f32_16x16x32_bf16 v[54:57], v[166:169], v[112:115], v[54:57]
	v_mfma_f32_16x16x32_bf16 v[58:61], v[170:173], v[112:115], v[58:61]
	v_mfma_f32_16x16x32_bf16 v[62:65], v[174:177], v[112:115], v[62:65]
	v_mfma_f32_16x16x32_bf16 v[68:71], v[178:181], v[112:115], v[68:71]
	v_mfma_f32_16x16x32_bf16 v[72:75], v[182:185], v[112:115], v[72:75]
	v_mfma_f32_16x16x32_bf16 v[76:79], v[186:189], v[112:115], v[76:79]
	v_mfma_f32_16x16x32_bf16 v[46:49], v[190:193], v[112:115], v[46:49]
	ds_read_b128 v[112:115], v6 offset:34816
	v_mfma_f32_16x16x32_bf16 v[80:83], v[162:165], v[194:197], v[80:83]
	v_mfma_f32_16x16x32_bf16 v[84:87], v[166:169], v[194:197], v[84:87]
	v_mfma_f32_16x16x32_bf16 v[88:91], v[170:173], v[194:197], v[88:91]
	v_mfma_f32_16x16x32_bf16 v[92:95], v[174:177], v[194:197], v[92:95]
	v_mfma_f32_16x16x32_bf16 v[96:99], v[178:181], v[194:197], v[96:99]
	v_mfma_f32_16x16x32_bf16 v[100:103], v[182:185], v[194:197], v[100:103]
	v_mfma_f32_16x16x32_bf16 v[104:107], v[186:189], v[194:197], v[104:107]
	v_mfma_f32_16x16x32_bf16 v[50:53], v[190:193], v[194:197], v[50:53]
	ds_read_b128 v[194:197], v6 offset:35840
	s_waitcnt lgkmcnt(1)
	v_mfma_f32_16x16x32_bf16 v[116:119], v[162:165], v[112:115], v[116:119]
	v_mfma_f32_16x16x32_bf16 v[120:123], v[166:169], v[112:115], v[120:123]
	v_mfma_f32_16x16x32_bf16 v[124:127], v[170:173], v[112:115], v[124:127]
	v_mfma_f32_16x16x32_bf16 v[138:141], v[174:177], v[112:115], v[138:141]
	v_mfma_f32_16x16x32_bf16 v[108:111], v[190:193], v[112:115], v[108:111]
	s_waitcnt lgkmcnt(0)
	v_mfma_f32_16x16x32_bf16 v[14:17], v[162:165], v[194:197], v[14:17]
	v_mfma_f32_16x16x32_bf16 v[18:21], v[166:169], v[194:197], v[18:21]
	v_mfma_f32_16x16x32_bf16 v[22:25], v[170:173], v[194:197], v[22:25]
	v_mfma_f32_16x16x32_bf16 v[26:29], v[174:177], v[194:197], v[26:29]
	v_mfma_f32_16x16x32_bf16 v[30:33], v[178:181], v[194:197], v[30:33]
	v_mfma_f32_16x16x32_bf16 v[34:37], v[182:185], v[194:197], v[34:37]
	v_mfma_f32_16x16x32_bf16 v[38:41], v[186:189], v[194:197], v[38:41]
	v_mfma_f32_16x16x32_bf16 v[42:45], v[190:193], v[194:197], v[42:45]
	v_mfma_f32_16x16x32_bf16 v[150:153], v[178:181], v[112:115], v[150:153]
	v_mfma_f32_16x16x32_bf16 v[154:157], v[182:185], v[112:115], v[154:157]
	v_mfma_f32_16x16x32_bf16 v[158:161], v[186:189], v[112:115], v[158:161]
	ds_read_b128 v[112:115], v7 offset:32768
	s_waitcnt lgkmcnt(0)
	v_lshlrev_b32_e32 v6, 16, v112
	v_and_b32_e32 v8, 0xffff0000, v112
	v_lshlrev_b32_e32 v13, 16, v113
	v_and_b32_e32 v67, 0xffff0000, v113
	v_lshlrev_b32_e32 v128, 16, v114
	v_and_b32_e32 v129, 0xffff0000, v114
	v_lshlrev_b32_e32 v142, 16, v115
	v_and_b32_e32 v143, 0xffff0000, v115
	ds_read_b128 v[112:115], v7 offset:40960
	s_waitcnt vmcnt(4)
	s_barrier
; DI void unpack8(uint4 u, float* v) { v[0] = bflo(u.x); v[1] = bfhi(u.x); v[2] = bflo(u.y); v[3] = bfhi(u.y); v[4] = bflo(u.z); v[5] = bfhi(u.z); v[6] = bflo(u.w); v[7] = bfhi(u.w); }
; #define MFMA16(a, b, c) __builtin_amdgcn_mfma_f32_16x16x32_bf16((a), (b), (c), 0, 0, 0)
; template <bool ROWSS, class AL, class EPI>
; DI void gemm8(unsigned char* smem, const AL& al, const bf16_t* __restrict__ Bt, int K, int m0, int n0, const EPI& epi) {
;     ...
;   for (int t = 0; t < nt; ++t) {
;     if (t + 2 < nt) asm volatile("s_waitcnt vmcnt(8)" ::: "memory");
;     else if (t + 1 < nt) asm volatile("s_waitcnt vmcnt(4)" ::: "memory");
;     else asm volatile("s_waitcnt vmcnt(0)" ::: "memory");
;     __builtin_amdgcn_s_barrier();
;     asm volatile("" ::: "memory");
;     const unsigned char* sa = smem + (t & 3) * 32768 + aoff;
;     const unsigned char* sb = smem + (t & 3) * 32768 + boff;
;     bf16x8 af0, af1, bfr[8];
;     af0 = *(const bf16x8*)(sa);
; #pragma unroll
;     for (int n = 0; n < 8; ++n) bfr[n] = *(const bf16x8*)(sb + n * 1024);
;     af1 = *(const bf16x8*)(sa + 1024);
;     __builtin_amdgcn_sched_barrier(0);
;     if (t + 3 < nt) G8_ISSUE(t + 3);
;     __builtin_amdgcn_sched_barrier(0);
; #pragma unroll
;     for (int n = 0; n < 8; ++n) acc[0][n] = MFMA16(bfr[n], af0, acc[0][n]);
; #pragma unroll
;     for (int n = 0; n < 8; ++n) acc[1][n] = MFMA16(bfr[n], af1, acc[1][n]);
;     __builtin_amdgcn_sched_barrier(0);
;     af0 = *(const bf16x8*)(sa + 2048); af1 = *(const bf16x8*)(sa + 3072);
;     __builtin_amdgcn_sched_barrier(0);
; #pragma unroll
;     for (int n = 0; n < 8; ++n) acc[2][n] = MFMA16(bfr[n], af0, acc[2][n]);
; #pragma unroll
;     for (int n = 0; n < 8; ++n) acc[3][n] = MFMA16(bfr[n], af1, acc[3][n]);
;     __builtin_amdgcn_sched_barrier(0);
;     if (ROWSS) {
;       float v[8];
;       unpack8(*(const uint4*)(smem + (t & 3) * 32768 + ptid * 16), v);
; #pragma unroll
;       for (int j = 0; j < 8; ++j) ss0 += v[j] * v[j];
;       unpack8(*(const uint4*)(smem + (t & 3) * 32768 + ptid * 16 + 8192), v);
; #pragma unroll
;       for (int j = 0; j < 8; ++j) ss1 += v[j] * v[j];
;     }
;   }
	v_fmac_f32_e32 v135, v6, v6
	s_waitcnt lgkmcnt(0)
	v_lshlrev_b32_e32 v7, 16, v112
	v_and_b32_e32 v112, 0xffff0000, v112
	v_fmac_f32_e32 v136, v7, v7
	v_lshlrev_b32_e32 v149, 16, v113
	v_fmac_f32_e32 v136, v112, v112
	v_and_b32_e32 v113, 0xffff0000, v113
	v_fmac_f32_e32 v136, v149, v149
	v_lshlrev_b32_e32 v162, 16, v114
	v_fmac_f32_e32 v136, v113, v113
	v_and_b32_e32 v114, 0xffff0000, v114
	v_fmac_f32_e32 v136, v162, v162
	v_lshlrev_b32_e32 v163, 16, v115
	v_fmac_f32_e32 v136, v114, v114
	v_and_b32_e32 v115, 0xffff0000, v115
	v_fmac_f32_e32 v136, v163, v163
	v_fmac_f32_e32 v136, v115, v115
	ds_read_b128 v[112:115], v9
	ds_read_b128 v[162:165], v11 offset:16384
	ds_read_b128 v[166:169], v11 offset:17408
	ds_read_b128 v[170:173], v11 offset:18432
	ds_read_b128 v[174:177], v11 offset:19456
	ds_read_b128 v[178:181], v11 offset:20480
	ds_read_b128 v[182:185], v11 offset:21504
	ds_read_b128 v[186:189], v11 offset:22528
	ds_read_b128 v[190:193], v11 offset:23552
	ds_read_b128 v[194:197], v9 offset:1024
	v_fmac_f32_e32 v135, v8, v8
	v_fmac_f32_e32 v135, v13, v13
	v_fmac_f32_e32 v135, v67, v67
	v_fmac_f32_e32 v135, v128, v128
	v_fmac_f32_e32 v135, v129, v129
	v_fmac_f32_e32 v135, v142, v142
	v_fmac_f32_e32 v135, v143, v143
	s_waitcnt lgkmcnt(0)
	v_mfma_f32_16x16x32_bf16 v[2:5], v[162:165], v[112:115], v[2:5]
	v_mfma_f32_16x16x32_bf16 v[54:57], v[166:169], v[112:115], v[54:57]
	v_mfma_f32_16x16x32_bf16 v[58:61], v[170:173], v[112:115], v[58:61]
	v_mfma_f32_16x16x32_bf16 v[62:65], v[174:177], v[112:115], v[62:65]
	v_mfma_f32_16x16x32_bf16 v[68:71], v[178:181], v[112:115], v[68:71]
	v_mfma_f32_16x16x32_bf16 v[72:75], v[182:185], v[112:115], v[72:75]
	v_mfma_f32_16x16x32_bf16 v[76:79], v[186:189], v[112:115], v[76:79]
	v_mfma_f32_16x16x32_bf16 v[46:49], v[190:193], v[112:115], v[46:49]
	v_mfma_f32_16x16x32_bf16 v[80:83], v[162:165], v[194:197], v[80:83]
	v_mfma_f32_16x16x32_bf16 v[84:87], v[166:169], v[194:197], v[84:87]
	v_mfma_f32_16x16x32_bf16 v[88:91], v[170:173], v[194:197], v[88:91]
	v_mfma_f32_16x16x32_bf16 v[92:95], v[174:177], v[194:197], v[92:95]
	v_mfma_f32_16x16x32_bf16 v[96:99], v[178:181], v[194:197], v[96:99]
	v_mfma_f32_16x16x32_bf16 v[100:103], v[182:185], v[194:197], v[100:103]
	v_mfma_f32_16x16x32_bf16 v[104:107], v[186:189], v[194:197], v[104:107]
	v_mfma_f32_16x16x32_bf16 v[112:115], v[190:193], v[194:197], v[50:53]
	s_nop 2
	ds_read_b128 v[50:53], v9 offset:2048
	ds_read_b128 v[6:9], v9 offset:3072
	s_waitcnt lgkmcnt(0)
	v_mfma_f32_16x16x32_bf16 v[116:119], v[162:165], v[50:53], v[116:119]
	v_mfma_f32_16x16x32_bf16 v[120:123], v[166:169], v[50:53], v[120:123]
	v_mfma_f32_16x16x32_bf16 v[124:127], v[170:173], v[50:53], v[124:127]
	v_mfma_f32_16x16x32_bf16 v[138:141], v[174:177], v[50:53], v[138:141]
	v_mfma_f32_16x16x32_bf16 v[108:111], v[190:193], v[50:53], v[108:111]
	v_mfma_f32_16x16x32_bf16 v[150:153], v[178:181], v[50:53], v[150:153]
	v_mfma_f32_16x16x32_bf16 v[154:157], v[182:185], v[50:53], v[154:157]
	v_mfma_f32_16x16x32_bf16 v[158:161], v[186:189], v[50:53], v[158:161]
	v_mfma_f32_16x16x32_bf16 v[162:165], v[162:165], v[6:9], v[14:17]
	v_mfma_f32_16x16x32_bf16 v[166:169], v[166:169], v[6:9], v[18:21]
	v_mfma_f32_16x16x32_bf16 v[170:173], v[170:173], v[6:9], v[22:25]
	v_mfma_f32_16x16x32_bf16 v[174:177], v[174:177], v[6:9], v[26:29]
	v_mfma_f32_16x16x32_bf16 v[178:181], v[178:181], v[6:9], v[30:33]
	v_mfma_f32_16x16x32_bf16 v[182:185], v[182:185], v[6:9], v[34:37]
	v_mfma_f32_16x16x32_bf16 v[186:189], v[186:189], v[6:9], v[38:41]
	v_mfma_f32_16x16x32_bf16 v[190:193], v[190:193], v[6:9], v[42:45]
	ds_read_b128 v[6:9], v10
	s_waitcnt lgkmcnt(0)
	v_lshlrev_b32_e32 v11, 16, v6
	v_and_b32_e32 v13, 0xffff0000, v6
	v_lshlrev_b32_e32 v14, 16, v7
	v_and_b32_e32 v15, 0xffff0000, v7
	v_lshlrev_b32_e32 v16, 16, v8
	v_and_b32_e32 v17, 0xffff0000, v8
	v_lshlrev_b32_e32 v18, 16, v9
	v_and_b32_e32 v19, 0xffff0000, v9
	ds_read_b128 v[6:9], v10 offset:8192
	s_waitcnt vmcnt(0)
	s_barrier
	ds_read_b128 v[30:33], v66
	ds_read_b128 v[194:197], v12 offset:16384
	ds_read_b128 v[198:201], v12 offset:17408
	ds_read_b128 v[206:209], v12 offset:18432
	ds_read_b128 v[210:213], v12 offset:19456
	ds_read_b128 v[214:217], v12 offset:20480
	ds_read_b128 v[218:221], v12 offset:21504
	ds_read_b128 v[222:225], v12 offset:22528
	ds_read_b128 v[226:229], v12 offset:23552
	ds_read_b128 v[230:233], v66 offset:1024
	s_waitcnt lgkmcnt(0)
	v_lshlrev_b32_e32 v10, 16, v6
	v_and_b32_e32 v6, 0xffff0000, v6
	v_fmac_f32_e32 v136, v10, v10
	v_fmac_f32_e32 v135, v11, v11
	v_lshlrev_b32_e32 v20, 16, v7
	v_fmac_f32_e32 v136, v6, v6
	v_fmac_f32_e32 v135, v13, v13
	v_and_b32_e32 v7, 0xffff0000, v7
	v_fmac_f32_e32 v136, v20, v20
	v_fmac_f32_e32 v135, v14, v14
	v_lshlrev_b32_e32 v21, 16, v8
	v_fmac_f32_e32 v136, v7, v7
	v_fmac_f32_e32 v135, v15, v15
	v_and_b32_e32 v8, 0xffff0000, v8
	v_fmac_f32_e32 v136, v21, v21
	v_fmac_f32_e32 v135, v16, v16
	v_lshlrev_b32_e32 v22, 16, v9
	v_fmac_f32_e32 v136, v8, v8
	v_fmac_f32_e32 v135, v17, v17
	v_and_b32_e32 v9, 0xffff0000, v9
	v_fmac_f32_e32 v136, v22, v22
	v_fmac_f32_e32 v135, v18, v18
	v_fmac_f32_e32 v136, v9, v9
	v_fmac_f32_e32 v135, v19, v19
	v_mfma_f32_16x16x32_bf16 v[2:5], v[194:197], v[30:33], v[2:5]
	v_mfma_f32_16x16x32_bf16 v[6:9], v[198:201], v[30:33], v[54:57]
	v_mfma_f32_16x16x32_bf16 v[10:13], v[206:209], v[30:33], v[58:61]
	v_mfma_f32_16x16x32_bf16 v[14:17], v[210:213], v[30:33], v[62:65]
	v_mfma_f32_16x16x32_bf16 v[18:21], v[214:217], v[30:33], v[68:71]
	v_mfma_f32_16x16x32_bf16 v[22:25], v[218:221], v[30:33], v[72:75]
	v_mfma_f32_16x16x32_bf16 v[26:29], v[222:225], v[30:33], v[76:79]
	v_mfma_f32_16x16x32_bf16 v[30:33], v[226:229], v[30:33], v[46:49]
	v_mfma_f32_16x16x32_bf16 v[34:37], v[194:197], v[230:233], v[80:83]
	v_mfma_f32_16x16x32_bf16 v[38:41], v[198:201], v[230:233], v[84:87]
	v_mfma_f32_16x16x32_bf16 v[42:45], v[206:209], v[230:233], v[88:91]
	v_mfma_f32_16x16x32_bf16 v[46:49], v[210:213], v[230:233], v[92:95]
	v_mfma_f32_16x16x32_bf16 v[50:53], v[214:217], v[230:233], v[96:99]
	v_mfma_f32_16x16x32_bf16 v[54:57], v[218:221], v[230:233], v[100:103]
	v_mfma_f32_16x16x32_bf16 v[58:61], v[222:225], v[230:233], v[104:107]
	v_mfma_f32_16x16x32_bf16 v[62:65], v[226:229], v[230:233], v[112:115]
	ds_read_b128 v[94:97], v66 offset:2048
	ds_read_b128 v[230:233], v66 offset:3072
	s_waitcnt lgkmcnt(0)
; DI void unpack8(uint4 u, float* v) { v[0] = bflo(u.x); v[1] = bfhi(u.x); v[2] = bflo(u.y); v[3] = bfhi(u.y); v[4] = bflo(u.z); v[5] = bfhi(u.z); v[6] = bflo(u.w); v[7] = bfhi(u.w); }
; #define MFMA16(a, b, c) __builtin_amdgcn_mfma_f32_16x16x32_bf16((a), (b), (c), 0, 0, 0)
; template <bool ROWSS, class AL, class EPI>
; DI void gemm8(unsigned char* smem, const AL& al, const bf16_t* __restrict__ Bt, int K, int m0, int n0, const EPI& epi) {
;     ...
;     for (int n = 0; n < 8; ++n) acc[3][n] = MFMA16(bfr[n], af1, acc[3][n]);
;     __builtin_amdgcn_sched_barrier(0);
;     if (ROWSS) {
;       float v[8];
;       unpack8(*(const uint4*)(smem + (t & 3) * 32768 + ptid * 16), v);
; #pragma unroll
;       for (int j = 0; j < 8; ++j) ss0 += v[j] * v[j];
;       unpack8(*(const uint4*)(smem + (t & 3) * 32768 + ptid * 16 + 8192), v);
; #pragma unroll
;       for (int j = 0; j < 8; ++j) ss1 += v[j] * v[j];
;     }
;     ...
;   if (ROWSS) {
;     ss0 += __shfl_xor(ss0, 1); ss0 += __shfl_xor(ss0, 2);
;     ss1 += __shfl_xor(ss1, 1); ss1 += __shfl_xor(ss1, 2);
;     if ((lane & 3) == 0) { rowss[Rb] = ss0; rowss[Rb + 128] = ss1; }
;   }
;   const int vb = ptid >> 8, vtid = ptid & 255;
; #pragma unroll
;   for (int p = 0; p < 2; ++p) {
;     if ((wm >> 1) == p) {
;       float* tw = (float*)(smem + wn * (128 * TLD * 4));
; #pragma unroll
;       for (int m = 0; m < 4; ++m)
; #pragma unroll
;         for (int n = 0; n < 8; ++n) *(f32x4*)(tw + ((wm & 1) * 64 + m * 16 + fr) * TLD + n * 16 + fq * 4) = acc[m][n];
	v_mfma_f32_16x16x32_bf16 v[66:69], v[194:197], v[94:97], v[116:119]
	v_mfma_f32_16x16x32_bf16 v[70:73], v[198:201], v[94:97], v[120:123]
	v_mfma_f32_16x16x32_bf16 v[74:77], v[206:209], v[94:97], v[124:127]
	v_mfma_f32_16x16x32_bf16 v[78:81], v[210:213], v[94:97], v[138:141]
	v_mfma_f32_16x16x32_bf16 v[82:85], v[214:217], v[94:97], v[150:153]
	v_mfma_f32_16x16x32_bf16 v[86:89], v[218:221], v[94:97], v[154:157]
	v_mfma_f32_16x16x32_bf16 v[90:93], v[222:225], v[94:97], v[158:161]
	v_mfma_f32_16x16x32_bf16 v[94:97], v[226:229], v[94:97], v[108:111]
	v_mfma_f32_16x16x32_bf16 v[98:101], v[194:197], v[230:233], v[162:165]
	v_mfma_f32_16x16x32_bf16 v[102:105], v[198:201], v[230:233], v[166:169]
	v_mfma_f32_16x16x32_bf16 v[106:109], v[206:209], v[230:233], v[170:173]
	v_mfma_f32_16x16x32_bf16 v[110:113], v[210:213], v[230:233], v[174:177]
	v_mfma_f32_16x16x32_bf16 v[114:117], v[214:217], v[230:233], v[178:181]
	v_mfma_f32_16x16x32_bf16 v[118:121], v[218:221], v[230:233], v[182:185]
	v_mfma_f32_16x16x32_bf16 v[122:125], v[222:225], v[230:233], v[186:189]
	v_mfma_f32_16x16x32_bf16 v[126:129], v[226:229], v[230:233], v[190:193]
	ds_read_b128 v[138:141], v137
	v_cmp_lt_i32_e32 vcc, v146, v147
	s_waitcnt lgkmcnt(0)
	v_lshlrev_b32_e32 v142, 16, v138
	v_and_b32_e32 v143, 0xffff0000, v138
	v_lshlrev_b32_e32 v149, 16, v139
	v_and_b32_e32 v150, 0xffff0000, v139
	v_lshlrev_b32_e32 v151, 16, v140
	v_and_b32_e32 v152, 0xffff0000, v140
	v_lshlrev_b32_e32 v153, 16, v141
	v_and_b32_e32 v154, 0xffff0000, v141
	ds_read_b128 v[138:141], v137 offset:8192
	v_fmac_f32_e32 v135, v142, v142
	v_fmac_f32_e32 v135, v143, v143
	v_fmac_f32_e32 v135, v149, v149
	v_fmac_f32_e32 v135, v150, v150
	s_waitcnt lgkmcnt(0)
	v_lshlrev_b32_e32 v137, 16, v138
	v_and_b32_e32 v138, 0xffff0000, v138
	v_fmac_f32_e32 v136, v137, v137
	v_lshlrev_b32_e32 v155, 16, v139
	v_fmac_f32_e32 v136, v138, v138
	v_and_b32_e32 v139, 0xffff0000, v139
	v_fmac_f32_e32 v136, v155, v155
	v_lshlrev_b32_e32 v156, 16, v140
	v_fmac_f32_e32 v136, v139, v139
	v_fmac_f32_e32 v135, v151, v151
	v_and_b32_e32 v140, 0xffff0000, v140
	v_fmac_f32_e32 v136, v156, v156
	v_fmac_f32_e32 v135, v152, v152
	v_lshlrev_b32_e32 v157, 16, v141
	v_fmac_f32_e32 v136, v140, v140
	v_fmac_f32_e32 v135, v153, v153
	v_cndmask_b32_e32 v137, v145, v146, vcc
	v_and_b32_e32 v141, 0xffff0000, v141
	v_fmac_f32_e32 v136, v157, v157
	v_fmac_f32_e32 v135, v154, v154
	v_lshlrev_b32_e32 v138, 2, v137
	v_fmac_f32_e32 v136, v141, v141
	ds_bpermute_b32 v137, v138, v135
	ds_bpermute_b32 v138, v138, v136
	v_cmp_lt_i32_e32 vcc, v148, v147
	s_waitcnt vmcnt(0) lgkmcnt(0)
	s_barrier
	v_add_f32_e32 v135, v135, v137
	v_cndmask_b32_e32 v137, v145, v148, vcc
	v_lshlrev_b32_e32 v139, 2, v137
	v_add_f32_e32 v136, v136, v138
	ds_bpermute_b32 v137, v139, v135
	ds_bpermute_b32 v138, v139, v136
	v_and_b32_e32 v139, 3, v130
	v_cmp_eq_u32_e32 vcc, 0, v139
	s_waitcnt lgkmcnt(0)
	s_and_saveexec_b64 s[0:1], vcc
	v_lshl_add_u32 v134, v134, 2, 0
	v_add_u32_e32 v134, 0x21000, v134
	v_add_f32_e32 v135, v135, v137
	v_add_f32_e32 v136, v136, v138
	ds_write2st64_b32 v134, v135, v136 offset1:2
	s_or_b64 exec, exec, s[0:1]
	s_mul_i32 s33, s33, 0x10800
	s_add_i32 s0, s33, 0
	s_lshl_b32 s1, s26, 6
	v_and_or_b32 v134, s1, 64, v131
	v_add_u32_e32 v132, s0, v132
	s_cmpk_gt_u32 s8, 0xff
	v_mad_u32_u24 v153, v134, s15, v132
	s_cbranch_scc1 .LBB0_383
	ds_write_b128 v153, v[2:5]
	ds_write_b128 v153, v[6:9] offset:64
	ds_write_b128 v153, v[10:13] offset:128
	ds_write_b128 v153, v[14:17] offset:192
	ds_write_b128 v153, v[18:21] offset:256
	ds_write_b128 v153, v[22:25] offset:320
	ds_write_b128 v153, v[26:29] offset:384
	ds_write_b128 v153, v[30:33] offset:448
	ds_write_b128 v153, v[34:37] offset:8448
	ds_write_b128 v153, v[38:41] offset:8512
	ds_write_b128 v153, v[42:45] offset:8576
	ds_write_b128 v153, v[46:49] offset:8640
	ds_write_b128 v153, v[50:53] offset:8704
	ds_write_b128 v153, v[54:57] offset:8768
	ds_write_b128 v153, v[58:61] offset:8832
	ds_write_b128 v153, v[62:65] offset:8896
	ds_write_b128 v153, v[66:69] offset:16896
	ds_write_b128 v153, v[70:73] offset:16960
	ds_write_b128 v153, v[74:77] offset:17024
	ds_write_b128 v153, v[78:81] offset:17088
	ds_write_b128 v153, v[82:85] offset:17152
	ds_write_b128 v153, v[86:89] offset:17216
	ds_write_b128 v153, v[90:93] offset:17280
	ds_write_b128 v153, v[94:97] offset:17344
	ds_write_b128 v153, v[98:101] offset:25344
	ds_write_b128 v153, v[102:105] offset:25408
	ds_write_b128 v153, v[106:109] offset:25472
	ds_write_b128 v153, v[110:113] offset:25536
	ds_write_b128 v153, v[114:117] offset:25600
	ds_write_b128 v153, v[118:121] offset:25664
	ds_write_b128 v153, v[122:125] offset:25728
	ds_write_b128 v153, v[126:129] offset:25792

; DI int PTID() { int t = threadIdx.x; asm volatile("" : "+v"(t)); return t; }
; template <bool ROWSS, class AL, class EPI>
; DI void gemm8(unsigned char* smem, const AL& al, const bf16_t* __restrict__ Bt, int K, int m0, int n0, const EPI& epi) {
;   const int ptid = PTID(), lane = ptid & 63, w = __builtin_amdgcn_readfirstlane(ptid >> 6), wm = w >> 1, wn = w & 1, fr = lane & 15, fq = lane >> 4;
;   f32x4 acc[4][8];
; #pragma unroll
;   for (int a = 0; a < 4; ++a)
; #pragma unroll
;     for (int b = 0; b < 8; ++b) acc[a][b] = (f32x4){0.f, 0.f, 0.f, 0.f};
;   const int sb_ = lane * 16, swz_ = sb_ ^ (((sb_ >> 9) & 1) << 5);
;   const int Rb = w * 16 + (swz_ >> 6), C0 = (swz_ & 63) >> 1;
;   const bf16_t* bp0 = Bt + (size_t)(n0 + Rb) * K + C0; const bf16_t* bp1 = bp0 + (size_t)128 * K;
;   float ss0 = 0.f, ss1 = 0.f;
;   const int nt = K >> 5;
;   const int frag = (fr * 64 + fq * 16) ^ (((fr >> 3) & 1) << 5);
;   const int aoff = wm * 4096 + frag, boff = 16384 + wn * 8192 + frag;
;     ...
;   if constexpr (ROWSS) {
;   G8_ISSUE(0); G8_ISSUE(1); G8_ISSUE(2);
;   for (int t = 0; t < nt; ++t) {
;     if (t + 2 < nt) asm volatile("s_waitcnt vmcnt(8)" ::: "memory");
;     else if (t + 1 < nt) asm volatile("s_waitcnt vmcnt(4)" ::: "memory");
;     else asm volatile("s_waitcnt vmcnt(0)" ::: "memory");
;     __builtin_amdgcn_s_barrier();
;     asm volatile("" ::: "memory");
;     const unsigned char* sa = smem + (t & 3) * 32768 + aoff;
;     const unsigned char* sb = smem + (t & 3) * 32768 + boff;
;     bf16x8 af0, af1, bfr[8];
;     af0 = *(const bf16x8*)(sa);
; #pragma unroll
;     for (int n = 0; n < 8; ++n) bfr[n] = *(const bf16x8*)(sb + n * 1024);
;     af1 = *(const bf16x8*)(sa + 1024);
;     __builtin_amdgcn_sched_barrier(0);
;     if (t + 3 < nt) G8_ISSUE(t + 3);
; DI void run_phase(unsigned char* smem_in, const Params& P, int ph) {
;     ...
;       for (int t = pbid; t < 128 * 3; t += pnb) gemm8<true>(psmem, a, Bt, 384, (t / 3) * 256, (t % 3) * 256, e);
.LBB0_1263:
	s_mul_hi_i32 s2, s75, 0x55555556
	s_lshr_b32 s3, s2, 31
	s_add_i32 s2, s2, s3
	v_mov_b32_e32 v132, v204
	s_lshl_b32 s8, s2, 8
	s_mul_i32 s2, s2, 3
	s_sub_i32 s2, s75, s2
	v_readfirstlane_b32 s76, v132
	s_ashr_i32 s5, s76, 6
	v_bfe_u32 v3, v132, 2, 4
	s_lshl_b32 s4, s2, 8
	v_and_b32_e32 v2, 32, v132
	v_lshl_or_b32 v134, s5, 4, v3
	v_lshlrev_b32_e32 v15, 4, v132
	v_bitop3_b32 v144, v15, v2, 48 bitop3:0x6c
	v_add_u32_e32 v2, s4, v134
	v_mad_i64_i32 v[2:3], s[2:3], v2, s11, v[142:143]
	v_lshl_add_u64 v[2:3], v[2:3], 0, v[144:145]
	s_mov_b64 s[2:3], 0x18000
	s_lshl_b32 s30, s5, 10
	v_add_u32_e32 v6, s8, v134
	v_lshl_add_u64 v[8:9], v[2:3], 0, s[2:3]
	s_add_i32 s77, s30, 0
	v_mad_i64_i32 v[4:5], s[2:3], v6, s11, v[146:147]
	v_add_u32_e32 v6, 0x80, v6
	v_lshl_add_u64 v[4:5], v[4:5], 0, v[144:145]
	s_mov_b32 m0, s77
	v_mad_i64_i32 v[6:7], s[2:3], v6, s11, v[146:147]
	s_add_i32 s79, s77, 0x2000
	global_load_lds_dwordx4 v[4:5], off
	v_lshl_add_u64 v[6:7], v[6:7], 0, v[144:145]
	s_mov_b32 m0, s79
	s_add_i32 s80, s77, 0x4000
	global_load_lds_dwordx4 v[6:7], off
	s_mov_b32 m0, s80
	s_add_i32 s78, s77, 0x6000
	global_load_lds_dwordx4 v[2:3], off
	s_mov_b32 m0, s78
	s_add_i32 s66, s77, 0x8000
	global_load_lds_dwordx4 v[8:9], off
	v_lshl_add_u64 v[8:9], v[4:5], 0, 64
	s_mov_b32 m0, s66
	s_add_i32 s67, s77, 0xa000
	global_load_lds_dwordx4 v[8:9], off
	v_lshl_add_u64 v[8:9], v[6:7], 0, 64
	s_mov_b32 m0, s67
	s_add_i32 s68, s77, 0xc000
	global_load_lds_dwordx4 v[8:9], off
	v_lshl_add_u64 v[8:9], v[2:3], 0, 64
	s_mov_b32 m0, s68
	s_mov_b64 s[2:3], 0x18040
	s_add_i32 s69, s77, 0xe000
	global_load_lds_dwordx4 v[8:9], off
	v_lshl_add_u64 v[8:9], v[2:3], 0, s[2:3]
	s_mov_b32 m0, s69
	s_add_i32 s30, s15, s30
	global_load_lds_dwordx4 v[8:9], off
	v_lshl_add_u64 v[8:9], v[4:5], 0, s[18:19]
	s_mov_b32 m0, s30
	s_mov_b64 s[2:3], 0x18080
	global_load_lds_dwordx4 v[8:9], off
	v_lshl_add_u64 v[8:9], v[6:7], 0, s[18:19]
	s_add_i32 m0, s30, 0x2000
	s_and_b32 s33, s5, 1
	global_load_lds_dwordx4 v[8:9], off
	v_lshl_add_u64 v[8:9], v[2:3], 0, s[18:19]
	s_add_i32 m0, s30, 0x4000
	s_ashr_i32 s5, s76, 7
	global_load_lds_dwordx4 v[8:9], off
	v_lshl_add_u64 v[8:9], v[2:3], 0, s[2:3]
	s_add_i32 m0, s30, 0x6000
	v_and_b32_e32 v133, 15, v132
	global_load_lds_dwordx4 v[8:9], off
	v_lshlrev_b32_e32 v9, 2, v132
	s_lshl_b32 s82, s5, 12
	v_lshlrev_b32_e32 v8, 6, v133
	v_and_b32_e32 v135, 48, v132
	v_and_b32_e32 v9, 32, v9
	s_lshl_b32 s81, s33, 13
	v_bitop3_b32 v144, v8, v9, v135 bitop3:0x36
	s_add_i32 s2, s82, 0
	v_add_u32_e32 v8, s2, v144
	s_add_i32 s2, s81, 0
	s_waitcnt vmcnt(8)
	s_barrier
	v_add_u32_e32 v10, s2, v144
	ds_read_b128 v[16:19], v10 offset:16384
	ds_read_b128 v[20:23], v10 offset:17408
	ds_read_b128 v[24:27], v10 offset:18432
	ds_read_b128 v[28:31], v10 offset:19456
	ds_read_b128 v[32:35], v10 offset:20480
	ds_read_b128 v[36:39], v10 offset:21504
	ds_read_b128 v[40:43], v10 offset:22528
	ds_read_b128 v[44:47], v10 offset:23552
	ds_read_b128 v[48:51], v8
	ds_read_b128 v[52:55], v8 offset:1024
	s_add_i32 s2, s77, 0x18000
	v_lshl_add_u64 v[12:13], v[4:5], 0, s[20:21]
	s_mov_b32 m0, s2
	s_add_i32 s3, s77, 0x1a000
	global_load_lds_dwordx4 v[12:13], off
	v_lshl_add_u64 v[12:13], v[6:7], 0, s[20:21]
	s_mov_b32 m0, s3
	s_add_i32 s64, s77, 0x1c000
	global_load_lds_dwordx4 v[12:13], off
	v_lshl_add_u64 v[12:13], v[2:3], 0, s[20:21]
	s_mov_b32 m0, s64
	s_mov_b64 s[30:31], 0x180c0
	s_add_i32 s65, s77, 0x1e000
	global_load_lds_dwordx4 v[12:13], off
	v_lshl_add_u64 v[12:13], v[2:3], 0, s[30:31]
	s_mov_b32 m0, s65
	s_nop 0
	global_load_lds_dwordx4 v[12:13], off
	s_waitcnt lgkmcnt(0)
	v_mfma_f32_16x16x32_bf16 v[56:59], v[16:19], v[48:51], 0
	v_mfma_f32_16x16x32_bf16 v[60:63], v[20:23], v[48:51], 0
	v_mfma_f32_16x16x32_bf16 v[64:67], v[24:27], v[48:51], 0
	v_mfma_f32_16x16x32_bf16 v[68:71], v[28:31], v[48:51], 0
	v_mfma_f32_16x16x32_bf16 v[72:75], v[32:35], v[48:51], 0
	v_mfma_f32_16x16x32_bf16 v[76:79], v[36:39], v[48:51], 0
	v_mfma_f32_16x16x32_bf16 v[80:83], v[40:43], v[48:51], 0
	v_mfma_f32_16x16x32_bf16 v[48:51], v[44:47], v[48:51], 0
	v_mfma_f32_16x16x32_bf16 v[84:87], v[16:19], v[52:55], 0
	v_mfma_f32_16x16x32_bf16 v[88:91], v[20:23], v[52:55], 0
	v_mfma_f32_16x16x32_bf16 v[92:95], v[24:27], v[52:55], 0
	v_mfma_f32_16x16x32_bf16 v[96:99], v[28:31], v[52:55], 0
	v_mfma_f32_16x16x32_bf16 v[100:103], v[32:35], v[52:55], 0
	v_mfma_f32_16x16x32_bf16 v[104:107], v[36:39], v[52:55], 0
	v_mfma_f32_16x16x32_bf16 v[108:111], v[40:43], v[52:55], 0
	v_mfma_f32_16x16x32_bf16 v[52:55], v[44:47], v[52:55], 0
	ds_read_b128 v[112:115], v8 offset:2048
	ds_read_b128 v[116:119], v8 offset:3072
	s_waitcnt lgkmcnt(0)
	v_mfma_f32_16x16x32_bf16 v[120:123], v[16:19], v[112:115], 0
	v_mfma_f32_16x16x32_bf16 v[124:127], v[20:23], v[112:115], 0
	v_mfma_f32_16x16x32_bf16 v[128:131], v[24:27], v[112:115], 0
	v_mfma_f32_16x16x32_bf16 v[136:139], v[28:31], v[112:115], 0
	v_mfma_f32_16x16x32_bf16 v[148:151], v[32:35], v[112:115], 0
	v_mfma_f32_16x16x32_bf16 v[152:155], v[36:39], v[112:115], 0
	v_mfma_f32_16x16x32_bf16 v[156:159], v[40:43], v[112:115], 0
	v_mfma_f32_16x16x32_bf16 v[112:115], v[44:47], v[112:115], 0
	v_mfma_f32_16x16x32_bf16 v[16:19], v[16:19], v[116:119], 0
	v_mfma_f32_16x16x32_bf16 v[20:23], v[20:23], v[116:119], 0
	v_mfma_f32_16x16x32_bf16 v[24:27], v[24:27], v[116:119], 0
	v_mfma_f32_16x16x32_bf16 v[28:31], v[28:31], v[116:119], 0
	v_mfma_f32_16x16x32_bf16 v[32:35], v[32:35], v[116:119], 0
	v_mfma_f32_16x16x32_bf16 v[36:39], v[36:39], v[116:119], 0
	v_mfma_f32_16x16x32_bf16 v[40:43], v[40:43], v[116:119], 0
	v_mfma_f32_16x16x32_bf16 v[44:47], v[44:47], v[116:119], 0
	v_add_u32_e32 v9, 0, v15
	ds_read_b128 v[116:119], v9
	ds_read_b128 v[160:163], v9 offset:8192
	s_waitcnt vmcnt(8)
	s_barrier
; DI void unpack8(uint4 u, float* v) { v[0] = bflo(u.x); v[1] = bfhi(u.x); v[2] = bflo(u.y); v[3] = bfhi(u.y); v[4] = bflo(u.z); v[5] = bfhi(u.z); v[6] = bflo(u.w); v[7] = bfhi(u.w); }
; #define MFMA16(a, b, c) __builtin_amdgcn_mfma_f32_16x16x32_bf16((a), (b), (c), 0, 0, 0)
; template <bool ROWSS, class AL, class EPI>
; DI void gemm8(unsigned char* smem, const AL& al, const bf16_t* __restrict__ Bt, int K, int m0, int n0, const EPI& epi) {
;     ...
;   for (int t = 0; t < nt; ++t) {
;     if (t + 2 < nt) asm volatile("s_waitcnt vmcnt(8)" ::: "memory");
;     else if (t + 1 < nt) asm volatile("s_waitcnt vmcnt(4)" ::: "memory");
;     else asm volatile("s_waitcnt vmcnt(0)" ::: "memory");
;     __builtin_amdgcn_s_barrier();
;     asm volatile("" ::: "memory");
;     const unsigned char* sa = smem + (t & 3) * 32768 + aoff;
;     const unsigned char* sb = smem + (t & 3) * 32768 + boff;
;     bf16x8 af0, af1, bfr[8];
;     af0 = *(const bf16x8*)(sa);
; #pragma unroll
;     for (int n = 0; n < 8; ++n) bfr[n] = *(const bf16x8*)(sb + n * 1024);
;     af1 = *(const bf16x8*)(sa + 1024);
;     __builtin_amdgcn_sched_barrier(0);
;     if (t + 3 < nt) G8_ISSUE(t + 3);
;     __builtin_amdgcn_sched_barrier(0);
; #pragma unroll
;     for (int n = 0; n < 8; ++n) acc[0][n] = MFMA16(bfr[n], af0, acc[0][n]);
; #pragma unroll
;     for (int n = 0; n < 8; ++n) acc[1][n] = MFMA16(bfr[n], af1, acc[1][n]);
;     __builtin_amdgcn_sched_barrier(0);
;     af0 = *(const bf16x8*)(sa + 2048); af1 = *(const bf16x8*)(sa + 3072);
;     __builtin_amdgcn_sched_barrier(0);
; #pragma unroll
;     for (int n = 0; n < 8; ++n) acc[2][n] = MFMA16(bfr[n], af0, acc[2][n]);
; #pragma unroll
;     for (int n = 0; n < 8; ++n) acc[3][n] = MFMA16(bfr[n], af1, acc[3][n]);
;     __builtin_amdgcn_sched_barrier(0);
;     if (ROWSS) {
;       float v[8];
;       unpack8(*(const uint4*)(smem + (t & 3) * 32768 + ptid * 16), v);
; #pragma unroll
;       for (int j = 0; j < 8; ++j) ss0 += v[j] * v[j];
;       unpack8(*(const uint4*)(smem + (t & 3) * 32768 + ptid * 16 + 8192), v);
; #pragma unroll
;       for (int j = 0; j < 8; ++j) ss1 += v[j] * v[j];
;     }
;   }
	s_waitcnt lgkmcnt(0)
	v_lshlrev_b32_e32 v12, 16, v116
	v_lshlrev_b32_e32 v13, 16, v160
	v_and_b32_e32 v141, 0xffff0000, v160
	v_and_b32_e32 v140, 0xffff0000, v116
	v_pk_mul_f32 v[12:13], v[12:13], v[12:13]
	v_lshlrev_b32_e32 v171, 16, v161
	v_lshlrev_b32_e32 v170, 16, v117
	v_pk_fma_f32 v[12:13], v[140:141], v[140:141], v[12:13]
	v_and_b32_e32 v161, 0xffff0000, v161
	v_and_b32_e32 v160, 0xffff0000, v117
	v_pk_fma_f32 v[12:13], v[170:171], v[170:171], v[12:13]
	v_lshlrev_b32_e32 v117, 16, v162
	v_lshlrev_b32_e32 v116, 16, v118
	v_pk_fma_f32 v[12:13], v[160:161], v[160:161], v[12:13]
	v_and_b32_e32 v173, 0xffff0000, v162
	v_and_b32_e32 v172, 0xffff0000, v118
	v_pk_fma_f32 v[12:13], v[116:117], v[116:117], v[12:13]
	v_lshlrev_b32_e32 v175, 16, v163
	v_lshlrev_b32_e32 v174, 16, v119
	v_pk_fma_f32 v[12:13], v[172:173], v[172:173], v[12:13]
	v_and_b32_e32 v163, 0xffff0000, v163
	v_and_b32_e32 v162, 0xffff0000, v119
	v_pk_fma_f32 v[12:13], v[174:175], v[174:175], v[12:13]
	s_nop 0
	v_pk_fma_f32 v[12:13], v[162:163], v[162:163], v[12:13]
	ds_read_b128 v[116:119], v8 offset:32768
	ds_read_b128 v[160:163], v10 offset:49152
	ds_read_b128 v[170:173], v10 offset:50176
	ds_read_b128 v[174:177], v10 offset:51200
	ds_read_b128 v[178:181], v10 offset:52224
	ds_read_b128 v[182:185], v10 offset:53248
	ds_read_b128 v[186:189], v10 offset:54272
	ds_read_b128 v[190:193], v10 offset:55296
	ds_read_b128 v[194:197], v10 offset:56320
	ds_read_b128 v[198:201], v8 offset:33792
	s_mov_b32 m0, s77
	v_lshl_add_u64 v[140:141], v[4:5], 0, s[22:23]
	global_load_lds_dwordx4 v[140:141], off
	v_lshl_add_u64 v[140:141], v[6:7], 0, s[22:23]
	s_mov_b32 m0, s79
	s_mov_b64 s[30:31], 0x18100
	global_load_lds_dwordx4 v[140:141], off
	v_lshl_add_u64 v[140:141], v[2:3], 0, s[22:23]
	s_mov_b32 m0, s80
	s_nop 0
	global_load_lds_dwordx4 v[140:141], off
	v_lshl_add_u64 v[140:141], v[2:3], 0, s[30:31]
	s_mov_b32 m0, s78
	s_nop 0
	global_load_lds_dwordx4 v[140:141], off
	s_waitcnt lgkmcnt(0)
	v_mfma_f32_16x16x32_bf16 v[56:59], v[160:163], v[116:119], v[56:59]
	v_mfma_f32_16x16x32_bf16 v[60:63], v[170:173], v[116:119], v[60:63]
	v_mfma_f32_16x16x32_bf16 v[64:67], v[174:177], v[116:119], v[64:67]
	v_mfma_f32_16x16x32_bf16 v[68:71], v[178:181], v[116:119], v[68:71]
	v_mfma_f32_16x16x32_bf16 v[72:75], v[182:185], v[116:119], v[72:75]
	v_mfma_f32_16x16x32_bf16 v[76:79], v[186:189], v[116:119], v[76:79]
	v_mfma_f32_16x16x32_bf16 v[80:83], v[190:193], v[116:119], v[80:83]
	v_mfma_f32_16x16x32_bf16 v[48:51], v[194:197], v[116:119], v[48:51]
	ds_read_b128 v[116:119], v8 offset:34816
	v_mfma_f32_16x16x32_bf16 v[84:87], v[160:163], v[198:201], v[84:87]
	v_mfma_f32_16x16x32_bf16 v[88:91], v[170:173], v[198:201], v[88:91]
	v_mfma_f32_16x16x32_bf16 v[92:95], v[174:177], v[198:201], v[92:95]
	v_mfma_f32_16x16x32_bf16 v[96:99], v[178:181], v[198:201], v[96:99]
	v_mfma_f32_16x16x32_bf16 v[100:103], v[182:185], v[198:201], v[100:103]
	v_mfma_f32_16x16x32_bf16 v[104:107], v[186:189], v[198:201], v[104:107]
	v_mfma_f32_16x16x32_bf16 v[108:111], v[190:193], v[198:201], v[108:111]
	v_mfma_f32_16x16x32_bf16 v[52:55], v[194:197], v[198:201], v[52:55]
	ds_read_b128 v[198:201], v8 offset:35840
	s_waitcnt lgkmcnt(1)
	v_mfma_f32_16x16x32_bf16 v[120:123], v[160:163], v[116:119], v[120:123]
	v_mfma_f32_16x16x32_bf16 v[124:127], v[170:173], v[116:119], v[124:127]
	v_mfma_f32_16x16x32_bf16 v[128:131], v[174:177], v[116:119], v[128:131]
	v_mfma_f32_16x16x32_bf16 v[136:139], v[178:181], v[116:119], v[136:139]
	v_mfma_f32_16x16x32_bf16 v[112:115], v[194:197], v[116:119], v[112:115]
	s_waitcnt lgkmcnt(0)
	v_mfma_f32_16x16x32_bf16 v[16:19], v[160:163], v[198:201], v[16:19]
	v_mfma_f32_16x16x32_bf16 v[20:23], v[170:173], v[198:201], v[20:23]
	v_mfma_f32_16x16x32_bf16 v[24:27], v[174:177], v[198:201], v[24:27]
	v_mfma_f32_16x16x32_bf16 v[28:31], v[178:181], v[198:201], v[28:31]
	v_mfma_f32_16x16x32_bf16 v[32:35], v[182:185], v[198:201], v[32:35]
	v_mfma_f32_16x16x32_bf16 v[36:39], v[186:189], v[198:201], v[36:39]
	v_mfma_f32_16x16x32_bf16 v[40:43], v[190:193], v[198:201], v[40:43]
	v_mfma_f32_16x16x32_bf16 v[44:47], v[194:197], v[198:201], v[44:47]
	v_mfma_f32_16x16x32_bf16 v[148:151], v[182:185], v[116:119], v[148:151]
	v_mfma_f32_16x16x32_bf16 v[152:155], v[186:189], v[116:119], v[152:155]
	v_mfma_f32_16x16x32_bf16 v[156:159], v[190:193], v[116:119], v[156:159]
	ds_read_b128 v[116:119], v9 offset:32768
	ds_read_b128 v[160:163], v9 offset:40960
	s_add_i32 s30, s15, s82
	s_waitcnt vmcnt(8)
	s_barrier
; DI void unpack8(uint4 u, float* v) { v[0] = bflo(u.x); v[1] = bfhi(u.x); v[2] = bflo(u.y); v[3] = bfhi(u.y); v[4] = bflo(u.z); v[5] = bfhi(u.z); v[6] = bflo(u.w); v[7] = bfhi(u.w); }
; #define MFMA16(a, b, c) __builtin_amdgcn_mfma_f32_16x16x32_bf16((a), (b), (c), 0, 0, 0)
; template <bool ROWSS, class AL, class EPI>
; DI void gemm8(unsigned char* smem, const AL& al, const bf16_t* __restrict__ Bt, int K, int m0, int n0, const EPI& epi) {
;     ...
;   for (int t = 0; t < nt; ++t) {
;     if (t + 2 < nt) asm volatile("s_waitcnt vmcnt(8)" ::: "memory");
;     else if (t + 1 < nt) asm volatile("s_waitcnt vmcnt(4)" ::: "memory");
;     else asm volatile("s_waitcnt vmcnt(0)" ::: "memory");
;     __builtin_amdgcn_s_barrier();
;     asm volatile("" ::: "memory");
;     const unsigned char* sa = smem + (t & 3) * 32768 + aoff;
;     const unsigned char* sb = smem + (t & 3) * 32768 + boff;
;     bf16x8 af0, af1, bfr[8];
;     af0 = *(const bf16x8*)(sa);
; #pragma unroll
;     for (int n = 0; n < 8; ++n) bfr[n] = *(const bf16x8*)(sb + n * 1024);
;     af1 = *(const bf16x8*)(sa + 1024);
;     __builtin_amdgcn_sched_barrier(0);
;     if (t + 3 < nt) G8_ISSUE(t + 3);
;     __builtin_amdgcn_sched_barrier(0);
; #pragma unroll
;     for (int n = 0; n < 8; ++n) acc[0][n] = MFMA16(bfr[n], af0, acc[0][n]);
; #pragma unroll
;     for (int n = 0; n < 8; ++n) acc[1][n] = MFMA16(bfr[n], af1, acc[1][n]);
;     __builtin_amdgcn_sched_barrier(0);
;     af0 = *(const bf16x8*)(sa + 2048); af1 = *(const bf16x8*)(sa + 3072);
;     __builtin_amdgcn_sched_barrier(0);
; #pragma unroll
;     for (int n = 0; n < 8; ++n) acc[2][n] = MFMA16(bfr[n], af0, acc[2][n]);
; #pragma unroll
;     for (int n = 0; n < 8; ++n) acc[3][n] = MFMA16(bfr[n], af1, acc[3][n]);
;     __builtin_amdgcn_sched_barrier(0);
;     if (ROWSS) {
;       float v[8];
;       unpack8(*(const uint4*)(smem + (t & 3) * 32768 + ptid * 16), v);
; #pragma unroll
;       for (int j = 0; j < 8; ++j) ss0 += v[j] * v[j];
;       unpack8(*(const uint4*)(smem + (t & 3) * 32768 + ptid * 16 + 8192), v);
; #pragma unroll
;       for (int j = 0; j < 8; ++j) ss1 += v[j] * v[j];
;     }
;   }
	s_waitcnt lgkmcnt(0)
	v_lshlrev_b32_e32 v140, 16, v116
	v_lshlrev_b32_e32 v141, 16, v160
	v_and_b32_e32 v171, 0xffff0000, v160
	v_and_b32_e32 v170, 0xffff0000, v116
	v_pk_fma_f32 v[12:13], v[140:141], v[140:141], v[12:13]
	v_lshlrev_b32_e32 v173, 16, v161
	v_lshlrev_b32_e32 v172, 16, v117
	v_pk_fma_f32 v[12:13], v[170:171], v[170:171], v[12:13]
	v_and_b32_e32 v161, 0xffff0000, v161
	v_and_b32_e32 v160, 0xffff0000, v117
	v_pk_fma_f32 v[12:13], v[172:173], v[172:173], v[12:13]
	v_lshlrev_b32_e32 v117, 16, v162
	v_lshlrev_b32_e32 v116, 16, v118
	v_pk_fma_f32 v[12:13], v[160:161], v[160:161], v[12:13]
	v_and_b32_e32 v175, 0xffff0000, v162
	v_and_b32_e32 v174, 0xffff0000, v118
	v_pk_fma_f32 v[12:13], v[116:117], v[116:117], v[12:13]
	v_lshlrev_b32_e32 v177, 16, v163
	v_lshlrev_b32_e32 v176, 16, v119
	v_pk_fma_f32 v[12:13], v[174:175], v[174:175], v[12:13]
	v_and_b32_e32 v163, 0xffff0000, v163
	v_and_b32_e32 v162, 0xffff0000, v119
	v_pk_fma_f32 v[12:13], v[176:177], v[176:177], v[12:13]
	v_add_u32_e32 v11, s30, v144
	s_add_i32 s30, s15, s81
	v_pk_fma_f32 v[140:141], v[162:163], v[162:163], v[12:13]
	v_add_u32_e32 v14, s30, v144
	ds_read_b128 v[116:119], v11
	ds_read_b128 v[160:163], v14 offset:16384
	ds_read_b128 v[170:173], v14 offset:17408
	ds_read_b128 v[174:177], v14 offset:18432
	ds_read_b128 v[178:181], v14 offset:19456
	ds_read_b128 v[182:185], v14 offset:20480
	ds_read_b128 v[186:189], v14 offset:21504
	ds_read_b128 v[190:193], v14 offset:22528
	ds_read_b128 v[194:197], v14 offset:23552
	ds_read_b128 v[198:201], v11 offset:1024
	s_mov_b32 m0, s66
	v_lshl_add_u64 v[12:13], v[4:5], 0, s[24:25]
	global_load_lds_dwordx4 v[12:13], off
	v_lshl_add_u64 v[12:13], v[6:7], 0, s[24:25]
	s_mov_b32 m0, s67
	s_mov_b64 s[30:31], 0x18140
	global_load_lds_dwordx4 v[12:13], off
	v_lshl_add_u64 v[12:13], v[2:3], 0, s[24:25]
	s_mov_b32 m0, s68
	s_nop 0
	global_load_lds_dwordx4 v[12:13], off
	v_lshl_add_u64 v[12:13], v[2:3], 0, s[30:31]
	s_mov_b32 m0, s69
	s_nop 0
	global_load_lds_dwordx4 v[12:13], off
	s_waitcnt lgkmcnt(0)
	v_mfma_f32_16x16x32_bf16 v[56:59], v[160:163], v[116:119], v[56:59]
	v_mfma_f32_16x16x32_bf16 v[60:63], v[170:173], v[116:119], v[60:63]
	v_mfma_f32_16x16x32_bf16 v[68:71], v[178:181], v[116:119], v[68:71]
	v_mfma_f32_16x16x32_bf16 v[72:75], v[182:185], v[116:119], v[72:75]
	v_mfma_f32_16x16x32_bf16 v[76:79], v[186:189], v[116:119], v[76:79]
	v_mfma_f32_16x16x32_bf16 v[80:83], v[190:193], v[116:119], v[80:83]
	v_mfma_f32_16x16x32_bf16 v[48:51], v[194:197], v[116:119], v[48:51]
	v_mfma_f32_16x16x32_bf16 v[84:87], v[160:163], v[198:201], v[84:87]
	v_mfma_f32_16x16x32_bf16 v[88:91], v[170:173], v[198:201], v[88:91]
	v_mfma_f32_16x16x32_bf16 v[92:95], v[174:177], v[198:201], v[92:95]
	v_mfma_f32_16x16x32_bf16 v[96:99], v[178:181], v[198:201], v[96:99]
	v_mfma_f32_16x16x32_bf16 v[100:103], v[182:185], v[198:201], v[100:103]
	v_mfma_f32_16x16x32_bf16 v[104:107], v[186:189], v[198:201], v[104:107]
	v_mfma_f32_16x16x32_bf16 v[108:111], v[190:193], v[198:201], v[108:111]
	v_mfma_f32_16x16x32_bf16 v[52:55], v[194:197], v[198:201], v[52:55]
	v_mfma_f32_16x16x32_bf16 v[206:209], v[174:177], v[116:119], v[64:67]
	s_nop 2
	ds_read_b128 v[64:67], v11 offset:2048
	ds_read_b128 v[116:119], v11 offset:3072
	s_waitcnt lgkmcnt(0)
	v_mfma_f32_16x16x32_bf16 v[120:123], v[160:163], v[64:67], v[120:123]
	v_mfma_f32_16x16x32_bf16 v[124:127], v[170:173], v[64:67], v[124:127]
	v_mfma_f32_16x16x32_bf16 v[128:131], v[174:177], v[64:67], v[128:131]
	v_mfma_f32_16x16x32_bf16 v[136:139], v[178:181], v[64:67], v[136:139]
	v_mfma_f32_16x16x32_bf16 v[112:115], v[194:197], v[64:67], v[112:115]
	v_mfma_f32_16x16x32_bf16 v[16:19], v[160:163], v[116:119], v[16:19]
	v_mfma_f32_16x16x32_bf16 v[20:23], v[170:173], v[116:119], v[20:23]
	v_mfma_f32_16x16x32_bf16 v[24:27], v[174:177], v[116:119], v[24:27]
	v_mfma_f32_16x16x32_bf16 v[28:31], v[178:181], v[116:119], v[28:31]
	v_mfma_f32_16x16x32_bf16 v[32:35], v[182:185], v[116:119], v[32:35]
	v_mfma_f32_16x16x32_bf16 v[36:39], v[186:189], v[116:119], v[36:39]
	v_mfma_f32_16x16x32_bf16 v[40:43], v[190:193], v[116:119], v[40:43]
	v_mfma_f32_16x16x32_bf16 v[44:47], v[194:197], v[116:119], v[44:47]
	v_mfma_f32_16x16x32_bf16 v[148:151], v[182:185], v[64:67], v[148:151]
	v_mfma_f32_16x16x32_bf16 v[152:155], v[186:189], v[64:67], v[152:155]
	v_mfma_f32_16x16x32_bf16 v[156:159], v[190:193], v[64:67], v[156:159]
	v_add_u32_e32 v13, s15, v15
	ds_read_b128 v[64:67], v13
	ds_read_b128 v[116:119], v13 offset:8192
	s_add_i32 s85, 0, 0x18000
	s_add_i32 s30, s85, s82
	s_waitcnt vmcnt(8)
	s_waitcnt lgkmcnt(0)
	v_lshlrev_b32_e32 v160, 16, v64
	v_lshlrev_b32_e32 v161, 16, v116
	v_and_b32_e32 v163, 0xffff0000, v116
	v_and_b32_e32 v162, 0xffff0000, v64
	v_lshlrev_b32_e32 v170, 16, v65
	v_and_b32_e32 v116, 0xffff0000, v65
	v_lshlrev_b32_e32 v65, 16, v118
	v_lshlrev_b32_e32 v64, 16, v66
	v_and_b32_e32 v173, 0xffff0000, v118
	v_and_b32_e32 v172, 0xffff0000, v66
	v_lshlrev_b32_e32 v174, 16, v67
	v_and_b32_e32 v118, 0xffff0000, v67
	v_pk_fma_f32 v[66:67], v[160:161], v[160:161], v[140:141]
	v_lshlrev_b32_e32 v171, 16, v117
	v_pk_fma_f32 v[66:67], v[162:163], v[162:163], v[66:67]
	v_and_b32_e32 v117, 0xffff0000, v117
	v_pk_fma_f32 v[66:67], v[170:171], v[170:171], v[66:67]
	v_lshlrev_b32_e32 v175, 16, v119
	v_pk_fma_f32 v[66:67], v[116:117], v[116:117], v[66:67]
	v_and_b32_e32 v119, 0xffff0000, v119
	v_pk_fma_f32 v[64:65], v[64:65], v[64:65], v[66:67]
	s_barrier
; DI void unpack8(uint4 u, float* v) { v[0] = bflo(u.x); v[1] = bfhi(u.x); v[2] = bflo(u.y); v[3] = bfhi(u.y); v[4] = bflo(u.z); v[5] = bfhi(u.z); v[6] = bflo(u.w); v[7] = bfhi(u.w); }
; #define MFMA16(a, b, c) __builtin_amdgcn_mfma_f32_16x16x32_bf16((a), (b), (c), 0, 0, 0)
; template <bool ROWSS, class AL, class EPI>
; DI void gemm8(unsigned char* smem, const AL& al, const bf16_t* __restrict__ Bt, int K, int m0, int n0, const EPI& epi) {
;     ...
;   for (int t = 0; t < nt; ++t) {
;     if (t + 2 < nt) asm volatile("s_waitcnt vmcnt(8)" ::: "memory");
;     else if (t + 1 < nt) asm volatile("s_waitcnt vmcnt(4)" ::: "memory");
;     else asm volatile("s_waitcnt vmcnt(0)" ::: "memory");
;     __builtin_amdgcn_s_barrier();
;     asm volatile("" ::: "memory");
;     const unsigned char* sa = smem + (t & 3) * 32768 + aoff;
;     const unsigned char* sb = smem + (t & 3) * 32768 + boff;
;     bf16x8 af0, af1, bfr[8];
;     af0 = *(const bf16x8*)(sa);
; #pragma unroll
;     for (int n = 0; n < 8; ++n) bfr[n] = *(const bf16x8*)(sb + n * 1024);
;     af1 = *(const bf16x8*)(sa + 1024);
;     __builtin_amdgcn_sched_barrier(0);
;     if (t + 3 < nt) G8_ISSUE(t + 3);
;     __builtin_amdgcn_sched_barrier(0);
; #pragma unroll
;     for (int n = 0; n < 8; ++n) acc[0][n] = MFMA16(bfr[n], af0, acc[0][n]);
; #pragma unroll
;     for (int n = 0; n < 8; ++n) acc[1][n] = MFMA16(bfr[n], af1, acc[1][n]);
;     __builtin_amdgcn_sched_barrier(0);
;     af0 = *(const bf16x8*)(sa + 2048); af1 = *(const bf16x8*)(sa + 3072);
;     __builtin_amdgcn_sched_barrier(0);
; #pragma unroll
;     for (int n = 0; n < 8; ++n) acc[2][n] = MFMA16(bfr[n], af0, acc[2][n]);
; #pragma unroll
;     for (int n = 0; n < 8; ++n) acc[3][n] = MFMA16(bfr[n], af1, acc[3][n]);
;     __builtin_amdgcn_sched_barrier(0);
;     if (ROWSS) {
;       float v[8];
;       unpack8(*(const uint4*)(smem + (t & 3) * 32768 + ptid * 16), v);
; #pragma unroll
;       for (int j = 0; j < 8; ++j) ss0 += v[j] * v[j];
;       unpack8(*(const uint4*)(smem + (t & 3) * 32768 + ptid * 16 + 8192), v);
; #pragma unroll
;       for (int j = 0; j < 8; ++j) ss1 += v[j] * v[j];
;     }
;   }
	v_pk_fma_f32 v[64:65], v[172:173], v[172:173], v[64:65]
	v_add_u32_e32 v66, s30, v144
	v_pk_fma_f32 v[64:65], v[174:175], v[174:175], v[64:65]
	s_add_i32 s30, s85, s81
	v_pk_fma_f32 v[64:65], v[118:119], v[118:119], v[64:65]
	v_add_u32_e32 v12, s30, v144
	ds_read_b128 v[116:119], v66
	ds_read_b128 v[160:163], v12 offset:16384
	ds_read_b128 v[170:173], v12 offset:17408
	ds_read_b128 v[174:177], v12 offset:18432
	ds_read_b128 v[178:181], v12 offset:19456
	ds_read_b128 v[182:185], v12 offset:20480
	ds_read_b128 v[186:189], v12 offset:21504
	ds_read_b128 v[190:193], v12 offset:22528
	ds_read_b128 v[194:197], v12 offset:23552
	ds_read_b128 v[198:201], v66 offset:1024
	s_add_i32 s81, s77, 0x10000
	v_lshl_add_u64 v[140:141], v[4:5], 0, s[26:27]
	s_mov_b32 m0, s81
	s_add_i32 s82, s77, 0x12000
	global_load_lds_dwordx4 v[140:141], off
	v_lshl_add_u64 v[140:141], v[6:7], 0, s[26:27]
	s_mov_b32 m0, s82
	s_add_i32 s83, s77, 0x14000
	global_load_lds_dwordx4 v[140:141], off
	v_lshl_add_u64 v[140:141], v[2:3], 0, s[26:27]
	s_mov_b32 m0, s83
	s_mov_b64 s[30:31], 0x18180
	s_add_i32 s84, s77, 0x16000
	global_load_lds_dwordx4 v[140:141], off
	v_lshl_add_u64 v[140:141], v[2:3], 0, s[30:31]
	s_mov_b32 m0, s84
	s_nop 0
	global_load_lds_dwordx4 v[140:141], off
	s_waitcnt lgkmcnt(0)
	v_mfma_f32_16x16x32_bf16 v[56:59], v[160:163], v[116:119], v[56:59]
	v_mfma_f32_16x16x32_bf16 v[60:63], v[170:173], v[116:119], v[60:63]
	v_mfma_f32_16x16x32_bf16 v[68:71], v[178:181], v[116:119], v[68:71]
	v_mfma_f32_16x16x32_bf16 v[72:75], v[182:185], v[116:119], v[72:75]
	v_mfma_f32_16x16x32_bf16 v[76:79], v[186:189], v[116:119], v[76:79]
	v_mfma_f32_16x16x32_bf16 v[80:83], v[190:193], v[116:119], v[80:83]
	v_mfma_f32_16x16x32_bf16 v[48:51], v[194:197], v[116:119], v[48:51]
	v_mfma_f32_16x16x32_bf16 v[84:87], v[160:163], v[198:201], v[84:87]
	v_mfma_f32_16x16x32_bf16 v[88:91], v[170:173], v[198:201], v[88:91]
	v_mfma_f32_16x16x32_bf16 v[92:95], v[174:177], v[198:201], v[92:95]
	v_mfma_f32_16x16x32_bf16 v[96:99], v[178:181], v[198:201], v[96:99]
	v_mfma_f32_16x16x32_bf16 v[100:103], v[182:185], v[198:201], v[100:103]
	v_mfma_f32_16x16x32_bf16 v[104:107], v[186:189], v[198:201], v[104:107]
	v_mfma_f32_16x16x32_bf16 v[108:111], v[190:193], v[198:201], v[108:111]
	v_mfma_f32_16x16x32_bf16 v[52:55], v[194:197], v[198:201], v[52:55]
	v_mfma_f32_16x16x32_bf16 v[206:209], v[174:177], v[116:119], v[206:209]
	ds_read_b128 v[116:119], v66 offset:2048
	ds_read_b128 v[198:201], v66 offset:3072
	s_waitcnt lgkmcnt(0)
	v_mfma_f32_16x16x32_bf16 v[120:123], v[160:163], v[116:119], v[120:123]
	v_mfma_f32_16x16x32_bf16 v[124:127], v[170:173], v[116:119], v[124:127]
	v_mfma_f32_16x16x32_bf16 v[128:131], v[174:177], v[116:119], v[128:131]
	v_mfma_f32_16x16x32_bf16 v[112:115], v[194:197], v[116:119], v[112:115]
	v_mfma_f32_16x16x32_bf16 v[16:19], v[160:163], v[198:201], v[16:19]
	v_mfma_f32_16x16x32_bf16 v[20:23], v[170:173], v[198:201], v[20:23]
	v_mfma_f32_16x16x32_bf16 v[24:27], v[174:177], v[198:201], v[24:27]
	v_mfma_f32_16x16x32_bf16 v[28:31], v[178:181], v[198:201], v[28:31]
	v_mfma_f32_16x16x32_bf16 v[32:35], v[182:185], v[198:201], v[32:35]
	v_mfma_f32_16x16x32_bf16 v[36:39], v[186:189], v[198:201], v[36:39]
	v_mfma_f32_16x16x32_bf16 v[40:43], v[190:193], v[198:201], v[40:43]
	v_mfma_f32_16x16x32_bf16 v[44:47], v[194:197], v[198:201], v[44:47]
	v_mfma_f32_16x16x32_bf16 v[138:141], v[178:181], v[116:119], v[136:139]
	v_mfma_f32_16x16x32_bf16 v[148:151], v[182:185], v[116:119], v[148:151]
	v_mfma_f32_16x16x32_bf16 v[152:155], v[186:189], v[116:119], v[152:155]
	v_mfma_f32_16x16x32_bf16 v[156:159], v[190:193], v[116:119], v[156:159]
	v_add_u32_e32 v136, s85, v15
	ds_read_b128 v[116:119], v136
	ds_read_b128 v[160:163], v136 offset:8192
	s_waitcnt vmcnt(8)
	s_barrier
	s_waitcnt lgkmcnt(0)
	v_lshlrev_b32_e32 v170, 16, v116
	v_lshlrev_b32_e32 v171, 16, v160
	v_and_b32_e32 v173, 0xffff0000, v160
	v_and_b32_e32 v172, 0xffff0000, v116
	v_pk_fma_f32 v[64:65], v[170:171], v[170:171], v[64:65]
	v_lshlrev_b32_e32 v175, 16, v161
	v_lshlrev_b32_e32 v174, 16, v117
	v_pk_fma_f32 v[64:65], v[172:173], v[172:173], v[64:65]
	v_and_b32_e32 v161, 0xffff0000, v161
	v_and_b32_e32 v160, 0xffff0000, v117
	v_pk_fma_f32 v[64:65], v[174:175], v[174:175], v[64:65]
	v_lshlrev_b32_e32 v117, 16, v162
	v_lshlrev_b32_e32 v116, 16, v118
	v_pk_fma_f32 v[64:65], v[160:161], v[160:161], v[64:65]
	v_and_b32_e32 v177, 0xffff0000, v162
	v_and_b32_e32 v176, 0xffff0000, v118
	v_pk_fma_f32 v[64:65], v[116:117], v[116:117], v[64:65]
	v_lshlrev_b32_e32 v179, 16, v163
	v_lshlrev_b32_e32 v178, 16, v119
	v_pk_fma_f32 v[64:65], v[176:177], v[176:177], v[64:65]
	v_and_b32_e32 v163, 0xffff0000, v163
	v_and_b32_e32 v162, 0xffff0000, v119
	v_pk_fma_f32 v[64:65], v[178:179], v[178:179], v[64:65]
	s_nop 0
	v_pk_fma_f32 v[64:65], v[162:163], v[162:163], v[64:65]
	ds_read_b128 v[116:119], v8
	ds_read_b128 v[160:163], v10 offset:16384
	ds_read_b128 v[170:173], v10 offset:17408
	ds_read_b128 v[174:177], v10 offset:18432
	ds_read_b128 v[178:181], v10 offset:19456
	ds_read_b128 v[182:185], v10 offset:20480
	ds_read_b128 v[186:189], v10 offset:21504
	ds_read_b128 v[190:193], v10 offset:22528
	ds_read_b128 v[194:197], v10 offset:23552
	ds_read_b128 v[198:201], v8 offset:1024
	s_mov_b32 m0, s2
	v_lshl_add_u64 v[202:203], v[4:5], 0, s[38:39]
	global_load_lds_dwordx4 v[202:203], off
	v_lshl_add_u64 v[202:203], v[6:7], 0, s[38:39]
	s_mov_b32 m0, s3
	s_mov_b64 s[30:31], 0x181c0
	global_load_lds_dwordx4 v[202:203], off
	v_lshl_add_u64 v[202:203], v[2:3], 0, s[38:39]
	s_mov_b32 m0, s64
	s_nop 0
	global_load_lds_dwordx4 v[202:203], off
	v_lshl_add_u64 v[202:203], v[2:3], 0, s[30:31]
	s_mov_b32 m0, s65
	s_nop 0
	global_load_lds_dwordx4 v[202:203], off
	s_waitcnt lgkmcnt(0)
; DI void unpack8(uint4 u, float* v) { v[0] = bflo(u.x); v[1] = bfhi(u.x); v[2] = bflo(u.y); v[3] = bfhi(u.y); v[4] = bflo(u.z); v[5] = bfhi(u.z); v[6] = bflo(u.w); v[7] = bfhi(u.w); }
; #define MFMA16(a, b, c) __builtin_amdgcn_mfma_f32_16x16x32_bf16((a), (b), (c), 0, 0, 0)
; template <bool ROWSS, class AL, class EPI>
; DI void gemm8(unsigned char* smem, const AL& al, const bf16_t* __restrict__ Bt, int K, int m0, int n0, const EPI& epi) {
;     ...
;   for (int t = 0; t < nt; ++t) {
;     if (t + 2 < nt) asm volatile("s_waitcnt vmcnt(8)" ::: "memory");
;     else if (t + 1 < nt) asm volatile("s_waitcnt vmcnt(4)" ::: "memory");
;     else asm volatile("s_waitcnt vmcnt(0)" ::: "memory");
;     __builtin_amdgcn_s_barrier();
;     asm volatile("" ::: "memory");
;     const unsigned char* sa = smem + (t & 3) * 32768 + aoff;
;     const unsigned char* sb = smem + (t & 3) * 32768 + boff;
;     bf16x8 af0, af1, bfr[8];
;     af0 = *(const bf16x8*)(sa);
; #pragma unroll
;     for (int n = 0; n < 8; ++n) bfr[n] = *(const bf16x8*)(sb + n * 1024);
;     af1 = *(const bf16x8*)(sa + 1024);
;     __builtin_amdgcn_sched_barrier(0);
;     if (t + 3 < nt) G8_ISSUE(t + 3);
;     __builtin_amdgcn_sched_barrier(0);
; #pragma unroll
;     for (int n = 0; n < 8; ++n) acc[0][n] = MFMA16(bfr[n], af0, acc[0][n]);
; #pragma unroll
;     for (int n = 0; n < 8; ++n) acc[1][n] = MFMA16(bfr[n], af1, acc[1][n]);
;     __builtin_amdgcn_sched_barrier(0);
;     af0 = *(const bf16x8*)(sa + 2048); af1 = *(const bf16x8*)(sa + 3072);
;     __builtin_amdgcn_sched_barrier(0);
; #pragma unroll
;     for (int n = 0; n < 8; ++n) acc[2][n] = MFMA16(bfr[n], af0, acc[2][n]);
; #pragma unroll
;     for (int n = 0; n < 8; ++n) acc[3][n] = MFMA16(bfr[n], af1, acc[3][n]);
;     __builtin_amdgcn_sched_barrier(0);
;     if (ROWSS) {
;       float v[8];
;       unpack8(*(const uint4*)(smem + (t & 3) * 32768 + ptid * 16), v);
; #pragma unroll
;       for (int j = 0; j < 8; ++j) ss0 += v[j] * v[j];
;       unpack8(*(const uint4*)(smem + (t & 3) * 32768 + ptid * 16 + 8192), v);
; #pragma unroll
;       for (int j = 0; j < 8; ++j) ss1 += v[j] * v[j];
;     }
;   }
	v_mfma_f32_16x16x32_bf16 v[56:59], v[160:163], v[116:119], v[56:59]
	v_mfma_f32_16x16x32_bf16 v[60:63], v[170:173], v[116:119], v[60:63]
	v_mfma_f32_16x16x32_bf16 v[68:71], v[178:181], v[116:119], v[68:71]
	v_mfma_f32_16x16x32_bf16 v[72:75], v[182:185], v[116:119], v[72:75]
	v_mfma_f32_16x16x32_bf16 v[76:79], v[186:189], v[116:119], v[76:79]
	v_mfma_f32_16x16x32_bf16 v[80:83], v[190:193], v[116:119], v[80:83]
	v_mfma_f32_16x16x32_bf16 v[48:51], v[194:197], v[116:119], v[48:51]
	v_mfma_f32_16x16x32_bf16 v[84:87], v[160:163], v[198:201], v[84:87]
	v_mfma_f32_16x16x32_bf16 v[88:91], v[170:173], v[198:201], v[88:91]
	v_mfma_f32_16x16x32_bf16 v[92:95], v[174:177], v[198:201], v[92:95]
	v_mfma_f32_16x16x32_bf16 v[96:99], v[178:181], v[198:201], v[96:99]
	v_mfma_f32_16x16x32_bf16 v[100:103], v[182:185], v[198:201], v[100:103]
	v_mfma_f32_16x16x32_bf16 v[104:107], v[186:189], v[198:201], v[104:107]
	v_mfma_f32_16x16x32_bf16 v[108:111], v[190:193], v[198:201], v[108:111]
	v_mfma_f32_16x16x32_bf16 v[52:55], v[194:197], v[198:201], v[52:55]
	v_mfma_f32_16x16x32_bf16 v[206:209], v[174:177], v[116:119], v[206:209]
	ds_read_b128 v[116:119], v8 offset:2048
	ds_read_b128 v[198:201], v8 offset:3072
	s_waitcnt lgkmcnt(0)
	v_mfma_f32_16x16x32_bf16 v[120:123], v[160:163], v[116:119], v[120:123]
	v_mfma_f32_16x16x32_bf16 v[124:127], v[170:173], v[116:119], v[124:127]
	v_mfma_f32_16x16x32_bf16 v[128:131], v[174:177], v[116:119], v[128:131]
	v_mfma_f32_16x16x32_bf16 v[112:115], v[194:197], v[116:119], v[112:115]
	v_mfma_f32_16x16x32_bf16 v[16:19], v[160:163], v[198:201], v[16:19]
	v_mfma_f32_16x16x32_bf16 v[20:23], v[170:173], v[198:201], v[20:23]
	v_mfma_f32_16x16x32_bf16 v[24:27], v[174:177], v[198:201], v[24:27]
	v_mfma_f32_16x16x32_bf16 v[28:31], v[178:181], v[198:201], v[28:31]
	v_mfma_f32_16x16x32_bf16 v[32:35], v[182:185], v[198:201], v[32:35]
	v_mfma_f32_16x16x32_bf16 v[36:39], v[186:189], v[198:201], v[36:39]
	v_mfma_f32_16x16x32_bf16 v[40:43], v[190:193], v[198:201], v[40:43]
	v_mfma_f32_16x16x32_bf16 v[44:47], v[194:197], v[198:201], v[44:47]
	v_mfma_f32_16x16x32_bf16 v[138:141], v[178:181], v[116:119], v[138:141]
	v_mfma_f32_16x16x32_bf16 v[148:151], v[182:185], v[116:119], v[148:151]
	v_mfma_f32_16x16x32_bf16 v[152:155], v[186:189], v[116:119], v[152:155]
	v_mfma_f32_16x16x32_bf16 v[156:159], v[190:193], v[116:119], v[156:159]
	ds_read_b128 v[116:119], v9
	ds_read_b128 v[160:163], v9 offset:8192
	s_waitcnt vmcnt(8)
	s_barrier
	s_waitcnt lgkmcnt(0)
	v_lshlrev_b32_e32 v170, 16, v116
	v_lshlrev_b32_e32 v171, 16, v160
	v_and_b32_e32 v173, 0xffff0000, v160
	v_and_b32_e32 v172, 0xffff0000, v116
	v_pk_fma_f32 v[64:65], v[170:171], v[170:171], v[64:65]
	v_lshlrev_b32_e32 v175, 16, v161
	v_lshlrev_b32_e32 v174, 16, v117
	v_pk_fma_f32 v[64:65], v[172:173], v[172:173], v[64:65]
	v_and_b32_e32 v161, 0xffff0000, v161
	v_and_b32_e32 v160, 0xffff0000, v117
	v_pk_fma_f32 v[64:65], v[174:175], v[174:175], v[64:65]
	v_lshlrev_b32_e32 v117, 16, v162
	v_lshlrev_b32_e32 v116, 16, v118
	v_pk_fma_f32 v[64:65], v[160:161], v[160:161], v[64:65]
	v_and_b32_e32 v177, 0xffff0000, v162
	v_and_b32_e32 v176, 0xffff0000, v118
	v_pk_fma_f32 v[64:65], v[116:117], v[116:117], v[64:65]
	v_lshlrev_b32_e32 v179, 16, v163
	v_lshlrev_b32_e32 v178, 16, v119
	v_pk_fma_f32 v[64:65], v[176:177], v[176:177], v[64:65]
	v_and_b32_e32 v163, 0xffff0000, v163
	v_and_b32_e32 v162, 0xffff0000, v119
	v_pk_fma_f32 v[64:65], v[178:179], v[178:179], v[64:65]
	s_nop 0
	v_pk_fma_f32 v[64:65], v[162:163], v[162:163], v[64:65]
	ds_read_b128 v[116:119], v8 offset:32768
	ds_read_b128 v[160:163], v10 offset:49152
	ds_read_b128 v[170:173], v10 offset:50176
	ds_read_b128 v[174:177], v10 offset:51200
	ds_read_b128 v[178:181], v10 offset:52224
	ds_read_b128 v[182:185], v10 offset:53248
	ds_read_b128 v[186:189], v10 offset:54272
	ds_read_b128 v[190:193], v10 offset:55296
	ds_read_b128 v[194:197], v10 offset:56320
	ds_read_b128 v[198:201], v8 offset:33792
	s_mov_b32 m0, s77
	v_lshl_add_u64 v[202:203], v[4:5], 0, s[40:41]
	global_load_lds_dwordx4 v[202:203], off
	v_lshl_add_u64 v[202:203], v[6:7], 0, s[40:41]
	s_mov_b32 m0, s79
	s_mov_b64 s[30:31], 0x18200
	global_load_lds_dwordx4 v[202:203], off
	v_lshl_add_u64 v[202:203], v[2:3], 0, s[40:41]
	s_mov_b32 m0, s80
	s_nop 0
	global_load_lds_dwordx4 v[202:203], off
	v_lshl_add_u64 v[202:203], v[2:3], 0, s[30:31]
	s_mov_b32 m0, s78
	s_nop 0
	global_load_lds_dwordx4 v[202:203], off
	s_waitcnt lgkmcnt(0)
	v_mfma_f32_16x16x32_bf16 v[56:59], v[160:163], v[116:119], v[56:59]
	v_mfma_f32_16x16x32_bf16 v[60:63], v[170:173], v[116:119], v[60:63]
	v_mfma_f32_16x16x32_bf16 v[68:71], v[178:181], v[116:119], v[68:71]
	v_mfma_f32_16x16x32_bf16 v[72:75], v[182:185], v[116:119], v[72:75]
	v_mfma_f32_16x16x32_bf16 v[76:79], v[186:189], v[116:119], v[76:79]
	v_mfma_f32_16x16x32_bf16 v[80:83], v[190:193], v[116:119], v[80:83]
	v_mfma_f32_16x16x32_bf16 v[48:51], v[194:197], v[116:119], v[48:51]
	v_mfma_f32_16x16x32_bf16 v[84:87], v[160:163], v[198:201], v[84:87]
	v_mfma_f32_16x16x32_bf16 v[88:91], v[170:173], v[198:201], v[88:91]
	v_mfma_f32_16x16x32_bf16 v[92:95], v[174:177], v[198:201], v[92:95]
	v_mfma_f32_16x16x32_bf16 v[96:99], v[178:181], v[198:201], v[96:99]
	v_mfma_f32_16x16x32_bf16 v[100:103], v[182:185], v[198:201], v[100:103]
	v_mfma_f32_16x16x32_bf16 v[104:107], v[186:189], v[198:201], v[104:107]
	v_mfma_f32_16x16x32_bf16 v[108:111], v[190:193], v[198:201], v[108:111]
	v_mfma_f32_16x16x32_bf16 v[52:55], v[194:197], v[198:201], v[52:55]
	v_mfma_f32_16x16x32_bf16 v[206:209], v[174:177], v[116:119], v[206:209]
	ds_read_b128 v[116:119], v8 offset:34816
	ds_read_b128 v[198:201], v8 offset:35840
	s_waitcnt lgkmcnt(0)
	v_mfma_f32_16x16x32_bf16 v[120:123], v[160:163], v[116:119], v[120:123]
	v_mfma_f32_16x16x32_bf16 v[124:127], v[170:173], v[116:119], v[124:127]
	v_mfma_f32_16x16x32_bf16 v[128:131], v[174:177], v[116:119], v[128:131]
	v_mfma_f32_16x16x32_bf16 v[112:115], v[194:197], v[116:119], v[112:115]
	v_mfma_f32_16x16x32_bf16 v[16:19], v[160:163], v[198:201], v[16:19]
	v_mfma_f32_16x16x32_bf16 v[20:23], v[170:173], v[198:201], v[20:23]
	v_mfma_f32_16x16x32_bf16 v[24:27], v[174:177], v[198:201], v[24:27]
	v_mfma_f32_16x16x32_bf16 v[28:31], v[178:181], v[198:201], v[28:31]
	v_mfma_f32_16x16x32_bf16 v[32:35], v[182:185], v[198:201], v[32:35]
	v_mfma_f32_16x16x32_bf16 v[36:39], v[186:189], v[198:201], v[36:39]
	v_mfma_f32_16x16x32_bf16 v[40:43], v[190:193], v[198:201], v[40:43]
	v_mfma_f32_16x16x32_bf16 v[44:47], v[194:197], v[198:201], v[44:47]
	v_mfma_f32_16x16x32_bf16 v[138:141], v[178:181], v[116:119], v[138:141]
	v_mfma_f32_16x16x32_bf16 v[148:151], v[182:185], v[116:119], v[148:151]
	v_mfma_f32_16x16x32_bf16 v[152:155], v[186:189], v[116:119], v[152:155]
	v_mfma_f32_16x16x32_bf16 v[156:159], v[190:193], v[116:119], v[156:159]
	ds_read_b128 v[116:119], v9 offset:32768
	ds_read_b128 v[160:163], v9 offset:40960
	s_waitcnt vmcnt(8)
	s_barrier
; DI void unpack8(uint4 u, float* v) { v[0] = bflo(u.x); v[1] = bfhi(u.x); v[2] = bflo(u.y); v[3] = bfhi(u.y); v[4] = bflo(u.z); v[5] = bfhi(u.z); v[6] = bflo(u.w); v[7] = bfhi(u.w); }
; #define MFMA16(a, b, c) __builtin_amdgcn_mfma_f32_16x16x32_bf16((a), (b), (c), 0, 0, 0)
; template <bool ROWSS, class AL, class EPI>
; DI void gemm8(unsigned char* smem, const AL& al, const bf16_t* __restrict__ Bt, int K, int m0, int n0, const EPI& epi) {
;     ...
;   for (int t = 0; t < nt; ++t) {
;     if (t + 2 < nt) asm volatile("s_waitcnt vmcnt(8)" ::: "memory");
;     else if (t + 1 < nt) asm volatile("s_waitcnt vmcnt(4)" ::: "memory");
;     else asm volatile("s_waitcnt vmcnt(0)" ::: "memory");
;     __builtin_amdgcn_s_barrier();
;     asm volatile("" ::: "memory");
;     const unsigned char* sa = smem + (t & 3) * 32768 + aoff;
;     const unsigned char* sb = smem + (t & 3) * 32768 + boff;
;     bf16x8 af0, af1, bfr[8];
;     af0 = *(const bf16x8*)(sa);
; #pragma unroll
;     for (int n = 0; n < 8; ++n) bfr[n] = *(const bf16x8*)(sb + n * 1024);
;     af1 = *(const bf16x8*)(sa + 1024);
;     __builtin_amdgcn_sched_barrier(0);
;     if (t + 3 < nt) G8_ISSUE(t + 3);
;     __builtin_amdgcn_sched_barrier(0);
; #pragma unroll
;     for (int n = 0; n < 8; ++n) acc[0][n] = MFMA16(bfr[n], af0, acc[0][n]);
; #pragma unroll
;     for (int n = 0; n < 8; ++n) acc[1][n] = MFMA16(bfr[n], af1, acc[1][n]);
;     __builtin_amdgcn_sched_barrier(0);
;     af0 = *(const bf16x8*)(sa + 2048); af1 = *(const bf16x8*)(sa + 3072);
;     __builtin_amdgcn_sched_barrier(0);
; #pragma unroll
;     for (int n = 0; n < 8; ++n) acc[2][n] = MFMA16(bfr[n], af0, acc[2][n]);
; #pragma unroll
;     for (int n = 0; n < 8; ++n) acc[3][n] = MFMA16(bfr[n], af1, acc[3][n]);
;     __builtin_amdgcn_sched_barrier(0);
;     if (ROWSS) {
;       float v[8];
;       unpack8(*(const uint4*)(smem + (t & 3) * 32768 + ptid * 16), v);
; #pragma unroll
;       for (int j = 0; j < 8; ++j) ss0 += v[j] * v[j];
;       unpack8(*(const uint4*)(smem + (t & 3) * 32768 + ptid * 16 + 8192), v);
; #pragma unroll
;       for (int j = 0; j < 8; ++j) ss1 += v[j] * v[j];
;     }
;   }
	s_waitcnt lgkmcnt(0)
	v_lshlrev_b32_e32 v170, 16, v116
	v_lshlrev_b32_e32 v171, 16, v160
	v_and_b32_e32 v173, 0xffff0000, v160
	v_and_b32_e32 v172, 0xffff0000, v116
	v_pk_fma_f32 v[64:65], v[170:171], v[170:171], v[64:65]
	v_lshlrev_b32_e32 v175, 16, v161
	v_lshlrev_b32_e32 v174, 16, v117
	v_pk_fma_f32 v[64:65], v[172:173], v[172:173], v[64:65]
	v_and_b32_e32 v161, 0xffff0000, v161
	v_and_b32_e32 v160, 0xffff0000, v117
	v_pk_fma_f32 v[64:65], v[174:175], v[174:175], v[64:65]
	v_lshlrev_b32_e32 v117, 16, v162
	v_lshlrev_b32_e32 v116, 16, v118
	v_pk_fma_f32 v[64:65], v[160:161], v[160:161], v[64:65]
	v_and_b32_e32 v177, 0xffff0000, v162
	v_and_b32_e32 v176, 0xffff0000, v118
	v_pk_fma_f32 v[64:65], v[116:117], v[116:117], v[64:65]
	v_lshlrev_b32_e32 v179, 16, v163
	v_lshlrev_b32_e32 v178, 16, v119
	v_pk_fma_f32 v[64:65], v[176:177], v[176:177], v[64:65]
	v_and_b32_e32 v163, 0xffff0000, v163
	v_and_b32_e32 v162, 0xffff0000, v119
	v_pk_fma_f32 v[64:65], v[178:179], v[178:179], v[64:65]
	s_nop 0
	v_pk_fma_f32 v[64:65], v[162:163], v[162:163], v[64:65]
	ds_read_b128 v[116:119], v11
	ds_read_b128 v[160:163], v14 offset:16384
	ds_read_b128 v[170:173], v14 offset:17408
	ds_read_b128 v[174:177], v14 offset:18432
	ds_read_b128 v[178:181], v14 offset:19456
	ds_read_b128 v[182:185], v14 offset:20480
	ds_read_b128 v[186:189], v14 offset:21504
	ds_read_b128 v[190:193], v14 offset:22528
	ds_read_b128 v[194:197], v14 offset:23552
	ds_read_b128 v[198:201], v11 offset:1024
	s_mov_b32 m0, s66
	v_lshl_add_u64 v[202:203], v[4:5], 0, s[44:45]
	global_load_lds_dwordx4 v[202:203], off
	v_lshl_add_u64 v[202:203], v[6:7], 0, s[44:45]
	s_mov_b32 m0, s67
	s_nop 0
	global_load_lds_dwordx4 v[202:203], off
	v_lshl_add_u64 v[202:203], v[2:3], 0, s[44:45]
	s_mov_b32 m0, s68
	s_nop 0
	global_load_lds_dwordx4 v[202:203], off
	v_lshl_add_u64 v[202:203], v[2:3], 0, s[50:51]
	s_mov_b32 m0, s69
	s_nop 0
	global_load_lds_dwordx4 v[202:203], off
	s_waitcnt lgkmcnt(0)
	v_mfma_f32_16x16x32_bf16 v[56:59], v[160:163], v[116:119], v[56:59]
	v_mfma_f32_16x16x32_bf16 v[60:63], v[170:173], v[116:119], v[60:63]
	v_mfma_f32_16x16x32_bf16 v[68:71], v[178:181], v[116:119], v[68:71]
	v_mfma_f32_16x16x32_bf16 v[72:75], v[182:185], v[116:119], v[72:75]
	v_mfma_f32_16x16x32_bf16 v[76:79], v[186:189], v[116:119], v[76:79]
	v_mfma_f32_16x16x32_bf16 v[80:83], v[190:193], v[116:119], v[80:83]
	v_mfma_f32_16x16x32_bf16 v[48:51], v[194:197], v[116:119], v[48:51]
	v_mfma_f32_16x16x32_bf16 v[84:87], v[160:163], v[198:201], v[84:87]
	v_mfma_f32_16x16x32_bf16 v[88:91], v[170:173], v[198:201], v[88:91]
	v_mfma_f32_16x16x32_bf16 v[92:95], v[174:177], v[198:201], v[92:95]
	v_mfma_f32_16x16x32_bf16 v[96:99], v[178:181], v[198:201], v[96:99]
	v_mfma_f32_16x16x32_bf16 v[100:103], v[182:185], v[198:201], v[100:103]
	v_mfma_f32_16x16x32_bf16 v[104:107], v[186:189], v[198:201], v[104:107]
	v_mfma_f32_16x16x32_bf16 v[108:111], v[190:193], v[198:201], v[108:111]
	v_mfma_f32_16x16x32_bf16 v[52:55], v[194:197], v[198:201], v[52:55]
	v_mfma_f32_16x16x32_bf16 v[206:209], v[174:177], v[116:119], v[206:209]
	ds_read_b128 v[116:119], v11 offset:2048
	ds_read_b128 v[198:201], v11 offset:3072
	s_waitcnt lgkmcnt(0)
	v_mfma_f32_16x16x32_bf16 v[120:123], v[160:163], v[116:119], v[120:123]
	v_mfma_f32_16x16x32_bf16 v[124:127], v[170:173], v[116:119], v[124:127]
	v_mfma_f32_16x16x32_bf16 v[128:131], v[174:177], v[116:119], v[128:131]
	v_mfma_f32_16x16x32_bf16 v[112:115], v[194:197], v[116:119], v[112:115]
	v_mfma_f32_16x16x32_bf16 v[16:19], v[160:163], v[198:201], v[16:19]
	v_mfma_f32_16x16x32_bf16 v[20:23], v[170:173], v[198:201], v[20:23]
	v_mfma_f32_16x16x32_bf16 v[24:27], v[174:177], v[198:201], v[24:27]
	v_mfma_f32_16x16x32_bf16 v[28:31], v[178:181], v[198:201], v[28:31]
	v_mfma_f32_16x16x32_bf16 v[32:35], v[182:185], v[198:201], v[32:35]
	v_mfma_f32_16x16x32_bf16 v[36:39], v[186:189], v[198:201], v[36:39]
	v_mfma_f32_16x16x32_bf16 v[40:43], v[190:193], v[198:201], v[40:43]
	v_mfma_f32_16x16x32_bf16 v[44:47], v[194:197], v[198:201], v[44:47]
	v_mfma_f32_16x16x32_bf16 v[138:141], v[178:181], v[116:119], v[138:141]
	v_mfma_f32_16x16x32_bf16 v[148:151], v[182:185], v[116:119], v[148:151]
	v_mfma_f32_16x16x32_bf16 v[152:155], v[186:189], v[116:119], v[152:155]
	v_mfma_f32_16x16x32_bf16 v[156:159], v[190:193], v[116:119], v[156:159]
	ds_read_b128 v[116:119], v13 offset:8192
	ds_read_b128 v[160:163], v13
	s_waitcnt vmcnt(8)
	s_barrier
; DI void unpack8(uint4 u, float* v) { v[0] = bflo(u.x); v[1] = bfhi(u.x); v[2] = bflo(u.y); v[3] = bfhi(u.y); v[4] = bflo(u.z); v[5] = bfhi(u.z); v[6] = bflo(u.w); v[7] = bfhi(u.w); }
; #define MFMA16(a, b, c) __builtin_amdgcn_mfma_f32_16x16x32_bf16((a), (b), (c), 0, 0, 0)
; template <bool ROWSS, class AL, class EPI>
; DI void gemm8(unsigned char* smem, const AL& al, const bf16_t* __restrict__ Bt, int K, int m0, int n0, const EPI& epi) {
;     ...
;   for (int t = 0; t < nt; ++t) {
;     if (t + 2 < nt) asm volatile("s_waitcnt vmcnt(8)" ::: "memory");
;     else if (t + 1 < nt) asm volatile("s_waitcnt vmcnt(4)" ::: "memory");
;     else asm volatile("s_waitcnt vmcnt(0)" ::: "memory");
;     __builtin_amdgcn_s_barrier();
;     asm volatile("" ::: "memory");
;     const unsigned char* sa = smem + (t & 3) * 32768 + aoff;
;     const unsigned char* sb = smem + (t & 3) * 32768 + boff;
;     bf16x8 af0, af1, bfr[8];
;     af0 = *(const bf16x8*)(sa);
; #pragma unroll
;     for (int n = 0; n < 8; ++n) bfr[n] = *(const bf16x8*)(sb + n * 1024);
;     af1 = *(const bf16x8*)(sa + 1024);
;     __builtin_amdgcn_sched_barrier(0);
;     if (t + 3 < nt) G8_ISSUE(t + 3);
;     __builtin_amdgcn_sched_barrier(0);
; #pragma unroll
;     for (int n = 0; n < 8; ++n) acc[0][n] = MFMA16(bfr[n], af0, acc[0][n]);
; #pragma unroll
;     for (int n = 0; n < 8; ++n) acc[1][n] = MFMA16(bfr[n], af1, acc[1][n]);
;     __builtin_amdgcn_sched_barrier(0);
;     af0 = *(const bf16x8*)(sa + 2048); af1 = *(const bf16x8*)(sa + 3072);
;     __builtin_amdgcn_sched_barrier(0);
; #pragma unroll
;     for (int n = 0; n < 8; ++n) acc[2][n] = MFMA16(bfr[n], af0, acc[2][n]);
; #pragma unroll
;     for (int n = 0; n < 8; ++n) acc[3][n] = MFMA16(bfr[n], af1, acc[3][n]);
;     __builtin_amdgcn_sched_barrier(0);
;     if (ROWSS) {
;       float v[8];
;       unpack8(*(const uint4*)(smem + (t & 3) * 32768 + ptid * 16), v);
; #pragma unroll
;       for (int j = 0; j < 8; ++j) ss0 += v[j] * v[j];
;       unpack8(*(const uint4*)(smem + (t & 3) * 32768 + ptid * 16 + 8192), v);
; #pragma unroll
;       for (int j = 0; j < 8; ++j) ss1 += v[j] * v[j];
;     }
;   }
	s_waitcnt lgkmcnt(0)
	v_lshlrev_b32_e32 v171, 16, v116
	v_lshlrev_b32_e32 v170, 16, v160
	v_and_b32_e32 v173, 0xffff0000, v116
	v_and_b32_e32 v172, 0xffff0000, v160
	v_pk_fma_f32 v[64:65], v[170:171], v[170:171], v[64:65]
	v_lshlrev_b32_e32 v175, 16, v117
	v_lshlrev_b32_e32 v174, 16, v161
	v_pk_fma_f32 v[64:65], v[172:173], v[172:173], v[64:65]
	v_and_b32_e32 v117, 0xffff0000, v117
	v_and_b32_e32 v116, 0xffff0000, v161
	v_pk_fma_f32 v[64:65], v[174:175], v[174:175], v[64:65]
	v_lshlrev_b32_e32 v203, 16, v118
	v_lshlrev_b32_e32 v202, 16, v162
	v_and_b32_e32 v211, 0xffff0000, v118
	v_and_b32_e32 v210, 0xffff0000, v162
	v_lshlrev_b32_e32 v213, 16, v119
	v_lshlrev_b32_e32 v212, 16, v163
	v_and_b32_e32 v215, 0xffff0000, v119
	v_and_b32_e32 v214, 0xffff0000, v163
	v_pk_fma_f32 v[64:65], v[116:117], v[116:117], v[64:65]
	ds_read_b128 v[116:119], v12 offset:16384
	ds_read_b128 v[160:163], v12 offset:17408
	ds_read_b128 v[170:173], v12 offset:18432
	ds_read_b128 v[174:177], v12 offset:19456
	ds_read_b128 v[178:181], v12 offset:20480
	ds_read_b128 v[182:185], v12 offset:21504
	ds_read_b128 v[186:189], v12 offset:22528
	ds_read_b128 v[190:193], v12 offset:23552
	ds_read_b128 v[194:197], v66
	ds_read_b128 v[198:201], v66 offset:1024
	v_pk_fma_f32 v[64:65], v[202:203], v[202:203], v[64:65]
	s_nop 0
	v_pk_fma_f32 v[64:65], v[210:211], v[210:211], v[64:65]
	s_nop 0
	v_pk_fma_f32 v[64:65], v[212:213], v[212:213], v[64:65]
	s_nop 0
	v_pk_fma_f32 v[64:65], v[214:215], v[214:215], v[64:65]
	s_mov_b32 m0, s81
	v_lshl_add_u64 v[202:203], v[4:5], 0, s[52:53]
	global_load_lds_dwordx4 v[202:203], off
	v_lshl_add_u64 v[202:203], v[6:7], 0, s[52:53]
	s_mov_b32 m0, s82
	s_nop 0
	global_load_lds_dwordx4 v[202:203], off
	v_lshl_add_u64 v[202:203], v[2:3], 0, s[52:53]
	s_mov_b32 m0, s83
	s_nop 0
	global_load_lds_dwordx4 v[202:203], off
	v_lshl_add_u64 v[202:203], v[2:3], 0, s[56:57]
	s_mov_b32 m0, s84
	s_nop 0
	global_load_lds_dwordx4 v[202:203], off
	s_waitcnt lgkmcnt(0)
	v_mfma_f32_16x16x32_bf16 v[56:59], v[116:119], v[194:197], v[56:59]
	v_mfma_f32_16x16x32_bf16 v[60:63], v[160:163], v[194:197], v[60:63]
	v_mfma_f32_16x16x32_bf16 v[68:71], v[174:177], v[194:197], v[68:71]
	v_mfma_f32_16x16x32_bf16 v[72:75], v[178:181], v[194:197], v[72:75]
	v_mfma_f32_16x16x32_bf16 v[76:79], v[182:185], v[194:197], v[76:79]
	v_mfma_f32_16x16x32_bf16 v[80:83], v[186:189], v[194:197], v[80:83]
	v_mfma_f32_16x16x32_bf16 v[48:51], v[190:193], v[194:197], v[48:51]
	v_mfma_f32_16x16x32_bf16 v[84:87], v[116:119], v[198:201], v[84:87]
	v_mfma_f32_16x16x32_bf16 v[88:91], v[160:163], v[198:201], v[88:91]
	v_mfma_f32_16x16x32_bf16 v[92:95], v[170:173], v[198:201], v[92:95]
	v_mfma_f32_16x16x32_bf16 v[96:99], v[174:177], v[198:201], v[96:99]
	v_mfma_f32_16x16x32_bf16 v[100:103], v[178:181], v[198:201], v[100:103]
	v_mfma_f32_16x16x32_bf16 v[104:107], v[182:185], v[198:201], v[104:107]
	v_mfma_f32_16x16x32_bf16 v[108:111], v[186:189], v[198:201], v[108:111]
	v_mfma_f32_16x16x32_bf16 v[52:55], v[190:193], v[198:201], v[52:55]
	v_mfma_f32_16x16x32_bf16 v[206:209], v[170:173], v[194:197], v[206:209]
	ds_read_b128 v[194:197], v66 offset:2048
	ds_read_b128 v[198:201], v66 offset:3072
	s_waitcnt lgkmcnt(0)
	v_mfma_f32_16x16x32_bf16 v[120:123], v[116:119], v[194:197], v[120:123]
	v_mfma_f32_16x16x32_bf16 v[124:127], v[160:163], v[194:197], v[124:127]
	v_mfma_f32_16x16x32_bf16 v[128:131], v[170:173], v[194:197], v[128:131]
	v_mfma_f32_16x16x32_bf16 v[112:115], v[190:193], v[194:197], v[112:115]
	v_mfma_f32_16x16x32_bf16 v[16:19], v[116:119], v[198:201], v[16:19]
	v_mfma_f32_16x16x32_bf16 v[20:23], v[160:163], v[198:201], v[20:23]
	v_mfma_f32_16x16x32_bf16 v[24:27], v[170:173], v[198:201], v[24:27]
	v_mfma_f32_16x16x32_bf16 v[28:31], v[174:177], v[198:201], v[28:31]
	v_mfma_f32_16x16x32_bf16 v[32:35], v[178:181], v[198:201], v[32:35]
	v_mfma_f32_16x16x32_bf16 v[36:39], v[182:185], v[198:201], v[36:39]
	v_mfma_f32_16x16x32_bf16 v[40:43], v[186:189], v[198:201], v[40:43]
	v_mfma_f32_16x16x32_bf16 v[44:47], v[190:193], v[198:201], v[44:47]
	v_mfma_f32_16x16x32_bf16 v[138:141], v[174:177], v[194:197], v[138:141]
	v_mfma_f32_16x16x32_bf16 v[148:151], v[178:181], v[194:197], v[148:151]
	v_mfma_f32_16x16x32_bf16 v[152:155], v[182:185], v[194:197], v[152:155]
	v_mfma_f32_16x16x32_bf16 v[156:159], v[186:189], v[194:197], v[156:159]
	ds_read_b128 v[116:119], v136 offset:8192
	ds_read_b128 v[160:163], v136
	s_waitcnt vmcnt(8)
	s_barrier
; DI void unpack8(uint4 u, float* v) { v[0] = bflo(u.x); v[1] = bfhi(u.x); v[2] = bflo(u.y); v[3] = bfhi(u.y); v[4] = bflo(u.z); v[5] = bfhi(u.z); v[6] = bflo(u.w); v[7] = bfhi(u.w); }
; #define MFMA16(a, b, c) __builtin_amdgcn_mfma_f32_16x16x32_bf16((a), (b), (c), 0, 0, 0)
; template <bool ROWSS, class AL, class EPI>
; DI void gemm8(unsigned char* smem, const AL& al, const bf16_t* __restrict__ Bt, int K, int m0, int n0, const EPI& epi) {
;     ...
;   for (int t = 0; t < nt; ++t) {
;     if (t + 2 < nt) asm volatile("s_waitcnt vmcnt(8)" ::: "memory");
;     else if (t + 1 < nt) asm volatile("s_waitcnt vmcnt(4)" ::: "memory");
;     else asm volatile("s_waitcnt vmcnt(0)" ::: "memory");
;     __builtin_amdgcn_s_barrier();
;     asm volatile("" ::: "memory");
;     const unsigned char* sa = smem + (t & 3) * 32768 + aoff;
;     const unsigned char* sb = smem + (t & 3) * 32768 + boff;
;     bf16x8 af0, af1, bfr[8];
;     af0 = *(const bf16x8*)(sa);
; #pragma unroll
;     for (int n = 0; n < 8; ++n) bfr[n] = *(const bf16x8*)(sb + n * 1024);
;     af1 = *(const bf16x8*)(sa + 1024);
;     __builtin_amdgcn_sched_barrier(0);
;     if (t + 3 < nt) G8_ISSUE(t + 3);
;     __builtin_amdgcn_sched_barrier(0);
; #pragma unroll
;     for (int n = 0; n < 8; ++n) acc[0][n] = MFMA16(bfr[n], af0, acc[0][n]);
; #pragma unroll
;     for (int n = 0; n < 8; ++n) acc[1][n] = MFMA16(bfr[n], af1, acc[1][n]);
;     __builtin_amdgcn_sched_barrier(0);
;     af0 = *(const bf16x8*)(sa + 2048); af1 = *(const bf16x8*)(sa + 3072);
;     __builtin_amdgcn_sched_barrier(0);
; #pragma unroll
;     for (int n = 0; n < 8; ++n) acc[2][n] = MFMA16(bfr[n], af0, acc[2][n]);
; #pragma unroll
;     for (int n = 0; n < 8; ++n) acc[3][n] = MFMA16(bfr[n], af1, acc[3][n]);
;     __builtin_amdgcn_sched_barrier(0);
;     if (ROWSS) {
;       float v[8];
;       unpack8(*(const uint4*)(smem + (t & 3) * 32768 + ptid * 16), v);
; #pragma unroll
;       for (int j = 0; j < 8; ++j) ss0 += v[j] * v[j];
;       unpack8(*(const uint4*)(smem + (t & 3) * 32768 + ptid * 16 + 8192), v);
; #pragma unroll
;       for (int j = 0; j < 8; ++j) ss1 += v[j] * v[j];
;     }
;   }
	s_waitcnt lgkmcnt(0)
	v_lshlrev_b32_e32 v171, 16, v116
	v_lshlrev_b32_e32 v170, 16, v160
	v_and_b32_e32 v173, 0xffff0000, v116
	v_and_b32_e32 v172, 0xffff0000, v160
	v_pk_fma_f32 v[64:65], v[170:171], v[170:171], v[64:65]
	v_lshlrev_b32_e32 v175, 16, v117
	v_lshlrev_b32_e32 v174, 16, v161
	v_pk_fma_f32 v[64:65], v[172:173], v[172:173], v[64:65]
	v_and_b32_e32 v117, 0xffff0000, v117
	v_and_b32_e32 v116, 0xffff0000, v161
	v_pk_fma_f32 v[64:65], v[174:175], v[174:175], v[64:65]
	v_lshlrev_b32_e32 v203, 16, v118
	v_lshlrev_b32_e32 v202, 16, v162
	v_and_b32_e32 v211, 0xffff0000, v118
	v_and_b32_e32 v210, 0xffff0000, v162
	v_lshlrev_b32_e32 v213, 16, v119
	v_lshlrev_b32_e32 v212, 16, v163
	v_and_b32_e32 v215, 0xffff0000, v119
	v_and_b32_e32 v214, 0xffff0000, v163
	v_pk_fma_f32 v[64:65], v[116:117], v[116:117], v[64:65]
	ds_read_b128 v[116:119], v10 offset:16384
	ds_read_b128 v[160:163], v10 offset:17408
	ds_read_b128 v[170:173], v10 offset:18432
	ds_read_b128 v[174:177], v10 offset:19456
	ds_read_b128 v[178:181], v10 offset:20480
	ds_read_b128 v[182:185], v10 offset:21504
	ds_read_b128 v[186:189], v10 offset:22528
	ds_read_b128 v[190:193], v10 offset:23552
	ds_read_b128 v[194:197], v8
	ds_read_b128 v[198:201], v8 offset:1024
	v_pk_fma_f32 v[64:65], v[202:203], v[202:203], v[64:65]
	s_nop 0
	v_pk_fma_f32 v[64:65], v[210:211], v[210:211], v[64:65]
	s_nop 0
	v_pk_fma_f32 v[64:65], v[212:213], v[212:213], v[64:65]
	s_nop 0
	v_pk_fma_f32 v[64:65], v[214:215], v[214:215], v[64:65]
	s_mov_b32 m0, s2
	v_lshl_add_u64 v[4:5], v[4:5], 0, s[58:59]
	global_load_lds_dwordx4 v[4:5], off
	v_lshl_add_u64 v[4:5], v[6:7], 0, s[58:59]
	s_mov_b32 m0, s3
	s_nop 0
	global_load_lds_dwordx4 v[4:5], off
	v_lshl_add_u64 v[4:5], v[2:3], 0, s[58:59]
	s_mov_b32 m0, s64
	v_lshl_add_u64 v[2:3], v[2:3], 0, s[60:61]
	global_load_lds_dwordx4 v[4:5], off
	s_mov_b32 m0, s65
	s_nop 0
	global_load_lds_dwordx4 v[2:3], off
	s_waitcnt lgkmcnt(0)
	v_mfma_f32_16x16x32_bf16 v[2:5], v[116:119], v[194:197], v[56:59]
	v_mfma_f32_16x16x32_bf16 v[56:59], v[160:163], v[194:197], v[60:63]
	v_mfma_f32_16x16x32_bf16 v[60:63], v[170:173], v[194:197], v[206:209]
	v_mfma_f32_16x16x32_bf16 v[68:71], v[174:177], v[194:197], v[68:71]
	v_mfma_f32_16x16x32_bf16 v[72:75], v[178:181], v[194:197], v[72:75]
	v_mfma_f32_16x16x32_bf16 v[76:79], v[182:185], v[194:197], v[76:79]
	v_mfma_f32_16x16x32_bf16 v[80:83], v[186:189], v[194:197], v[80:83]
	v_mfma_f32_16x16x32_bf16 v[48:51], v[190:193], v[194:197], v[48:51]
	ds_read_b128 v[194:197], v8 offset:2048
	v_mfma_f32_16x16x32_bf16 v[84:87], v[116:119], v[198:201], v[84:87]
	v_mfma_f32_16x16x32_bf16 v[88:91], v[160:163], v[198:201], v[88:91]
	v_mfma_f32_16x16x32_bf16 v[92:95], v[170:173], v[198:201], v[92:95]
	v_mfma_f32_16x16x32_bf16 v[96:99], v[174:177], v[198:201], v[96:99]
	v_mfma_f32_16x16x32_bf16 v[100:103], v[178:181], v[198:201], v[100:103]
	v_mfma_f32_16x16x32_bf16 v[104:107], v[182:185], v[198:201], v[104:107]
	v_mfma_f32_16x16x32_bf16 v[108:111], v[186:189], v[198:201], v[108:111]
	v_mfma_f32_16x16x32_bf16 v[52:55], v[190:193], v[198:201], v[52:55]
	ds_read_b128 v[198:201], v8 offset:3072
	s_waitcnt lgkmcnt(1)
	v_mfma_f32_16x16x32_bf16 v[120:123], v[116:119], v[194:197], v[120:123]
	v_mfma_f32_16x16x32_bf16 v[124:127], v[160:163], v[194:197], v[124:127]
	v_mfma_f32_16x16x32_bf16 v[112:115], v[190:193], v[194:197], v[112:115]
	s_waitcnt lgkmcnt(0)
	v_mfma_f32_16x16x32_bf16 v[16:19], v[116:119], v[198:201], v[16:19]
	v_mfma_f32_16x16x32_bf16 v[20:23], v[160:163], v[198:201], v[20:23]
	v_mfma_f32_16x16x32_bf16 v[24:27], v[170:173], v[198:201], v[24:27]
	v_mfma_f32_16x16x32_bf16 v[28:31], v[174:177], v[198:201], v[28:31]
	v_mfma_f32_16x16x32_bf16 v[32:35], v[178:181], v[198:201], v[32:35]
	v_mfma_f32_16x16x32_bf16 v[36:39], v[182:185], v[198:201], v[36:39]
	v_mfma_f32_16x16x32_bf16 v[40:43], v[186:189], v[198:201], v[40:43]
	v_mfma_f32_16x16x32_bf16 v[44:47], v[190:193], v[198:201], v[44:47]
	v_mfma_f32_16x16x32_bf16 v[206:209], v[170:173], v[194:197], v[128:131]
	v_mfma_f32_16x16x32_bf16 v[138:141], v[174:177], v[194:197], v[138:141]
	v_mfma_f32_16x16x32_bf16 v[148:151], v[178:181], v[194:197], v[148:151]
	v_mfma_f32_16x16x32_bf16 v[152:155], v[182:185], v[194:197], v[152:155]
	v_mfma_f32_16x16x32_bf16 v[156:159], v[186:189], v[194:197], v[156:159]
	ds_read_b128 v[116:119], v9 offset:8192
	ds_read_b128 v[128:131], v9
	s_waitcnt vmcnt(8)
	s_barrier
; DI void unpack8(uint4 u, float* v) { v[0] = bflo(u.x); v[1] = bfhi(u.x); v[2] = bflo(u.y); v[3] = bfhi(u.y); v[4] = bflo(u.z); v[5] = bfhi(u.z); v[6] = bflo(u.w); v[7] = bfhi(u.w); }
; #define MFMA16(a, b, c) __builtin_amdgcn_mfma_f32_16x16x32_bf16((a), (b), (c), 0, 0, 0)
; template <bool ROWSS, class AL, class EPI>
; DI void gemm8(unsigned char* smem, const AL& al, const bf16_t* __restrict__ Bt, int K, int m0, int n0, const EPI& epi) {
;     ...
;   for (int t = 0; t < nt; ++t) {
;     if (t + 2 < nt) asm volatile("s_waitcnt vmcnt(8)" ::: "memory");
;     else if (t + 1 < nt) asm volatile("s_waitcnt vmcnt(4)" ::: "memory");
;     else asm volatile("s_waitcnt vmcnt(0)" ::: "memory");
;     __builtin_amdgcn_s_barrier();
;     asm volatile("" ::: "memory");
;     const unsigned char* sa = smem + (t & 3) * 32768 + aoff;
;     const unsigned char* sb = smem + (t & 3) * 32768 + boff;
;     bf16x8 af0, af1, bfr[8];
;     af0 = *(const bf16x8*)(sa);
; #pragma unroll
;     for (int n = 0; n < 8; ++n) bfr[n] = *(const bf16x8*)(sb + n * 1024);
;     af1 = *(const bf16x8*)(sa + 1024);
;     __builtin_amdgcn_sched_barrier(0);
;     if (t + 3 < nt) G8_ISSUE(t + 3);
;     __builtin_amdgcn_sched_barrier(0);
; #pragma unroll
;     for (int n = 0; n < 8; ++n) acc[0][n] = MFMA16(bfr[n], af0, acc[0][n]);
; #pragma unroll
;     for (int n = 0; n < 8; ++n) acc[1][n] = MFMA16(bfr[n], af1, acc[1][n]);
;     __builtin_amdgcn_sched_barrier(0);
;     af0 = *(const bf16x8*)(sa + 2048); af1 = *(const bf16x8*)(sa + 3072);
;     __builtin_amdgcn_sched_barrier(0);
; #pragma unroll
;     for (int n = 0; n < 8; ++n) acc[2][n] = MFMA16(bfr[n], af0, acc[2][n]);
; #pragma unroll
;     for (int n = 0; n < 8; ++n) acc[3][n] = MFMA16(bfr[n], af1, acc[3][n]);
;     __builtin_amdgcn_sched_barrier(0);
;     if (ROWSS) {
;       float v[8];
;       unpack8(*(const uint4*)(smem + (t & 3) * 32768 + ptid * 16), v);
; #pragma unroll
;       for (int j = 0; j < 8; ++j) ss0 += v[j] * v[j];
;       unpack8(*(const uint4*)(smem + (t & 3) * 32768 + ptid * 16 + 8192), v);
; #pragma unroll
;       for (int j = 0; j < 8; ++j) ss1 += v[j] * v[j];
;     }
;   }
	s_waitcnt lgkmcnt(0)
	v_lshlrev_b32_e32 v7, 16, v116
	v_lshlrev_b32_e32 v6, 16, v128
	v_and_b32_e32 v161, 0xffff0000, v116
	v_and_b32_e32 v160, 0xffff0000, v128
	v_pk_fma_f32 v[6:7], v[6:7], v[6:7], v[64:65]
	v_lshlrev_b32_e32 v163, 16, v117
	v_lshlrev_b32_e32 v162, 16, v129
	v_pk_fma_f32 v[6:7], v[160:161], v[160:161], v[6:7]
	v_and_b32_e32 v117, 0xffff0000, v117
	v_and_b32_e32 v116, 0xffff0000, v129
	v_pk_fma_f32 v[6:7], v[162:163], v[162:163], v[6:7]
	v_lshlrev_b32_e32 v129, 16, v118
	v_and_b32_e32 v203, 0xffff0000, v118
	v_lshlrev_b32_e32 v211, 16, v119
	v_and_b32_e32 v213, 0xffff0000, v119
	v_pk_fma_f32 v[6:7], v[116:117], v[116:117], v[6:7]
	ds_read_b128 v[116:119], v10 offset:49152
	ds_read_b128 v[160:163], v10 offset:50176
	ds_read_b128 v[170:173], v10 offset:51200
	ds_read_b128 v[174:177], v10 offset:52224
	ds_read_b128 v[178:181], v10 offset:53248
	ds_read_b128 v[182:185], v10 offset:54272
	ds_read_b128 v[186:189], v10 offset:55296
	ds_read_b128 v[190:193], v10 offset:56320
	ds_read_b128 v[194:197], v8 offset:32768
	ds_read_b128 v[198:201], v8 offset:33792
	v_lshlrev_b32_e32 v128, 16, v130
	v_and_b32_e32 v202, 0xffff0000, v130
	v_pk_fma_f32 v[6:7], v[128:129], v[128:129], v[6:7]
	v_lshlrev_b32_e32 v210, 16, v131
	v_pk_fma_f32 v[6:7], v[202:203], v[202:203], v[6:7]
	v_and_b32_e32 v212, 0xffff0000, v131
	v_pk_fma_f32 v[6:7], v[210:211], v[210:211], v[6:7]
	s_nop 0
	v_pk_fma_f32 v[130:131], v[212:213], v[212:213], v[6:7]
	s_waitcnt lgkmcnt(0)
	v_mfma_f32_16x16x32_bf16 v[2:5], v[116:119], v[194:197], v[2:5]
	v_mfma_f32_16x16x32_bf16 v[56:59], v[160:163], v[194:197], v[56:59]
	v_mfma_f32_16x16x32_bf16 v[60:63], v[170:173], v[194:197], v[60:63]
	v_mfma_f32_16x16x32_bf16 v[68:71], v[174:177], v[194:197], v[68:71]
	v_mfma_f32_16x16x32_bf16 v[72:75], v[178:181], v[194:197], v[72:75]
	v_mfma_f32_16x16x32_bf16 v[76:79], v[182:185], v[194:197], v[76:79]
	v_mfma_f32_16x16x32_bf16 v[80:83], v[186:189], v[194:197], v[80:83]
	v_mfma_f32_16x16x32_bf16 v[48:51], v[190:193], v[194:197], v[48:51]
	ds_read_b128 v[194:197], v8 offset:34816
	v_mfma_f32_16x16x32_bf16 v[84:87], v[116:119], v[198:201], v[84:87]
	v_mfma_f32_16x16x32_bf16 v[88:91], v[160:163], v[198:201], v[88:91]
	v_mfma_f32_16x16x32_bf16 v[92:95], v[170:173], v[198:201], v[92:95]
	v_mfma_f32_16x16x32_bf16 v[96:99], v[174:177], v[198:201], v[96:99]
	v_mfma_f32_16x16x32_bf16 v[100:103], v[178:181], v[198:201], v[100:103]
	v_mfma_f32_16x16x32_bf16 v[104:107], v[182:185], v[198:201], v[104:107]
	v_mfma_f32_16x16x32_bf16 v[108:111], v[186:189], v[198:201], v[108:111]
	v_mfma_f32_16x16x32_bf16 v[52:55], v[190:193], v[198:201], v[52:55]
	ds_read_b128 v[198:201], v8 offset:35840
	s_waitcnt lgkmcnt(1)
	v_mfma_f32_16x16x32_bf16 v[120:123], v[116:119], v[194:197], v[120:123]
	v_mfma_f32_16x16x32_bf16 v[124:127], v[160:163], v[194:197], v[124:127]
	v_mfma_f32_16x16x32_bf16 v[112:115], v[190:193], v[194:197], v[112:115]
	s_waitcnt lgkmcnt(0)
	v_mfma_f32_16x16x32_bf16 v[16:19], v[116:119], v[198:201], v[16:19]
	v_mfma_f32_16x16x32_bf16 v[20:23], v[160:163], v[198:201], v[20:23]
	v_mfma_f32_16x16x32_bf16 v[24:27], v[170:173], v[198:201], v[24:27]
	v_mfma_f32_16x16x32_bf16 v[28:31], v[174:177], v[198:201], v[28:31]
	v_mfma_f32_16x16x32_bf16 v[32:35], v[178:181], v[198:201], v[32:35]
	v_mfma_f32_16x16x32_bf16 v[36:39], v[182:185], v[198:201], v[36:39]
	v_mfma_f32_16x16x32_bf16 v[40:43], v[186:189], v[198:201], v[40:43]
	v_mfma_f32_16x16x32_bf16 v[44:47], v[190:193], v[198:201], v[44:47]
	v_mfma_f32_16x16x32_bf16 v[206:209], v[170:173], v[194:197], v[206:209]
	v_mfma_f32_16x16x32_bf16 v[138:141], v[174:177], v[194:197], v[138:141]
	v_mfma_f32_16x16x32_bf16 v[148:151], v[178:181], v[194:197], v[148:151]
	v_mfma_f32_16x16x32_bf16 v[152:155], v[182:185], v[194:197], v[152:155]
	v_mfma_f32_16x16x32_bf16 v[156:159], v[186:189], v[194:197], v[156:159]
	ds_read_b128 v[116:119], v9 offset:32768
	ds_read_b128 v[6:9], v9 offset:40960
	s_waitcnt vmcnt(4)
	s_barrier
	s_waitcnt lgkmcnt(0)
	v_lshlrev_b32_e32 v10, 16, v116
	v_and_b32_e32 v15, 0xffff0000, v116
	v_lshlrev_b32_e32 v116, 16, v6
	v_and_b32_e32 v6, 0xffff0000, v6
	v_fma_f32 v144, v116, v116, v131
	v_lshlrev_b32_e32 v64, 16, v117
	v_and_b32_e32 v65, 0xffff0000, v117
	v_lshlrev_b32_e32 v117, 16, v7
	v_fmac_f32_e32 v144, v6, v6
	v_and_b32_e32 v7, 0xffff0000, v7
	v_fmac_f32_e32 v144, v117, v117
	v_lshlrev_b32_e32 v67, 16, v118
	v_and_b32_e32 v128, 0xffff0000, v118
	v_lshlrev_b32_e32 v118, 16, v8
	v_fmac_f32_e32 v144, v7, v7
	v_and_b32_e32 v8, 0xffff0000, v8
	v_fmac_f32_e32 v144, v118, v118
	v_lshlrev_b32_e32 v129, 16, v119
	v_and_b32_e32 v137, 0xffff0000, v119
	v_lshlrev_b32_e32 v119, 16, v9
	v_fmac_f32_e32 v144, v8, v8
	v_and_b32_e32 v9, 0xffff0000, v9
	v_fmac_f32_e32 v144, v119, v119
	v_fmac_f32_e32 v144, v9, v9
	ds_read_b128 v[6:9], v14 offset:16384
	ds_read_b128 v[116:119], v14 offset:17408
	ds_read_b128 v[160:163], v14 offset:18432
	ds_read_b128 v[170:173], v14 offset:19456
	ds_read_b128 v[174:177], v14 offset:20480
	ds_read_b128 v[178:181], v14 offset:21504
	ds_read_b128 v[182:185], v14 offset:22528
	ds_read_b128 v[186:189], v14 offset:23552
	ds_read_b128 v[190:193], v11
	ds_read_b128 v[194:197], v11 offset:1024
	v_fmac_f32_e32 v130, v10, v10
	v_fmac_f32_e32 v130, v15, v15
	v_fmac_f32_e32 v130, v64, v64
	v_fmac_f32_e32 v130, v65, v65
	v_fmac_f32_e32 v130, v67, v67
	v_fmac_f32_e32 v130, v128, v128
	v_fmac_f32_e32 v130, v129, v129
	v_fmac_f32_e32 v130, v137, v137
	s_waitcnt lgkmcnt(0)
; #define MFMA16(a, b, c) __builtin_amdgcn_mfma_f32_16x16x32_bf16((a), (b), (c), 0, 0, 0)
; template <bool ROWSS, class AL, class EPI>
; DI void gemm8(unsigned char* smem, const AL& al, const bf16_t* __restrict__ Bt, int K, int m0, int n0, const EPI& epi) {
;     ...
;     for (int n = 0; n < 8; ++n) acc[0][n] = MFMA16(bfr[n], af0, acc[0][n]);
; #pragma unroll
;     for (int n = 0; n < 8; ++n) acc[1][n] = MFMA16(bfr[n], af1, acc[1][n]);
;     __builtin_amdgcn_sched_barrier(0);
;     af0 = *(const bf16x8*)(sa + 2048); af1 = *(const bf16x8*)(sa + 3072);
;     __builtin_amdgcn_sched_barrier(0);
; #pragma unroll
;     for (int n = 0; n < 8; ++n) acc[2][n] = MFMA16(bfr[n], af0, acc[2][n]);
; #pragma unroll
;     for (int n = 0; n < 8; ++n) acc[3][n] = MFMA16(bfr[n], af1, acc[3][n]);
	v_mfma_f32_16x16x32_bf16 v[2:5], v[6:9], v[190:193], v[2:5]
	v_mfma_f32_16x16x32_bf16 v[56:59], v[116:119], v[190:193], v[56:59]
	v_mfma_f32_16x16x32_bf16 v[60:63], v[160:163], v[190:193], v[60:63]
	v_mfma_f32_16x16x32_bf16 v[68:71], v[170:173], v[190:193], v[68:71]
	v_mfma_f32_16x16x32_bf16 v[72:75], v[174:177], v[190:193], v[72:75]
	v_mfma_f32_16x16x32_bf16 v[76:79], v[178:181], v[190:193], v[76:79]
	v_mfma_f32_16x16x32_bf16 v[80:83], v[182:185], v[190:193], v[80:83]
	v_mfma_f32_16x16x32_bf16 v[48:51], v[186:189], v[190:193], v[48:51]
	v_mfma_f32_16x16x32_bf16 v[84:87], v[6:9], v[194:197], v[84:87]
	v_mfma_f32_16x16x32_bf16 v[88:91], v[116:119], v[194:197], v[88:91]
	v_mfma_f32_16x16x32_bf16 v[92:95], v[160:163], v[194:197], v[92:95]
	v_mfma_f32_16x16x32_bf16 v[96:99], v[170:173], v[194:197], v[96:99]
	v_mfma_f32_16x16x32_bf16 v[100:103], v[174:177], v[194:197], v[100:103]
	v_mfma_f32_16x16x32_bf16 v[104:107], v[178:181], v[194:197], v[104:107]
	v_mfma_f32_16x16x32_bf16 v[108:111], v[182:185], v[194:197], v[108:111]
	v_mfma_f32_16x16x32_bf16 v[190:193], v[186:189], v[194:197], v[52:55]
	s_nop 2
	ds_read_b128 v[52:55], v11 offset:2048
	ds_read_b128 v[194:197], v11 offset:3072
	s_waitcnt lgkmcnt(0)
	v_mfma_f32_16x16x32_bf16 v[120:123], v[6:9], v[52:55], v[120:123]
	v_mfma_f32_16x16x32_bf16 v[124:127], v[116:119], v[52:55], v[124:127]
	v_mfma_f32_16x16x32_bf16 v[112:115], v[186:189], v[52:55], v[112:115]
	v_mfma_f32_16x16x32_bf16 v[116:119], v[116:119], v[194:197], v[20:23]
	v_mfma_f32_16x16x32_bf16 v[198:201], v[160:163], v[52:55], v[206:209]
	v_mfma_f32_16x16x32_bf16 v[138:141], v[170:173], v[52:55], v[138:141]
	v_mfma_f32_16x16x32_bf16 v[148:151], v[174:177], v[52:55], v[148:151]
	v_mfma_f32_16x16x32_bf16 v[152:155], v[178:181], v[52:55], v[152:155]
	v_mfma_f32_16x16x32_bf16 v[156:159], v[182:185], v[52:55], v[156:159]
	v_mfma_f32_16x16x32_bf16 v[206:209], v[6:9], v[194:197], v[16:19]
	v_mfma_f32_16x16x32_bf16 v[160:163], v[160:163], v[194:197], v[24:27]
	v_mfma_f32_16x16x32_bf16 v[170:173], v[170:173], v[194:197], v[28:31]
	v_mfma_f32_16x16x32_bf16 v[174:177], v[174:177], v[194:197], v[32:35]
	v_mfma_f32_16x16x32_bf16 v[178:181], v[178:181], v[194:197], v[36:39]
	v_mfma_f32_16x16x32_bf16 v[182:185], v[182:185], v[194:197], v[40:43]
	v_mfma_f32_16x16x32_bf16 v[186:189], v[186:189], v[194:197], v[44:47]
	ds_read_b128 v[6:9], v13
	ds_read_b128 v[14:17], v13 offset:8192
	s_waitcnt vmcnt(0)
	s_barrier
; DI void unpack8(uint4 u, float* v) { v[0] = bflo(u.x); v[1] = bfhi(u.x); v[2] = bflo(u.y); v[3] = bfhi(u.y); v[4] = bflo(u.z); v[5] = bfhi(u.z); v[6] = bflo(u.w); v[7] = bfhi(u.w); }
; #define MFMA16(a, b, c) __builtin_amdgcn_mfma_f32_16x16x32_bf16((a), (b), (c), 0, 0, 0)
; template <bool ROWSS, class AL, class EPI>
; DI void gemm8(unsigned char* smem, const AL& al, const bf16_t* __restrict__ Bt, int K, int m0, int n0, const EPI& epi) {
;     ...
;     const unsigned char* sa = smem + (t & 3) * 32768 + aoff;
;     const unsigned char* sb = smem + (t & 3) * 32768 + boff;
;     bf16x8 af0, af1, bfr[8];
;     af0 = *(const bf16x8*)(sa);
; #pragma unroll
;     for (int n = 0; n < 8; ++n) bfr[n] = *(const bf16x8*)(sb + n * 1024);
;     af1 = *(const bf16x8*)(sa + 1024);
;     __builtin_amdgcn_sched_barrier(0);
;     if (t + 3 < nt) G8_ISSUE(t + 3);
;     __builtin_amdgcn_sched_barrier(0);
; #pragma unroll
;     for (int n = 0; n < 8; ++n) acc[0][n] = MFMA16(bfr[n], af0, acc[0][n]);
; #pragma unroll
;     for (int n = 0; n < 8; ++n) acc[1][n] = MFMA16(bfr[n], af1, acc[1][n]);
;     __builtin_amdgcn_sched_barrier(0);
;     af0 = *(const bf16x8*)(sa + 2048); af1 = *(const bf16x8*)(sa + 3072);
;     __builtin_amdgcn_sched_barrier(0);
; #pragma unroll
;     for (int n = 0; n < 8; ++n) acc[2][n] = MFMA16(bfr[n], af0, acc[2][n]);
; #pragma unroll
;     for (int n = 0; n < 8; ++n) acc[3][n] = MFMA16(bfr[n], af1, acc[3][n]);
;     __builtin_amdgcn_sched_barrier(0);
;     if (ROWSS) {
;       float v[8];
;       unpack8(*(const uint4*)(smem + (t & 3) * 32768 + ptid * 16), v);
; #pragma unroll
;       for (int j = 0; j < 8; ++j) ss0 += v[j] * v[j];
;       unpack8(*(const uint4*)(smem + (t & 3) * 32768 + ptid * 16 + 8192), v);
; #pragma unroll
;       for (int j = 0; j < 8; ++j) ss1 += v[j] * v[j];
;     }
;     ...
;   if (ROWSS) {
;     ss0 += __shfl_xor(ss0, 1); ss0 += __shfl_xor(ss0, 2);
;     ss1 += __shfl_xor(ss1, 1); ss1 += __shfl_xor(ss1, 2);
;     if ((lane & 3) == 0) { rowss[Rb] = ss0; rowss[Rb + 128] = ss1; }
;   }
	ds_read_b128 v[194:197], v12 offset:16384
	ds_read_b128 v[210:213], v12 offset:17408
	ds_read_b128 v[214:217], v12 offset:18432
	ds_read_b128 v[218:221], v12 offset:19456
	ds_read_b128 v[222:225], v12 offset:20480
	ds_read_b128 v[226:229], v12 offset:21504
	ds_read_b128 v[230:233], v12 offset:22528
	ds_read_b128 v[234:237], v12 offset:23552
	ds_read_b128 v[30:33], v66
	ds_read_b128 v[238:241], v66 offset:1024
	s_waitcnt lgkmcnt(0)
	v_lshlrev_b32_e32 v10, 16, v6
	v_and_b32_e32 v6, 0xffff0000, v6
	v_lshlrev_b32_e32 v19, 16, v14
	v_fmac_f32_e32 v130, v10, v10
	v_lshlrev_b32_e32 v11, 16, v7
	v_and_b32_e32 v14, 0xffff0000, v14
	v_fmac_f32_e32 v144, v19, v19
	v_fmac_f32_e32 v130, v6, v6
	v_and_b32_e32 v7, 0xffff0000, v7
	v_lshlrev_b32_e32 v20, 16, v15
	v_fmac_f32_e32 v144, v14, v14
	v_fmac_f32_e32 v130, v11, v11
	v_lshlrev_b32_e32 v13, 16, v8
	v_and_b32_e32 v15, 0xffff0000, v15
	v_fmac_f32_e32 v144, v20, v20
	v_fmac_f32_e32 v130, v7, v7
	v_and_b32_e32 v8, 0xffff0000, v8
	v_lshlrev_b32_e32 v21, 16, v16
	v_fmac_f32_e32 v144, v15, v15
	v_fmac_f32_e32 v130, v13, v13
	v_lshlrev_b32_e32 v18, 16, v9
	v_and_b32_e32 v16, 0xffff0000, v16
	v_fmac_f32_e32 v144, v21, v21
	v_fmac_f32_e32 v130, v8, v8
	v_and_b32_e32 v9, 0xffff0000, v9
	v_lshlrev_b32_e32 v22, 16, v17
	v_fmac_f32_e32 v144, v16, v16
	v_fmac_f32_e32 v130, v18, v18
	v_and_b32_e32 v17, 0xffff0000, v17
	v_fmac_f32_e32 v144, v22, v22
	v_fmac_f32_e32 v130, v9, v9
	v_fmac_f32_e32 v144, v17, v17
	v_mfma_f32_16x16x32_bf16 v[2:5], v[194:197], v[30:33], v[2:5]
	v_mfma_f32_16x16x32_bf16 v[6:9], v[210:213], v[30:33], v[56:59]
	v_mfma_f32_16x16x32_bf16 v[10:13], v[214:217], v[30:33], v[60:63]
	v_mfma_f32_16x16x32_bf16 v[14:17], v[218:221], v[30:33], v[68:71]
	v_mfma_f32_16x16x32_bf16 v[18:21], v[222:225], v[30:33], v[72:75]
	v_mfma_f32_16x16x32_bf16 v[22:25], v[226:229], v[30:33], v[76:79]
	v_mfma_f32_16x16x32_bf16 v[26:29], v[230:233], v[30:33], v[80:83]
	v_mfma_f32_16x16x32_bf16 v[30:33], v[234:237], v[30:33], v[48:51]
	v_mfma_f32_16x16x32_bf16 v[34:37], v[194:197], v[238:241], v[84:87]
	v_mfma_f32_16x16x32_bf16 v[38:41], v[210:213], v[238:241], v[88:91]
	v_mfma_f32_16x16x32_bf16 v[42:45], v[214:217], v[238:241], v[92:95]
	v_mfma_f32_16x16x32_bf16 v[46:49], v[218:221], v[238:241], v[96:99]
	v_mfma_f32_16x16x32_bf16 v[50:53], v[222:225], v[238:241], v[100:103]
	v_mfma_f32_16x16x32_bf16 v[54:57], v[226:229], v[238:241], v[104:107]
	v_mfma_f32_16x16x32_bf16 v[58:61], v[230:233], v[238:241], v[108:111]
	v_mfma_f32_16x16x32_bf16 v[62:65], v[234:237], v[238:241], v[190:193]
	ds_read_b128 v[94:97], v66 offset:2048
	s_nop 1
	ds_read_b128 v[190:193], v66 offset:3072
	s_waitcnt lgkmcnt(0)
	v_mfma_f32_16x16x32_bf16 v[66:69], v[194:197], v[94:97], v[120:123]
	v_mfma_f32_16x16x32_bf16 v[70:73], v[210:213], v[94:97], v[124:127]
	v_mfma_f32_16x16x32_bf16 v[74:77], v[214:217], v[94:97], v[198:201]
	v_mfma_f32_16x16x32_bf16 v[78:81], v[218:221], v[94:97], v[138:141]
	v_mfma_f32_16x16x32_bf16 v[82:85], v[222:225], v[94:97], v[148:151]
	v_mfma_f32_16x16x32_bf16 v[86:89], v[226:229], v[94:97], v[152:155]
	v_mfma_f32_16x16x32_bf16 v[90:93], v[230:233], v[94:97], v[156:159]
	v_mfma_f32_16x16x32_bf16 v[94:97], v[234:237], v[94:97], v[112:115]
	v_mfma_f32_16x16x32_bf16 v[98:101], v[194:197], v[190:193], v[206:209]
	v_mfma_f32_16x16x32_bf16 v[102:105], v[210:213], v[190:193], v[116:119]
	v_mfma_f32_16x16x32_bf16 v[106:109], v[214:217], v[190:193], v[160:163]
	v_mfma_f32_16x16x32_bf16 v[110:113], v[218:221], v[190:193], v[170:173]
	v_mfma_f32_16x16x32_bf16 v[114:117], v[222:225], v[190:193], v[174:177]
	v_mfma_f32_16x16x32_bf16 v[118:121], v[226:229], v[190:193], v[178:181]
	v_mfma_f32_16x16x32_bf16 v[122:125], v[230:233], v[190:193], v[182:185]
	v_mfma_f32_16x16x32_bf16 v[126:129], v[234:237], v[190:193], v[186:189]
	ds_read_b128 v[138:141], v136
	ds_read_b128 v[148:151], v136 offset:8192
	v_cmp_lt_i32_e32 vcc, v165, v166
	s_waitcnt vmcnt(0) lgkmcnt(0)
	s_barrier
	v_lshlrev_b32_e32 v131, 16, v138
	v_and_b32_e32 v136, 0xffff0000, v138
	v_fmac_f32_e32 v130, v131, v131
	v_lshlrev_b32_e32 v137, 16, v139
	v_fmac_f32_e32 v130, v136, v136
	v_and_b32_e32 v138, 0xffff0000, v139
	v_fmac_f32_e32 v130, v137, v137
	v_lshlrev_b32_e32 v139, 16, v140
	v_fmac_f32_e32 v130, v138, v138
	v_and_b32_e32 v140, 0xffff0000, v140
	v_lshlrev_b32_e32 v153, 16, v148
	v_fmac_f32_e32 v130, v139, v139
	v_lshlrev_b32_e32 v152, 16, v141
	v_and_b32_e32 v148, 0xffff0000, v148
	v_fmac_f32_e32 v144, v153, v153
	v_fmac_f32_e32 v130, v140, v140
	v_and_b32_e32 v141, 0xffff0000, v141
	v_lshlrev_b32_e32 v154, 16, v149
	v_fmac_f32_e32 v144, v148, v148
	v_fmac_f32_e32 v130, v152, v152
	v_cndmask_b32_e32 v131, v164, v165, vcc
	v_and_b32_e32 v149, 0xffff0000, v149
	v_fmac_f32_e32 v144, v154, v154
	v_fmac_f32_e32 v130, v141, v141
	v_lshlrev_b32_e32 v131, 2, v131
	v_lshlrev_b32_e32 v155, 16, v150
	v_fmac_f32_e32 v144, v149, v149
	ds_bpermute_b32 v136, v131, v130
	v_and_b32_e32 v150, 0xffff0000, v150
	v_fmac_f32_e32 v144, v155, v155
	v_lshlrev_b32_e32 v156, 16, v151
	v_fmac_f32_e32 v144, v150, v150
	v_and_b32_e32 v151, 0xffff0000, v151
	v_fmac_f32_e32 v144, v156, v156
	v_fmac_f32_e32 v144, v151, v151
	s_waitcnt lgkmcnt(0)
	v_add_f32_e32 v130, v130, v136
	ds_bpermute_b32 v136, v131, v144
	v_cmp_lt_i32_e32 vcc, v167, v166
	v_and_b32_e32 v138, 3, v132
	s_waitcnt lgkmcnt(0)
	v_cndmask_b32_e32 v131, v164, v167, vcc
	v_lshlrev_b32_e32 v137, 2, v131
	v_add_f32_e32 v136, v144, v136
	ds_bpermute_b32 v131, v137, v130
	ds_bpermute_b32 v137, v137, v136
	v_cmp_eq_u32_e32 vcc, 0, v138
	s_and_saveexec_b64 s[2:3], vcc
	s_cbranch_execz .LBB0_1265
	v_lshl_add_u32 v134, v134, 2, 0
	v_add_u32_e32 v134, 0x21000, v134
	s_waitcnt lgkmcnt(1)
	v_add_f32_e32 v130, v130, v131
	s_waitcnt lgkmcnt(0)
	v_add_f32_e32 v131, v136, v137
	ds_write2st64_b32 v134, v130, v131 offset1:2

; DI int PTID() { int t = threadIdx.x; asm volatile("" : "+v"(t)); return t; }
; template <bool ROWSS, class AL, class EPI>
; DI void gemm8(unsigned char* smem, const AL& al, const bf16_t* __restrict__ Bt, int K, int m0, int n0, const EPI& epi) {
;   const int ptid = PTID(), lane = ptid & 63, w = __builtin_amdgcn_readfirstlane(ptid >> 6), wm = w >> 1, wn = w & 1, fr = lane & 15, fq = lane >> 4;
;   f32x4 acc[4][8];
; #pragma unroll
;   for (int a = 0; a < 4; ++a)
; #pragma unroll
;     for (int b = 0; b < 8; ++b) acc[a][b] = (f32x4){0.f, 0.f, 0.f, 0.f};
;   const int sb_ = lane * 16, swz_ = sb_ ^ (((sb_ >> 9) & 1) << 5);
;   const int Rb = w * 16 + (swz_ >> 6), C0 = (swz_ & 63) >> 1;
;   const bf16_t* bp0 = Bt + (size_t)(n0 + Rb) * K + C0; const bf16_t* bp1 = bp0 + (size_t)128 * K;
;   float ss0 = 0.f, ss1 = 0.f;
;   const int nt = K >> 5;
;   const int frag = (fr * 64 + fq * 16) ^ (((fr >> 3) & 1) << 5);
;   const int aoff = wm * 4096 + frag, boff = 16384 + wn * 8192 + frag;
;     ...
;   if constexpr (ROWSS) {
;   G8_ISSUE(0); G8_ISSUE(1); G8_ISSUE(2);
;   for (int t = 0; t < nt; ++t) {
;     if (t + 2 < nt) asm volatile("s_waitcnt vmcnt(8)" ::: "memory");
;     else if (t + 1 < nt) asm volatile("s_waitcnt vmcnt(4)" ::: "memory");
;     else asm volatile("s_waitcnt vmcnt(0)" ::: "memory");
;     __builtin_amdgcn_s_barrier();
;     asm volatile("" ::: "memory");
;     const unsigned char* sa = smem + (t & 3) * 32768 + aoff;
;     const unsigned char* sb = smem + (t & 3) * 32768 + boff;
;     bf16x8 af0, af1, bfr[8];
;     af0 = *(const bf16x8*)(sa);
; #pragma unroll
;     for (int n = 0; n < 8; ++n) bfr[n] = *(const bf16x8*)(sb + n * 1024);
;     af1 = *(const bf16x8*)(sa + 1024);
;     __builtin_amdgcn_sched_barrier(0);
;     if (t + 3 < nt) G8_ISSUE(t + 3);
; DI void run_phase(unsigned char* smem_in, const Params& P, int ph) {
;     ...
;       { int tm, tn; for (int i = 0; tile_map(i, pbid, pnb, 128, 4, tm, tn); ++i) gemm8<true>(psmem, a, Bt, 256, tm * 256, tn * 256, e); }
.LBB0_1300:
	v_mov_b32_e32 v130, v204
	s_lshl_b32 s2, s77, 8
	v_readfirstlane_b32 s82, v130
	s_ashr_i32 s0, s82, 6
	v_bfe_u32 v3, v130, 2, 4
	v_lshl_or_b32 v134, s0, 4, v3
	v_add_u32_e32 v4, s2, v134
	s_lshl_b32 s3, s79, 8
	v_and_b32_e32 v2, 32, v130
	v_lshlrev_b32_e32 v9, 4, v130
	v_ashrrev_i32_e32 v5, 31, v4
	v_bitop3_b32 v132, v9, v2, 48 bitop3:0x6c
	v_add_u32_e32 v2, s3, v134
	s_lshl_b32 s1, s0, 10
	v_lshlrev_b64 v[4:5], 9, v[4:5]
	v_ashrrev_i32_e32 v3, 31, v2
	s_add_i32 s84, s1, 0
	v_lshl_add_u64 v[4:5], s[20:21], 0, v[4:5]
	v_lshlrev_b64 v[2:3], 9, v[2:3]
	v_lshl_add_u64 v[4:5], v[4:5], 0, v[132:133]
	s_mov_b32 m0, s84
	s_add_i32 s30, s84, 0x2000
	v_lshl_add_u64 v[2:3], s[22:23], 0, v[2:3]
	global_load_lds_dwordx4 v[4:5], off
	v_lshl_add_u64 v[10:11], v[4:5], 0, s[38:39]
	s_mov_b32 m0, s30
	s_add_i32 s31, s84, 0x4000
	v_lshl_add_u64 v[2:3], v[2:3], 0, v[132:133]
	global_load_lds_dwordx4 v[10:11], off
	s_mov_b32 m0, s31
	s_add_i32 vcc_lo, s84, 0x6000
	v_lshl_add_u64 v[6:7], v[2:3], 0, s[38:39]
	global_load_lds_dwordx4 v[2:3], off
	s_mov_b32 m0, vcc_lo
	s_add_i32 s94, s84, 0x8000
	global_load_lds_dwordx4 v[6:7], off
	v_lshl_add_u64 v[6:7], v[4:5], 0, 64
	s_mov_b32 m0, s94
	s_add_i32 s95, s84, 0xa000
	global_load_lds_dwordx4 v[6:7], off
	v_lshl_add_u64 v[6:7], v[4:5], 0, s[40:41]
	s_mov_b32 m0, s95
	s_add_i32 s96, s84, 0xc000
	global_load_lds_dwordx4 v[6:7], off
	v_lshl_add_u64 v[6:7], v[2:3], 0, 64
	s_mov_b32 m0, s96
	s_add_i32 s97, s84, 0xe000
	s_add_i32 s93, 0, 0x10000
	global_load_lds_dwordx4 v[6:7], off
	v_lshl_add_u64 v[6:7], v[2:3], 0, s[40:41]
	s_mov_b32 m0, s97
	s_add_i32 s1, s93, s1
	global_load_lds_dwordx4 v[6:7], off
	v_lshl_add_u64 v[6:7], v[4:5], 0, s[44:45]
	s_mov_b32 m0, s1
	s_ashr_i32 s26, s82, 7
	global_load_lds_dwordx4 v[6:7], off
	v_lshl_add_u64 v[6:7], v[4:5], 0, s[50:51]
	s_add_i32 m0, s1, 0x2000
	v_and_b32_e32 v131, 15, v130
	global_load_lds_dwordx4 v[6:7], off
	v_lshl_add_u64 v[6:7], v[2:3], 0, s[44:45]
	s_add_i32 m0, s1, 0x4000
	s_and_b32 s80, s0, 1
	global_load_lds_dwordx4 v[6:7], off
	v_lshl_add_u64 v[6:7], v[2:3], 0, s[50:51]
	s_add_i32 m0, s1, 0x6000
	v_and_b32_e32 v132, 48, v130
	global_load_lds_dwordx4 v[6:7], off
	v_lshlrev_b32_e32 v7, 2, v130
	v_lshlrev_b32_e32 v6, 6, v131
	v_and_b32_e32 v7, 32, v7
	s_lshl_b32 s92, s26, 12
	v_bitop3_b32 v11, v6, v7, v132 bitop3:0x36
	s_lshl_b32 s85, s80, 13
	s_add_i32 s0, s92, 0
	v_add_u32_e32 v6, s0, v11
	s_add_i32 s0, s85, 0
	s_waitcnt vmcnt(8)
	s_barrier
	v_add_u32_e32 v7, s0, v11
	ds_read_b128 v[12:15], v7 offset:16384
	ds_read_b128 v[16:19], v7 offset:17408
	ds_read_b128 v[20:23], v7 offset:18432
	ds_read_b128 v[24:27], v7 offset:19456
	ds_read_b128 v[28:31], v7 offset:20480
	ds_read_b128 v[32:35], v7 offset:21504
	ds_read_b128 v[36:39], v7 offset:22528
	ds_read_b128 v[40:43], v7 offset:23552
	ds_read_b128 v[44:47], v6
	ds_read_b128 v[48:51], v6 offset:1024
	s_add_i32 s0, s84, 0x18000
	v_lshl_add_u64 v[52:53], v[4:5], 0, s[52:53]
	s_mov_b32 m0, s0
	s_add_i32 s1, s84, 0x1a000
	global_load_lds_dwordx4 v[52:53], off
	v_lshl_add_u64 v[52:53], v[4:5], 0, s[56:57]
	s_mov_b32 m0, s1
	s_add_i32 s81, s84, 0x1c000
	global_load_lds_dwordx4 v[52:53], off
	v_lshl_add_u64 v[52:53], v[2:3], 0, s[52:53]
	s_mov_b32 m0, s81
	s_add_i32 s83, s84, 0x1e000
	global_load_lds_dwordx4 v[52:53], off
	v_lshl_add_u64 v[52:53], v[2:3], 0, s[56:57]
	s_mov_b32 m0, s83
	s_nop 0
	global_load_lds_dwordx4 v[52:53], off
	s_waitcnt lgkmcnt(0)
	v_mfma_f32_16x16x32_bf16 v[52:55], v[12:15], v[44:47], 0
	v_mfma_f32_16x16x32_bf16 v[56:59], v[16:19], v[44:47], 0
	v_mfma_f32_16x16x32_bf16 v[60:63], v[20:23], v[44:47], 0
	v_mfma_f32_16x16x32_bf16 v[64:67], v[24:27], v[44:47], 0
	v_mfma_f32_16x16x32_bf16 v[68:71], v[28:31], v[44:47], 0
	v_mfma_f32_16x16x32_bf16 v[72:75], v[32:35], v[44:47], 0
	v_mfma_f32_16x16x32_bf16 v[76:79], v[36:39], v[44:47], 0
	v_mfma_f32_16x16x32_bf16 v[44:47], v[40:43], v[44:47], 0
	v_mfma_f32_16x16x32_bf16 v[80:83], v[12:15], v[48:51], 0
	v_mfma_f32_16x16x32_bf16 v[84:87], v[16:19], v[48:51], 0
	v_mfma_f32_16x16x32_bf16 v[88:91], v[20:23], v[48:51], 0
	v_mfma_f32_16x16x32_bf16 v[92:95], v[24:27], v[48:51], 0
	v_mfma_f32_16x16x32_bf16 v[96:99], v[28:31], v[48:51], 0
	v_mfma_f32_16x16x32_bf16 v[100:103], v[32:35], v[48:51], 0
	v_mfma_f32_16x16x32_bf16 v[104:107], v[36:39], v[48:51], 0
	v_mfma_f32_16x16x32_bf16 v[48:51], v[40:43], v[48:51], 0
	ds_read_b128 v[108:111], v6 offset:2048
	ds_read_b128 v[112:115], v6 offset:3072
	s_waitcnt lgkmcnt(0)
	v_mfma_f32_16x16x32_bf16 v[116:119], v[12:15], v[108:111], 0
	v_mfma_f32_16x16x32_bf16 v[120:123], v[16:19], v[108:111], 0
	v_mfma_f32_16x16x32_bf16 v[124:127], v[20:23], v[108:111], 0
	v_mfma_f32_16x16x32_bf16 v[138:141], v[24:27], v[108:111], 0
	v_mfma_f32_16x16x32_bf16 v[150:153], v[28:31], v[108:111], 0
	v_mfma_f32_16x16x32_bf16 v[154:157], v[32:35], v[108:111], 0
	v_mfma_f32_16x16x32_bf16 v[158:161], v[36:39], v[108:111], 0
	v_mfma_f32_16x16x32_bf16 v[108:111], v[40:43], v[108:111], 0
	v_mfma_f32_16x16x32_bf16 v[12:15], v[12:15], v[112:115], 0
	v_mfma_f32_16x16x32_bf16 v[16:19], v[16:19], v[112:115], 0
	v_mfma_f32_16x16x32_bf16 v[20:23], v[20:23], v[112:115], 0
	v_mfma_f32_16x16x32_bf16 v[24:27], v[24:27], v[112:115], 0
	v_mfma_f32_16x16x32_bf16 v[28:31], v[28:31], v[112:115], 0
	v_mfma_f32_16x16x32_bf16 v[32:35], v[32:35], v[112:115], 0
	v_mfma_f32_16x16x32_bf16 v[36:39], v[36:39], v[112:115], 0
	v_mfma_f32_16x16x32_bf16 v[40:43], v[40:43], v[112:115], 0
	v_add_u32_e32 v8, 0, v9
	ds_read_b128 v[112:115], v8
	s_waitcnt lgkmcnt(0)
	v_lshlrev_b32_e32 v10, 16, v112
	v_and_b32_e32 v128, 0xffff0000, v112
	v_lshlrev_b32_e32 v129, 16, v113
	v_and_b32_e32 v137, 0xffff0000, v113
	v_lshlrev_b32_e32 v142, 16, v114
	v_and_b32_e32 v143, 0xffff0000, v114
	v_lshlrev_b32_e32 v149, 16, v115
	v_and_b32_e32 v162, 0xffff0000, v115
	ds_read_b128 v[112:115], v8 offset:8192
	v_mul_f32_e32 v135, v10, v10
	v_fmac_f32_e32 v135, v128, v128
	v_fmac_f32_e32 v135, v129, v129
	v_fmac_f32_e32 v135, v137, v137
	s_waitcnt lgkmcnt(0)
	v_lshlrev_b32_e32 v10, 16, v112
	v_and_b32_e32 v112, 0xffff0000, v112
	v_mul_f32_e32 v136, v10, v10
	v_lshlrev_b32_e32 v163, 16, v113
	v_fmac_f32_e32 v136, v112, v112
	v_and_b32_e32 v113, 0xffff0000, v113
	v_fmac_f32_e32 v136, v163, v163
	v_lshlrev_b32_e32 v164, 16, v114
	v_fmac_f32_e32 v136, v113, v113
	v_and_b32_e32 v114, 0xffff0000, v114
	v_fmac_f32_e32 v136, v164, v164
	v_fmac_f32_e32 v135, v142, v142
	v_lshlrev_b32_e32 v165, 16, v115
	v_fmac_f32_e32 v136, v114, v114
	v_fmac_f32_e32 v135, v143, v143
	v_and_b32_e32 v115, 0xffff0000, v115
	v_fmac_f32_e32 v136, v165, v165
	v_fmac_f32_e32 v135, v149, v149
	s_waitcnt vmcnt(8)
	s_barrier
; DI void unpack8(uint4 u, float* v) { v[0] = bflo(u.x); v[1] = bfhi(u.x); v[2] = bflo(u.y); v[3] = bfhi(u.y); v[4] = bflo(u.z); v[5] = bfhi(u.z); v[6] = bflo(u.w); v[7] = bfhi(u.w); }
; #define MFMA16(a, b, c) __builtin_amdgcn_mfma_f32_16x16x32_bf16((a), (b), (c), 0, 0, 0)
; template <bool ROWSS, class AL, class EPI>
; DI void gemm8(unsigned char* smem, const AL& al, const bf16_t* __restrict__ Bt, int K, int m0, int n0, const EPI& epi) {
;     ...
;   for (int t = 0; t < nt; ++t) {
;     if (t + 2 < nt) asm volatile("s_waitcnt vmcnt(8)" ::: "memory");
;     else if (t + 1 < nt) asm volatile("s_waitcnt vmcnt(4)" ::: "memory");
;     else asm volatile("s_waitcnt vmcnt(0)" ::: "memory");
;     __builtin_amdgcn_s_barrier();
;     asm volatile("" ::: "memory");
;     const unsigned char* sa = smem + (t & 3) * 32768 + aoff;
;     const unsigned char* sb = smem + (t & 3) * 32768 + boff;
;     bf16x8 af0, af1, bfr[8];
;     af0 = *(const bf16x8*)(sa);
; #pragma unroll
;     for (int n = 0; n < 8; ++n) bfr[n] = *(const bf16x8*)(sb + n * 1024);
;     af1 = *(const bf16x8*)(sa + 1024);
;     __builtin_amdgcn_sched_barrier(0);
;     if (t + 3 < nt) G8_ISSUE(t + 3);
;     __builtin_amdgcn_sched_barrier(0);
; #pragma unroll
;     for (int n = 0; n < 8; ++n) acc[0][n] = MFMA16(bfr[n], af0, acc[0][n]);
; #pragma unroll
;     for (int n = 0; n < 8; ++n) acc[1][n] = MFMA16(bfr[n], af1, acc[1][n]);
;     __builtin_amdgcn_sched_barrier(0);
;     af0 = *(const bf16x8*)(sa + 2048); af1 = *(const bf16x8*)(sa + 3072);
;     __builtin_amdgcn_sched_barrier(0);
; #pragma unroll
;     for (int n = 0; n < 8; ++n) acc[2][n] = MFMA16(bfr[n], af0, acc[2][n]);
; #pragma unroll
;     for (int n = 0; n < 8; ++n) acc[3][n] = MFMA16(bfr[n], af1, acc[3][n]);
;     __builtin_amdgcn_sched_barrier(0);
;     if (ROWSS) {
;       float v[8];
;       unpack8(*(const uint4*)(smem + (t & 3) * 32768 + ptid * 16), v);
; #pragma unroll
;       for (int j = 0; j < 8; ++j) ss0 += v[j] * v[j];
;       unpack8(*(const uint4*)(smem + (t & 3) * 32768 + ptid * 16 + 8192), v);
; #pragma unroll
;       for (int j = 0; j < 8; ++j) ss1 += v[j] * v[j];
;     }
;   }
	v_fmac_f32_e32 v136, v115, v115
	v_fmac_f32_e32 v135, v162, v162
	ds_read_b128 v[112:115], v6 offset:32768
	ds_read_b128 v[162:165], v7 offset:49152
	ds_read_b128 v[166:169], v7 offset:50176
	ds_read_b128 v[170:173], v7 offset:51200
	ds_read_b128 v[174:177], v7 offset:52224
	ds_read_b128 v[178:181], v7 offset:53248
	ds_read_b128 v[182:185], v7 offset:54272
	ds_read_b128 v[186:189], v7 offset:55296
	ds_read_b128 v[190:193], v7 offset:56320
	ds_read_b128 v[194:197], v6 offset:33792
	s_mov_b32 m0, s84
	v_lshl_add_u64 v[128:129], v[4:5], 0, s[58:59]
	global_load_lds_dwordx4 v[128:129], off
	v_lshl_add_u64 v[128:129], v[4:5], 0, s[60:61]
	s_mov_b32 m0, s30
	s_nop 0
	global_load_lds_dwordx4 v[128:129], off
	v_lshl_add_u64 v[128:129], v[2:3], 0, s[58:59]
	s_mov_b32 m0, s31
	s_nop 0
	global_load_lds_dwordx4 v[128:129], off
	v_lshl_add_u64 v[128:129], v[2:3], 0, s[60:61]
	s_mov_b32 m0, vcc_lo
	s_nop 0
	global_load_lds_dwordx4 v[128:129], off
	s_waitcnt lgkmcnt(0)
	v_mfma_f32_16x16x32_bf16 v[52:55], v[162:165], v[112:115], v[52:55]
	v_mfma_f32_16x16x32_bf16 v[56:59], v[166:169], v[112:115], v[56:59]
	v_mfma_f32_16x16x32_bf16 v[60:63], v[170:173], v[112:115], v[60:63]
	v_mfma_f32_16x16x32_bf16 v[64:67], v[174:177], v[112:115], v[64:67]
	v_mfma_f32_16x16x32_bf16 v[68:71], v[178:181], v[112:115], v[68:71]
	v_mfma_f32_16x16x32_bf16 v[72:75], v[182:185], v[112:115], v[72:75]
	v_mfma_f32_16x16x32_bf16 v[76:79], v[186:189], v[112:115], v[76:79]
	v_mfma_f32_16x16x32_bf16 v[44:47], v[190:193], v[112:115], v[44:47]
	ds_read_b128 v[112:115], v6 offset:34816
	v_mfma_f32_16x16x32_bf16 v[80:83], v[162:165], v[194:197], v[80:83]
	v_mfma_f32_16x16x32_bf16 v[84:87], v[166:169], v[194:197], v[84:87]
	v_mfma_f32_16x16x32_bf16 v[88:91], v[170:173], v[194:197], v[88:91]
	v_mfma_f32_16x16x32_bf16 v[92:95], v[174:177], v[194:197], v[92:95]
	v_mfma_f32_16x16x32_bf16 v[96:99], v[178:181], v[194:197], v[96:99]
	v_mfma_f32_16x16x32_bf16 v[100:103], v[182:185], v[194:197], v[100:103]
	v_mfma_f32_16x16x32_bf16 v[104:107], v[186:189], v[194:197], v[104:107]
	v_mfma_f32_16x16x32_bf16 v[48:51], v[190:193], v[194:197], v[48:51]
	ds_read_b128 v[194:197], v6 offset:35840
	s_waitcnt lgkmcnt(1)
	v_mfma_f32_16x16x32_bf16 v[116:119], v[162:165], v[112:115], v[116:119]
	v_mfma_f32_16x16x32_bf16 v[120:123], v[166:169], v[112:115], v[120:123]
	v_mfma_f32_16x16x32_bf16 v[124:127], v[170:173], v[112:115], v[124:127]
	v_mfma_f32_16x16x32_bf16 v[138:141], v[174:177], v[112:115], v[138:141]
	v_mfma_f32_16x16x32_bf16 v[150:153], v[178:181], v[112:115], v[150:153]
	v_mfma_f32_16x16x32_bf16 v[154:157], v[182:185], v[112:115], v[154:157]
	v_mfma_f32_16x16x32_bf16 v[158:161], v[186:189], v[112:115], v[158:161]
	v_mfma_f32_16x16x32_bf16 v[108:111], v[190:193], v[112:115], v[108:111]
	s_waitcnt lgkmcnt(0)
	v_mfma_f32_16x16x32_bf16 v[112:115], v[162:165], v[194:197], v[12:15]
	v_mfma_f32_16x16x32_bf16 v[14:17], v[166:169], v[194:197], v[16:19]
	v_mfma_f32_16x16x32_bf16 v[18:21], v[170:173], v[194:197], v[20:23]
	v_mfma_f32_16x16x32_bf16 v[22:25], v[174:177], v[194:197], v[24:27]
	v_mfma_f32_16x16x32_bf16 v[26:29], v[178:181], v[194:197], v[28:31]
	v_mfma_f32_16x16x32_bf16 v[30:33], v[182:185], v[194:197], v[32:35]
	v_mfma_f32_16x16x32_bf16 v[34:37], v[186:189], v[194:197], v[36:39]
	v_mfma_f32_16x16x32_bf16 v[38:41], v[190:193], v[194:197], v[40:43]
	ds_read_b128 v[162:165], v8 offset:32768
	s_add_i32 s30, s93, s92
	s_waitcnt lgkmcnt(0)
	v_lshlrev_b32_e32 v10, 16, v162
	v_and_b32_e32 v12, 0xffff0000, v162
	v_lshlrev_b32_e32 v13, 16, v163
	v_and_b32_e32 v42, 0xffff0000, v163
	v_lshlrev_b32_e32 v43, 16, v164
	v_and_b32_e32 v128, 0xffff0000, v164
	v_lshlrev_b32_e32 v129, 16, v165
	v_and_b32_e32 v137, 0xffff0000, v165
	ds_read_b128 v[162:165], v8 offset:40960
	v_fmac_f32_e32 v135, v10, v10
	s_waitcnt vmcnt(8)
	s_barrier
	s_waitcnt lgkmcnt(0)
	v_lshlrev_b32_e32 v142, 16, v162
	v_and_b32_e32 v143, 0xffff0000, v162
	v_fmac_f32_e32 v136, v142, v142
	v_lshlrev_b32_e32 v149, 16, v163
	v_fmac_f32_e32 v136, v143, v143
	v_and_b32_e32 v162, 0xffff0000, v163
	v_fmac_f32_e32 v136, v149, v149
	v_lshlrev_b32_e32 v163, 16, v164
	v_fmac_f32_e32 v136, v162, v162
	v_and_b32_e32 v164, 0xffff0000, v164
	v_fmac_f32_e32 v136, v163, v163
	v_lshlrev_b32_e32 v166, 16, v165
	v_fmac_f32_e32 v136, v164, v164
	v_and_b32_e32 v165, 0xffff0000, v165
	v_fmac_f32_e32 v136, v166, v166
	v_add_u32_e32 v10, s30, v11
	s_add_i32 s30, s93, s85
	v_fmac_f32_e32 v136, v165, v165
	v_fmac_f32_e32 v135, v12, v12
	v_add_u32_e32 v12, s30, v11
	ds_read_b128 v[162:165], v10
	ds_read_b128 v[166:169], v12 offset:16384
	ds_read_b128 v[170:173], v12 offset:17408
	ds_read_b128 v[174:177], v12 offset:18432
	ds_read_b128 v[178:181], v12 offset:19456
	ds_read_b128 v[182:185], v12 offset:20480
	ds_read_b128 v[186:189], v12 offset:21504
	ds_read_b128 v[190:193], v12 offset:22528
	ds_read_b128 v[194:197], v12 offset:23552
	ds_read_b128 v[198:201], v10 offset:1024
	v_fmac_f32_e32 v135, v13, v13
	v_fmac_f32_e32 v135, v42, v42
	v_fmac_f32_e32 v135, v43, v43
	v_fmac_f32_e32 v135, v128, v128
	v_fmac_f32_e32 v135, v129, v129
	v_fmac_f32_e32 v135, v137, v137
	s_mov_b32 m0, s94
	v_lshl_add_u64 v[42:43], v[4:5], 0, s[62:63]
	global_load_lds_dwordx4 v[42:43], off
	v_lshl_add_u64 v[42:43], v[4:5], 0, s[64:65]
	s_mov_b32 m0, s95
	s_nop 0
	global_load_lds_dwordx4 v[42:43], off
	v_lshl_add_u64 v[42:43], v[2:3], 0, s[62:63]
	s_mov_b32 m0, s96
	s_nop 0
	global_load_lds_dwordx4 v[42:43], off
	v_lshl_add_u64 v[42:43], v[2:3], 0, s[64:65]
	s_mov_b32 m0, s97
	s_nop 0
	global_load_lds_dwordx4 v[42:43], off
	s_waitcnt lgkmcnt(0)
; DI void unpack8(uint4 u, float* v) { v[0] = bflo(u.x); v[1] = bfhi(u.x); v[2] = bflo(u.y); v[3] = bfhi(u.y); v[4] = bflo(u.z); v[5] = bfhi(u.z); v[6] = bflo(u.w); v[7] = bfhi(u.w); }
; #define MFMA16(a, b, c) __builtin_amdgcn_mfma_f32_16x16x32_bf16((a), (b), (c), 0, 0, 0)
; template <bool ROWSS, class AL, class EPI>
; DI void gemm8(unsigned char* smem, const AL& al, const bf16_t* __restrict__ Bt, int K, int m0, int n0, const EPI& epi) {
;     ...
;   for (int t = 0; t < nt; ++t) {
;     if (t + 2 < nt) asm volatile("s_waitcnt vmcnt(8)" ::: "memory");
;     else if (t + 1 < nt) asm volatile("s_waitcnt vmcnt(4)" ::: "memory");
;     else asm volatile("s_waitcnt vmcnt(0)" ::: "memory");
;     __builtin_amdgcn_s_barrier();
;     asm volatile("" ::: "memory");
;     const unsigned char* sa = smem + (t & 3) * 32768 + aoff;
;     const unsigned char* sb = smem + (t & 3) * 32768 + boff;
;     bf16x8 af0, af1, bfr[8];
;     af0 = *(const bf16x8*)(sa);
; #pragma unroll
;     for (int n = 0; n < 8; ++n) bfr[n] = *(const bf16x8*)(sb + n * 1024);
;     af1 = *(const bf16x8*)(sa + 1024);
;     __builtin_amdgcn_sched_barrier(0);
;     if (t + 3 < nt) G8_ISSUE(t + 3);
;     __builtin_amdgcn_sched_barrier(0);
; #pragma unroll
;     for (int n = 0; n < 8; ++n) acc[0][n] = MFMA16(bfr[n], af0, acc[0][n]);
; #pragma unroll
;     for (int n = 0; n < 8; ++n) acc[1][n] = MFMA16(bfr[n], af1, acc[1][n]);
;     __builtin_amdgcn_sched_barrier(0);
;     af0 = *(const bf16x8*)(sa + 2048); af1 = *(const bf16x8*)(sa + 3072);
;     __builtin_amdgcn_sched_barrier(0);
; #pragma unroll
;     for (int n = 0; n < 8; ++n) acc[2][n] = MFMA16(bfr[n], af0, acc[2][n]);
; #pragma unroll
;     for (int n = 0; n < 8; ++n) acc[3][n] = MFMA16(bfr[n], af1, acc[3][n]);
;     __builtin_amdgcn_sched_barrier(0);
;     if (ROWSS) {
;       float v[8];
;       unpack8(*(const uint4*)(smem + (t & 3) * 32768 + ptid * 16), v);
; #pragma unroll
;       for (int j = 0; j < 8; ++j) ss0 += v[j] * v[j];
;       unpack8(*(const uint4*)(smem + (t & 3) * 32768 + ptid * 16 + 8192), v);
; #pragma unroll
;       for (int j = 0; j < 8; ++j) ss1 += v[j] * v[j];
;     }
;   }
	v_mfma_f32_16x16x32_bf16 v[52:55], v[166:169], v[162:165], v[52:55]
	v_mfma_f32_16x16x32_bf16 v[56:59], v[170:173], v[162:165], v[56:59]
	v_mfma_f32_16x16x32_bf16 v[60:63], v[174:177], v[162:165], v[60:63]
	v_mfma_f32_16x16x32_bf16 v[68:71], v[182:185], v[162:165], v[68:71]
	v_mfma_f32_16x16x32_bf16 v[72:75], v[186:189], v[162:165], v[72:75]
	v_mfma_f32_16x16x32_bf16 v[76:79], v[190:193], v[162:165], v[76:79]
	v_mfma_f32_16x16x32_bf16 v[42:45], v[194:197], v[162:165], v[44:47]
	v_mfma_f32_16x16x32_bf16 v[80:83], v[166:169], v[198:201], v[80:83]
	v_mfma_f32_16x16x32_bf16 v[84:87], v[170:173], v[198:201], v[84:87]
	v_mfma_f32_16x16x32_bf16 v[88:91], v[174:177], v[198:201], v[88:91]
	v_mfma_f32_16x16x32_bf16 v[92:95], v[178:181], v[198:201], v[92:95]
	v_mfma_f32_16x16x32_bf16 v[96:99], v[182:185], v[198:201], v[96:99]
	v_mfma_f32_16x16x32_bf16 v[100:103], v[186:189], v[198:201], v[100:103]
	v_mfma_f32_16x16x32_bf16 v[104:107], v[190:193], v[198:201], v[104:107]
	v_mfma_f32_16x16x32_bf16 v[46:49], v[194:197], v[198:201], v[48:51]
	v_mfma_f32_16x16x32_bf16 v[206:209], v[178:181], v[162:165], v[64:67]
	s_nop 2
	ds_read_b128 v[64:67], v10 offset:2048
	ds_read_b128 v[162:165], v10 offset:3072
	s_waitcnt lgkmcnt(0)
	v_mfma_f32_16x16x32_bf16 v[116:119], v[166:169], v[64:67], v[116:119]
	v_mfma_f32_16x16x32_bf16 v[120:123], v[170:173], v[64:67], v[120:123]
	v_mfma_f32_16x16x32_bf16 v[124:127], v[174:177], v[64:67], v[124:127]
	v_mfma_f32_16x16x32_bf16 v[138:141], v[178:181], v[64:67], v[138:141]
	v_mfma_f32_16x16x32_bf16 v[108:111], v[194:197], v[64:67], v[108:111]
	v_mfma_f32_16x16x32_bf16 v[112:115], v[166:169], v[162:165], v[112:115]
	v_mfma_f32_16x16x32_bf16 v[14:17], v[170:173], v[162:165], v[14:17]
	v_mfma_f32_16x16x32_bf16 v[18:21], v[174:177], v[162:165], v[18:21]
	v_mfma_f32_16x16x32_bf16 v[22:25], v[178:181], v[162:165], v[22:25]
	v_mfma_f32_16x16x32_bf16 v[26:29], v[182:185], v[162:165], v[26:29]
	v_mfma_f32_16x16x32_bf16 v[30:33], v[186:189], v[162:165], v[30:33]
	v_mfma_f32_16x16x32_bf16 v[34:37], v[190:193], v[162:165], v[34:37]
	v_mfma_f32_16x16x32_bf16 v[38:41], v[194:197], v[162:165], v[38:41]
	v_mfma_f32_16x16x32_bf16 v[150:153], v[182:185], v[64:67], v[150:153]
	v_mfma_f32_16x16x32_bf16 v[154:157], v[186:189], v[64:67], v[154:157]
	v_mfma_f32_16x16x32_bf16 v[158:161], v[190:193], v[64:67], v[158:161]
	v_add_u32_e32 v13, s93, v9
	ds_read_b128 v[64:67], v13
	s_add_i32 s30, 0, 0x18000
	s_add_i32 s31, s30, s92
	s_waitcnt lgkmcnt(0)
	v_lshlrev_b32_e32 v50, 16, v64
	v_and_b32_e32 v51, 0xffff0000, v64
	v_lshlrev_b32_e32 v128, 16, v65
	v_and_b32_e32 v129, 0xffff0000, v65
	v_lshlrev_b32_e32 v137, 16, v66
	v_and_b32_e32 v142, 0xffff0000, v66
	v_lshlrev_b32_e32 v143, 16, v67
	v_and_b32_e32 v149, 0xffff0000, v67
	ds_read_b128 v[64:67], v13 offset:8192
	s_waitcnt vmcnt(8)
	s_barrier
	v_fmac_f32_e32 v135, v50, v50
	s_waitcnt lgkmcnt(0)
	v_lshlrev_b32_e32 v162, 16, v64
	v_and_b32_e32 v64, 0xffff0000, v64
	v_fmac_f32_e32 v136, v162, v162
	v_lshlrev_b32_e32 v163, 16, v65
	v_fmac_f32_e32 v136, v64, v64
	v_and_b32_e32 v65, 0xffff0000, v65
	v_fmac_f32_e32 v136, v163, v163
	v_lshlrev_b32_e32 v164, 16, v66
	v_fmac_f32_e32 v136, v65, v65
	v_and_b32_e32 v66, 0xffff0000, v66
	v_fmac_f32_e32 v136, v164, v164
	v_lshlrev_b32_e32 v165, 16, v67
	v_fmac_f32_e32 v136, v66, v66
	v_add_u32_e32 v66, s31, v11
	s_add_i32 s31, s30, s85
	v_fmac_f32_e32 v136, v165, v165
	v_add_u32_e32 v11, s31, v11
	ds_read_b128 v[162:165], v66
	ds_read_b128 v[166:169], v11 offset:16384
	ds_read_b128 v[170:173], v11 offset:17408
	ds_read_b128 v[174:177], v11 offset:18432
	ds_read_b128 v[178:181], v11 offset:19456
	ds_read_b128 v[182:185], v11 offset:20480
	ds_read_b128 v[186:189], v11 offset:21504
	ds_read_b128 v[190:193], v11 offset:22528
	ds_read_b128 v[194:197], v11 offset:23552
	ds_read_b128 v[198:201], v66 offset:1024
	v_fmac_f32_e32 v135, v51, v51
	v_fmac_f32_e32 v135, v128, v128
	v_fmac_f32_e32 v135, v129, v129
	v_fmac_f32_e32 v135, v137, v137
	v_fmac_f32_e32 v135, v142, v142
	v_and_b32_e32 v67, 0xffff0000, v67
	v_fmac_f32_e32 v135, v143, v143
	v_fmac_f32_e32 v136, v67, v67
	v_fmac_f32_e32 v135, v149, v149
	s_add_i32 m0, s84, 0x10000
	v_lshl_add_u64 v[50:51], v[4:5], 0, s[66:67]
	global_load_lds_dwordx4 v[50:51], off
	v_lshl_add_u64 v[50:51], v[4:5], 0, s[68:69]
	s_add_i32 m0, s84, 0x12000
	s_nop 0
	global_load_lds_dwordx4 v[50:51], off
	v_lshl_add_u64 v[50:51], v[2:3], 0, s[66:67]
	s_add_i32 m0, s84, 0x14000
	s_nop 0
	global_load_lds_dwordx4 v[50:51], off
	v_lshl_add_u64 v[50:51], v[2:3], 0, s[68:69]
	s_add_i32 m0, s84, 0x16000
	s_nop 0
	global_load_lds_dwordx4 v[50:51], off
	s_waitcnt lgkmcnt(0)
	v_mfma_f32_16x16x32_bf16 v[50:53], v[166:169], v[162:165], v[52:55]
	v_mfma_f32_16x16x32_bf16 v[54:57], v[170:173], v[162:165], v[56:59]
	v_mfma_f32_16x16x32_bf16 v[58:61], v[174:177], v[162:165], v[60:63]
	v_mfma_f32_16x16x32_bf16 v[62:65], v[178:181], v[162:165], v[206:209]
	v_mfma_f32_16x16x32_bf16 v[68:71], v[182:185], v[162:165], v[68:71]
	v_mfma_f32_16x16x32_bf16 v[72:75], v[186:189], v[162:165], v[72:75]
	v_mfma_f32_16x16x32_bf16 v[76:79], v[190:193], v[162:165], v[76:79]
	v_mfma_f32_16x16x32_bf16 v[42:45], v[194:197], v[162:165], v[42:45]
	ds_read_b128 v[162:165], v66 offset:2048
	v_mfma_f32_16x16x32_bf16 v[80:83], v[166:169], v[198:201], v[80:83]
	v_mfma_f32_16x16x32_bf16 v[84:87], v[170:173], v[198:201], v[84:87]
	v_mfma_f32_16x16x32_bf16 v[88:91], v[174:177], v[198:201], v[88:91]
	v_mfma_f32_16x16x32_bf16 v[92:95], v[178:181], v[198:201], v[92:95]
	v_mfma_f32_16x16x32_bf16 v[96:99], v[182:185], v[198:201], v[96:99]
	v_mfma_f32_16x16x32_bf16 v[100:103], v[186:189], v[198:201], v[100:103]
	v_mfma_f32_16x16x32_bf16 v[104:107], v[190:193], v[198:201], v[104:107]
	v_mfma_f32_16x16x32_bf16 v[46:49], v[194:197], v[198:201], v[46:49]
	ds_read_b128 v[198:201], v66 offset:3072
	s_waitcnt lgkmcnt(1)
; DI void unpack8(uint4 u, float* v) { v[0] = bflo(u.x); v[1] = bfhi(u.x); v[2] = bflo(u.y); v[3] = bfhi(u.y); v[4] = bflo(u.z); v[5] = bfhi(u.z); v[6] = bflo(u.w); v[7] = bfhi(u.w); }
; #define MFMA16(a, b, c) __builtin_amdgcn_mfma_f32_16x16x32_bf16((a), (b), (c), 0, 0, 0)
; template <bool ROWSS, class AL, class EPI>
; DI void gemm8(unsigned char* smem, const AL& al, const bf16_t* __restrict__ Bt, int K, int m0, int n0, const EPI& epi) {
;     ...
;   for (int t = 0; t < nt; ++t) {
;     if (t + 2 < nt) asm volatile("s_waitcnt vmcnt(8)" ::: "memory");
;     else if (t + 1 < nt) asm volatile("s_waitcnt vmcnt(4)" ::: "memory");
;     else asm volatile("s_waitcnt vmcnt(0)" ::: "memory");
;     __builtin_amdgcn_s_barrier();
;     asm volatile("" ::: "memory");
;     const unsigned char* sa = smem + (t & 3) * 32768 + aoff;
;     const unsigned char* sb = smem + (t & 3) * 32768 + boff;
;     bf16x8 af0, af1, bfr[8];
;     af0 = *(const bf16x8*)(sa);
; #pragma unroll
;     for (int n = 0; n < 8; ++n) bfr[n] = *(const bf16x8*)(sb + n * 1024);
;     af1 = *(const bf16x8*)(sa + 1024);
;     __builtin_amdgcn_sched_barrier(0);
;     if (t + 3 < nt) G8_ISSUE(t + 3);
;     __builtin_amdgcn_sched_barrier(0);
; #pragma unroll
;     for (int n = 0; n < 8; ++n) acc[0][n] = MFMA16(bfr[n], af0, acc[0][n]);
; #pragma unroll
;     for (int n = 0; n < 8; ++n) acc[1][n] = MFMA16(bfr[n], af1, acc[1][n]);
;     __builtin_amdgcn_sched_barrier(0);
;     af0 = *(const bf16x8*)(sa + 2048); af1 = *(const bf16x8*)(sa + 3072);
;     __builtin_amdgcn_sched_barrier(0);
; #pragma unroll
;     for (int n = 0; n < 8; ++n) acc[2][n] = MFMA16(bfr[n], af0, acc[2][n]);
; #pragma unroll
;     for (int n = 0; n < 8; ++n) acc[3][n] = MFMA16(bfr[n], af1, acc[3][n]);
;     __builtin_amdgcn_sched_barrier(0);
;     if (ROWSS) {
;       float v[8];
;       unpack8(*(const uint4*)(smem + (t & 3) * 32768 + ptid * 16), v);
; #pragma unroll
;       for (int j = 0; j < 8; ++j) ss0 += v[j] * v[j];
;       unpack8(*(const uint4*)(smem + (t & 3) * 32768 + ptid * 16 + 8192), v);
; #pragma unroll
;       for (int j = 0; j < 8; ++j) ss1 += v[j] * v[j];
;     }
;   }
	v_mfma_f32_16x16x32_bf16 v[116:119], v[166:169], v[162:165], v[116:119]
	v_mfma_f32_16x16x32_bf16 v[120:123], v[170:173], v[162:165], v[120:123]
	v_mfma_f32_16x16x32_bf16 v[124:127], v[174:177], v[162:165], v[124:127]
	v_mfma_f32_16x16x32_bf16 v[138:141], v[178:181], v[162:165], v[138:141]
	v_mfma_f32_16x16x32_bf16 v[108:111], v[194:197], v[162:165], v[108:111]
	s_waitcnt lgkmcnt(0)
	v_mfma_f32_16x16x32_bf16 v[112:115], v[166:169], v[198:201], v[112:115]
	v_mfma_f32_16x16x32_bf16 v[14:17], v[170:173], v[198:201], v[14:17]
	v_mfma_f32_16x16x32_bf16 v[18:21], v[174:177], v[198:201], v[18:21]
	v_mfma_f32_16x16x32_bf16 v[22:25], v[178:181], v[198:201], v[22:25]
	v_mfma_f32_16x16x32_bf16 v[26:29], v[182:185], v[198:201], v[26:29]
	v_mfma_f32_16x16x32_bf16 v[30:33], v[186:189], v[198:201], v[30:33]
	v_mfma_f32_16x16x32_bf16 v[34:37], v[190:193], v[198:201], v[34:37]
	v_mfma_f32_16x16x32_bf16 v[38:41], v[194:197], v[198:201], v[38:41]
	v_mfma_f32_16x16x32_bf16 v[150:153], v[182:185], v[162:165], v[150:153]
	v_mfma_f32_16x16x32_bf16 v[154:157], v[186:189], v[162:165], v[154:157]
	v_mfma_f32_16x16x32_bf16 v[158:161], v[190:193], v[162:165], v[158:161]
	v_add_u32_e32 v137, s30, v9
	ds_read_b128 v[162:165], v137
	ds_read_b128 v[166:169], v137 offset:8192
	s_waitcnt vmcnt(8)
	s_barrier
	s_waitcnt lgkmcnt(0)
	v_lshlrev_b32_e32 v9, 16, v162
	v_and_b32_e32 v67, 0xffff0000, v162
	v_lshlrev_b32_e32 v162, 16, v166
	v_lshlrev_b32_e32 v128, 16, v163
	v_and_b32_e32 v129, 0xffff0000, v163
	v_and_b32_e32 v163, 0xffff0000, v166
	v_fmac_f32_e32 v136, v162, v162
	v_lshlrev_b32_e32 v142, 16, v164
	v_and_b32_e32 v143, 0xffff0000, v164
	v_lshlrev_b32_e32 v164, 16, v167
	v_fmac_f32_e32 v136, v163, v163
	v_lshlrev_b32_e32 v149, 16, v165
	v_and_b32_e32 v202, 0xffff0000, v165
	v_and_b32_e32 v165, 0xffff0000, v167
	v_fmac_f32_e32 v136, v164, v164
	v_lshlrev_b32_e32 v166, 16, v168
	v_fmac_f32_e32 v136, v165, v165
	v_and_b32_e32 v167, 0xffff0000, v168
	v_fmac_f32_e32 v136, v166, v166
	v_lshlrev_b32_e32 v168, 16, v169
	v_fmac_f32_e32 v136, v167, v167
	v_and_b32_e32 v169, 0xffff0000, v169
	v_fmac_f32_e32 v136, v168, v168
	v_fmac_f32_e32 v136, v169, v169
	ds_read_b128 v[162:165], v7 offset:16384
	ds_read_b128 v[166:169], v7 offset:17408
	ds_read_b128 v[170:173], v7 offset:18432
	ds_read_b128 v[174:177], v7 offset:19456
	ds_read_b128 v[178:181], v7 offset:20480
	ds_read_b128 v[182:185], v7 offset:21504
	ds_read_b128 v[186:189], v7 offset:22528
	ds_read_b128 v[190:193], v7 offset:23552
	ds_read_b128 v[194:197], v6
	ds_read_b128 v[198:201], v6 offset:1024
	v_fmac_f32_e32 v135, v9, v9
	v_fmac_f32_e32 v135, v67, v67
	v_fmac_f32_e32 v135, v128, v128
	v_fmac_f32_e32 v135, v129, v129
	v_fmac_f32_e32 v135, v142, v142
	v_fmac_f32_e32 v135, v143, v143
	v_fmac_f32_e32 v135, v149, v149
	v_fmac_f32_e32 v135, v202, v202
	s_mov_b32 m0, s0
	v_lshl_add_u64 v[128:129], v[4:5], 0, s[70:71]
	global_load_lds_dwordx4 v[128:129], off
	v_lshl_add_u64 v[4:5], v[4:5], 0, s[72:73]
	s_mov_b32 m0, s1
	s_nop 0
	global_load_lds_dwordx4 v[4:5], off
	v_lshl_add_u64 v[4:5], v[2:3], 0, s[70:71]
	s_mov_b32 m0, s81
	v_lshl_add_u64 v[2:3], v[2:3], 0, s[72:73]
	global_load_lds_dwordx4 v[4:5], off
	s_mov_b32 m0, s83
	s_nop 0
	global_load_lds_dwordx4 v[2:3], off
	s_waitcnt lgkmcnt(0)
	v_mfma_f32_16x16x32_bf16 v[2:5], v[162:165], v[194:197], v[50:53]
	v_mfma_f32_16x16x32_bf16 v[50:53], v[166:169], v[194:197], v[54:57]
	v_mfma_f32_16x16x32_bf16 v[54:57], v[170:173], v[194:197], v[58:61]
	v_mfma_f32_16x16x32_bf16 v[58:61], v[174:177], v[194:197], v[62:65]
	v_mfma_f32_16x16x32_bf16 v[62:65], v[178:181], v[194:197], v[68:71]
	v_mfma_f32_16x16x32_bf16 v[68:71], v[182:185], v[194:197], v[72:75]
	v_mfma_f32_16x16x32_bf16 v[72:75], v[186:189], v[194:197], v[76:79]
	v_mfma_f32_16x16x32_bf16 v[42:45], v[190:193], v[194:197], v[42:45]
	v_mfma_f32_16x16x32_bf16 v[76:79], v[162:165], v[198:201], v[80:83]
	v_mfma_f32_16x16x32_bf16 v[80:83], v[166:169], v[198:201], v[84:87]
	v_mfma_f32_16x16x32_bf16 v[84:87], v[170:173], v[198:201], v[88:91]
	v_mfma_f32_16x16x32_bf16 v[88:91], v[174:177], v[198:201], v[92:95]
	v_mfma_f32_16x16x32_bf16 v[92:95], v[178:181], v[198:201], v[96:99]
	v_mfma_f32_16x16x32_bf16 v[96:99], v[182:185], v[198:201], v[100:103]
	v_mfma_f32_16x16x32_bf16 v[100:103], v[186:189], v[198:201], v[104:107]
	v_mfma_f32_16x16x32_bf16 v[46:49], v[190:193], v[198:201], v[46:49]
	s_nop 1
	ds_read_b128 v[104:107], v6 offset:2048
	ds_read_b128 v[194:197], v6 offset:3072
	s_waitcnt lgkmcnt(0)
	v_mfma_f32_16x16x32_bf16 v[116:119], v[162:165], v[104:107], v[116:119]
	v_mfma_f32_16x16x32_bf16 v[120:123], v[166:169], v[104:107], v[120:123]
	v_mfma_f32_16x16x32_bf16 v[124:127], v[170:173], v[104:107], v[124:127]
	v_mfma_f32_16x16x32_bf16 v[138:141], v[174:177], v[104:107], v[138:141]
	v_mfma_f32_16x16x32_bf16 v[150:153], v[178:181], v[104:107], v[150:153]
	v_mfma_f32_16x16x32_bf16 v[154:157], v[182:185], v[104:107], v[154:157]
	v_mfma_f32_16x16x32_bf16 v[158:161], v[186:189], v[104:107], v[158:161]
	v_mfma_f32_16x16x32_bf16 v[104:107], v[190:193], v[104:107], v[108:111]
	v_mfma_f32_16x16x32_bf16 v[108:111], v[162:165], v[194:197], v[112:115]
	v_mfma_f32_16x16x32_bf16 v[14:17], v[166:169], v[194:197], v[14:17]
	v_mfma_f32_16x16x32_bf16 v[18:21], v[170:173], v[194:197], v[18:21]
	v_mfma_f32_16x16x32_bf16 v[22:25], v[174:177], v[194:197], v[22:25]
	v_mfma_f32_16x16x32_bf16 v[26:29], v[178:181], v[194:197], v[26:29]
	v_mfma_f32_16x16x32_bf16 v[30:33], v[182:185], v[194:197], v[30:33]
	v_mfma_f32_16x16x32_bf16 v[34:37], v[186:189], v[194:197], v[34:37]
	v_mfma_f32_16x16x32_bf16 v[38:41], v[190:193], v[194:197], v[38:41]
	ds_read_b128 v[112:115], v8
	ds_read_b128 v[162:165], v8 offset:8192
	s_waitcnt vmcnt(8)
	s_barrier
; DI void unpack8(uint4 u, float* v) { v[0] = bflo(u.x); v[1] = bfhi(u.x); v[2] = bflo(u.y); v[3] = bfhi(u.y); v[4] = bflo(u.z); v[5] = bfhi(u.z); v[6] = bflo(u.w); v[7] = bfhi(u.w); }
; #define MFMA16(a, b, c) __builtin_amdgcn_mfma_f32_16x16x32_bf16((a), (b), (c), 0, 0, 0)
; template <bool ROWSS, class AL, class EPI>
; DI void gemm8(unsigned char* smem, const AL& al, const bf16_t* __restrict__ Bt, int K, int m0, int n0, const EPI& epi) {
;     ...
;   for (int t = 0; t < nt; ++t) {
;     if (t + 2 < nt) asm volatile("s_waitcnt vmcnt(8)" ::: "memory");
;     else if (t + 1 < nt) asm volatile("s_waitcnt vmcnt(4)" ::: "memory");
;     else asm volatile("s_waitcnt vmcnt(0)" ::: "memory");
;     __builtin_amdgcn_s_barrier();
;     asm volatile("" ::: "memory");
;     const unsigned char* sa = smem + (t & 3) * 32768 + aoff;
;     const unsigned char* sb = smem + (t & 3) * 32768 + boff;
;     bf16x8 af0, af1, bfr[8];
;     af0 = *(const bf16x8*)(sa);
; #pragma unroll
;     for (int n = 0; n < 8; ++n) bfr[n] = *(const bf16x8*)(sb + n * 1024);
;     af1 = *(const bf16x8*)(sa + 1024);
;     __builtin_amdgcn_sched_barrier(0);
;     if (t + 3 < nt) G8_ISSUE(t + 3);
;     __builtin_amdgcn_sched_barrier(0);
; #pragma unroll
;     for (int n = 0; n < 8; ++n) acc[0][n] = MFMA16(bfr[n], af0, acc[0][n]);
; #pragma unroll
;     for (int n = 0; n < 8; ++n) acc[1][n] = MFMA16(bfr[n], af1, acc[1][n]);
;     __builtin_amdgcn_sched_barrier(0);
;     af0 = *(const bf16x8*)(sa + 2048); af1 = *(const bf16x8*)(sa + 3072);
;     __builtin_amdgcn_sched_barrier(0);
; #pragma unroll
;     for (int n = 0; n < 8; ++n) acc[2][n] = MFMA16(bfr[n], af0, acc[2][n]);
; #pragma unroll
;     for (int n = 0; n < 8; ++n) acc[3][n] = MFMA16(bfr[n], af1, acc[3][n]);
;     __builtin_amdgcn_sched_barrier(0);
;     if (ROWSS) {
;       float v[8];
;       unpack8(*(const uint4*)(smem + (t & 3) * 32768 + ptid * 16), v);
; #pragma unroll
;       for (int j = 0; j < 8; ++j) ss0 += v[j] * v[j];
;       unpack8(*(const uint4*)(smem + (t & 3) * 32768 + ptid * 16 + 8192), v);
; #pragma unroll
;       for (int j = 0; j < 8; ++j) ss1 += v[j] * v[j];
;     }
;   }
	s_waitcnt lgkmcnt(0)
	v_lshlrev_b32_e32 v128, 16, v114
	v_and_b32_e32 v129, 0xffff0000, v114
	v_lshlrev_b32_e32 v114, 16, v162
	v_lshlrev_b32_e32 v142, 16, v115
	v_and_b32_e32 v143, 0xffff0000, v115
	v_and_b32_e32 v115, 0xffff0000, v162
	v_fmac_f32_e32 v136, v114, v114
	v_lshlrev_b32_e32 v149, 16, v163
	v_fmac_f32_e32 v136, v115, v115
	v_and_b32_e32 v162, 0xffff0000, v163
	v_fmac_f32_e32 v136, v149, v149
	v_lshlrev_b32_e32 v9, 16, v112
	v_lshlrev_b32_e32 v163, 16, v164
	v_fmac_f32_e32 v136, v162, v162
	v_and_b32_e32 v67, 0xffff0000, v112
	v_and_b32_e32 v164, 0xffff0000, v164
	v_fmac_f32_e32 v136, v163, v163
	v_fmac_f32_e32 v135, v9, v9
	v_lshlrev_b32_e32 v112, 16, v113
	v_lshlrev_b32_e32 v166, 16, v165
	v_fmac_f32_e32 v136, v164, v164
	v_fmac_f32_e32 v135, v67, v67
	v_and_b32_e32 v113, 0xffff0000, v113
	v_and_b32_e32 v165, 0xffff0000, v165
	v_fmac_f32_e32 v136, v166, v166
	v_fmac_f32_e32 v135, v112, v112
	v_fmac_f32_e32 v136, v165, v165
	v_fmac_f32_e32 v135, v113, v113
	ds_read_b128 v[112:115], v7 offset:49152
	ds_read_b128 v[162:165], v7 offset:50176
	ds_read_b128 v[166:169], v7 offset:51200
	ds_read_b128 v[170:173], v7 offset:52224
	ds_read_b128 v[174:177], v7 offset:53248
	ds_read_b128 v[178:181], v7 offset:54272
	ds_read_b128 v[182:185], v7 offset:55296
	ds_read_b128 v[186:189], v7 offset:56320
	ds_read_b128 v[190:193], v6 offset:32768
	ds_read_b128 v[194:197], v6 offset:33792
	v_fmac_f32_e32 v135, v128, v128
	v_fmac_f32_e32 v135, v129, v129
	v_fmac_f32_e32 v135, v142, v142
	v_fmac_f32_e32 v135, v143, v143
	s_waitcnt lgkmcnt(0)
	v_mfma_f32_16x16x32_bf16 v[2:5], v[112:115], v[190:193], v[2:5]
	v_mfma_f32_16x16x32_bf16 v[50:53], v[162:165], v[190:193], v[50:53]
	v_mfma_f32_16x16x32_bf16 v[54:57], v[166:169], v[190:193], v[54:57]
	v_mfma_f32_16x16x32_bf16 v[58:61], v[170:173], v[190:193], v[58:61]
	v_mfma_f32_16x16x32_bf16 v[62:65], v[174:177], v[190:193], v[62:65]
	v_mfma_f32_16x16x32_bf16 v[68:71], v[178:181], v[190:193], v[68:71]
	v_mfma_f32_16x16x32_bf16 v[72:75], v[182:185], v[190:193], v[72:75]
	v_mfma_f32_16x16x32_bf16 v[42:45], v[186:189], v[190:193], v[42:45]
	ds_read_b128 v[190:193], v6 offset:34816
	v_mfma_f32_16x16x32_bf16 v[76:79], v[112:115], v[194:197], v[76:79]
	v_mfma_f32_16x16x32_bf16 v[80:83], v[162:165], v[194:197], v[80:83]
	v_mfma_f32_16x16x32_bf16 v[84:87], v[166:169], v[194:197], v[84:87]
	v_mfma_f32_16x16x32_bf16 v[88:91], v[170:173], v[194:197], v[88:91]
	v_mfma_f32_16x16x32_bf16 v[92:95], v[174:177], v[194:197], v[92:95]
	v_mfma_f32_16x16x32_bf16 v[96:99], v[178:181], v[194:197], v[96:99]
	v_mfma_f32_16x16x32_bf16 v[100:103], v[182:185], v[194:197], v[100:103]
	v_mfma_f32_16x16x32_bf16 v[46:49], v[186:189], v[194:197], v[46:49]
	ds_read_b128 v[194:197], v6 offset:35840
	s_waitcnt lgkmcnt(1)
	v_mfma_f32_16x16x32_bf16 v[116:119], v[112:115], v[190:193], v[116:119]
	v_mfma_f32_16x16x32_bf16 v[120:123], v[162:165], v[190:193], v[120:123]
	v_mfma_f32_16x16x32_bf16 v[124:127], v[166:169], v[190:193], v[124:127]
	v_mfma_f32_16x16x32_bf16 v[138:141], v[170:173], v[190:193], v[138:141]
	v_mfma_f32_16x16x32_bf16 v[104:107], v[186:189], v[190:193], v[104:107]
	s_waitcnt lgkmcnt(0)
	v_mfma_f32_16x16x32_bf16 v[108:111], v[112:115], v[194:197], v[108:111]
	v_mfma_f32_16x16x32_bf16 v[14:17], v[162:165], v[194:197], v[14:17]
	v_mfma_f32_16x16x32_bf16 v[18:21], v[166:169], v[194:197], v[18:21]
	v_mfma_f32_16x16x32_bf16 v[22:25], v[170:173], v[194:197], v[22:25]
	v_mfma_f32_16x16x32_bf16 v[26:29], v[174:177], v[194:197], v[26:29]
	v_mfma_f32_16x16x32_bf16 v[30:33], v[178:181], v[194:197], v[30:33]
	v_mfma_f32_16x16x32_bf16 v[34:37], v[182:185], v[194:197], v[34:37]
	v_mfma_f32_16x16x32_bf16 v[38:41], v[186:189], v[194:197], v[38:41]
	v_mfma_f32_16x16x32_bf16 v[150:153], v[174:177], v[190:193], v[150:153]
	v_mfma_f32_16x16x32_bf16 v[154:157], v[178:181], v[190:193], v[154:157]
	v_mfma_f32_16x16x32_bf16 v[158:161], v[182:185], v[190:193], v[158:161]
	ds_read_b128 v[112:115], v8 offset:32768
	ds_read_b128 v[6:9], v8 offset:40960
	s_waitcnt vmcnt(4)
	s_barrier
	s_waitcnt lgkmcnt(0)
	v_lshlrev_b32_e32 v129, 16, v114
	v_and_b32_e32 v142, 0xffff0000, v114
	v_lshlrev_b32_e32 v114, 16, v6
	v_and_b32_e32 v6, 0xffff0000, v6
	v_fmac_f32_e32 v136, v114, v114
	v_lshlrev_b32_e32 v143, 16, v115
	v_and_b32_e32 v149, 0xffff0000, v115
	v_lshlrev_b32_e32 v115, 16, v7
	v_fmac_f32_e32 v136, v6, v6
	v_and_b32_e32 v7, 0xffff0000, v7
	v_fmac_f32_e32 v136, v115, v115
	v_lshlrev_b32_e32 v67, 16, v112
	v_lshlrev_b32_e32 v162, 16, v8
	v_fmac_f32_e32 v136, v7, v7
	v_and_b32_e32 v112, 0xffff0000, v112
	v_and_b32_e32 v8, 0xffff0000, v8
	v_fmac_f32_e32 v136, v162, v162
	v_fmac_f32_e32 v135, v67, v67
	v_lshlrev_b32_e32 v128, 16, v113
	v_lshlrev_b32_e32 v163, 16, v9
	v_fmac_f32_e32 v136, v8, v8
	v_fmac_f32_e32 v135, v112, v112
	v_and_b32_e32 v113, 0xffff0000, v113
	v_and_b32_e32 v9, 0xffff0000, v9
	v_fmac_f32_e32 v136, v163, v163
	v_fmac_f32_e32 v135, v128, v128
	v_fmac_f32_e32 v136, v9, v9
	v_fmac_f32_e32 v135, v113, v113
	ds_read_b128 v[6:9], v12 offset:16384
	ds_read_b128 v[112:115], v12 offset:17408
	ds_read_b128 v[162:165], v12 offset:18432
	ds_read_b128 v[166:169], v12 offset:19456
	ds_read_b128 v[170:173], v12 offset:20480
	ds_read_b128 v[174:177], v12 offset:21504
	ds_read_b128 v[178:181], v12 offset:22528
	ds_read_b128 v[182:185], v12 offset:23552
	ds_read_b128 v[186:189], v10
	ds_read_b128 v[190:193], v10 offset:1024
	v_fmac_f32_e32 v135, v129, v129
	v_fmac_f32_e32 v135, v142, v142
	v_fmac_f32_e32 v135, v143, v143
	v_fmac_f32_e32 v135, v149, v149
	s_waitcnt lgkmcnt(0)
; #define MFMA16(a, b, c) __builtin_amdgcn_mfma_f32_16x16x32_bf16((a), (b), (c), 0, 0, 0)
; template <bool ROWSS, class AL, class EPI>
; DI void gemm8(unsigned char* smem, const AL& al, const bf16_t* __restrict__ Bt, int K, int m0, int n0, const EPI& epi) {
;     ...
;     for (int n = 0; n < 8; ++n) acc[0][n] = MFMA16(bfr[n], af0, acc[0][n]);
; #pragma unroll
;     for (int n = 0; n < 8; ++n) acc[1][n] = MFMA16(bfr[n], af1, acc[1][n]);
;     __builtin_amdgcn_sched_barrier(0);
;     af0 = *(const bf16x8*)(sa + 2048); af1 = *(const bf16x8*)(sa + 3072);
;     __builtin_amdgcn_sched_barrier(0);
; #pragma unroll
;     for (int n = 0; n < 8; ++n) acc[2][n] = MFMA16(bfr[n], af0, acc[2][n]);
; #pragma unroll
;     for (int n = 0; n < 8; ++n) acc[3][n] = MFMA16(bfr[n], af1, acc[3][n]);
	v_mfma_f32_16x16x32_bf16 v[2:5], v[6:9], v[186:189], v[2:5]
	v_mfma_f32_16x16x32_bf16 v[50:53], v[112:115], v[186:189], v[50:53]
	v_mfma_f32_16x16x32_bf16 v[54:57], v[162:165], v[186:189], v[54:57]
	v_mfma_f32_16x16x32_bf16 v[58:61], v[166:169], v[186:189], v[58:61]
	v_mfma_f32_16x16x32_bf16 v[62:65], v[170:173], v[186:189], v[62:65]
	v_mfma_f32_16x16x32_bf16 v[68:71], v[174:177], v[186:189], v[68:71]
	v_mfma_f32_16x16x32_bf16 v[72:75], v[178:181], v[186:189], v[72:75]
	v_mfma_f32_16x16x32_bf16 v[42:45], v[182:185], v[186:189], v[42:45]
	v_mfma_f32_16x16x32_bf16 v[76:79], v[6:9], v[190:193], v[76:79]
	v_mfma_f32_16x16x32_bf16 v[80:83], v[112:115], v[190:193], v[80:83]
	v_mfma_f32_16x16x32_bf16 v[84:87], v[162:165], v[190:193], v[84:87]
	v_mfma_f32_16x16x32_bf16 v[88:91], v[166:169], v[190:193], v[88:91]
	v_mfma_f32_16x16x32_bf16 v[92:95], v[170:173], v[190:193], v[92:95]
	v_mfma_f32_16x16x32_bf16 v[96:99], v[174:177], v[190:193], v[96:99]
	v_mfma_f32_16x16x32_bf16 v[100:103], v[178:181], v[190:193], v[100:103]
	v_mfma_f32_16x16x32_bf16 v[186:189], v[182:185], v[190:193], v[46:49]
	s_nop 2
	ds_read_b128 v[46:49], v10 offset:2048
	ds_read_b128 v[190:193], v10 offset:3072
	s_waitcnt lgkmcnt(0)
	v_mfma_f32_16x16x32_bf16 v[116:119], v[6:9], v[46:49], v[116:119]
	v_mfma_f32_16x16x32_bf16 v[120:123], v[112:115], v[46:49], v[120:123]
	v_mfma_f32_16x16x32_bf16 v[124:127], v[162:165], v[46:49], v[124:127]
	v_mfma_f32_16x16x32_bf16 v[138:141], v[166:169], v[46:49], v[138:141]
	v_mfma_f32_16x16x32_bf16 v[104:107], v[182:185], v[46:49], v[104:107]
	v_mfma_f32_16x16x32_bf16 v[108:111], v[6:9], v[190:193], v[108:111]
	v_mfma_f32_16x16x32_bf16 v[112:115], v[112:115], v[190:193], v[14:17]
	v_mfma_f32_16x16x32_bf16 v[150:153], v[170:173], v[46:49], v[150:153]
	v_mfma_f32_16x16x32_bf16 v[154:157], v[174:177], v[46:49], v[154:157]
	v_mfma_f32_16x16x32_bf16 v[158:161], v[178:181], v[46:49], v[158:161]
	v_mfma_f32_16x16x32_bf16 v[162:165], v[162:165], v[190:193], v[18:21]
	v_mfma_f32_16x16x32_bf16 v[166:169], v[166:169], v[190:193], v[22:25]
	v_mfma_f32_16x16x32_bf16 v[170:173], v[170:173], v[190:193], v[26:29]
	v_mfma_f32_16x16x32_bf16 v[174:177], v[174:177], v[190:193], v[30:33]
	v_mfma_f32_16x16x32_bf16 v[178:181], v[178:181], v[190:193], v[34:37]
	v_mfma_f32_16x16x32_bf16 v[182:185], v[182:185], v[190:193], v[38:41]
	ds_read_b128 v[6:9], v13
	ds_read_b128 v[12:15], v13 offset:8192
	s_waitcnt vmcnt(0)
	s_barrier
; DI void unpack8(uint4 u, float* v) { v[0] = bflo(u.x); v[1] = bfhi(u.x); v[2] = bflo(u.y); v[3] = bfhi(u.y); v[4] = bflo(u.z); v[5] = bfhi(u.z); v[6] = bflo(u.w); v[7] = bfhi(u.w); }
; #define MFMA16(a, b, c) __builtin_amdgcn_mfma_f32_16x16x32_bf16((a), (b), (c), 0, 0, 0)
; template <bool ROWSS, class AL, class EPI>
; DI void gemm8(unsigned char* smem, const AL& al, const bf16_t* __restrict__ Bt, int K, int m0, int n0, const EPI& epi) {
;     ...
;     const unsigned char* sa = smem + (t & 3) * 32768 + aoff;
;     const unsigned char* sb = smem + (t & 3) * 32768 + boff;
;     bf16x8 af0, af1, bfr[8];
;     af0 = *(const bf16x8*)(sa);
; #pragma unroll
;     for (int n = 0; n < 8; ++n) bfr[n] = *(const bf16x8*)(sb + n * 1024);
;     af1 = *(const bf16x8*)(sa + 1024);
;     __builtin_amdgcn_sched_barrier(0);
;     if (t + 3 < nt) G8_ISSUE(t + 3);
;     __builtin_amdgcn_sched_barrier(0);
; #pragma unroll
;     for (int n = 0; n < 8; ++n) acc[0][n] = MFMA16(bfr[n], af0, acc[0][n]);
; #pragma unroll
;     for (int n = 0; n < 8; ++n) acc[1][n] = MFMA16(bfr[n], af1, acc[1][n]);
;     __builtin_amdgcn_sched_barrier(0);
;     af0 = *(const bf16x8*)(sa + 2048); af1 = *(const bf16x8*)(sa + 3072);
;     __builtin_amdgcn_sched_barrier(0);
; #pragma unroll
;     for (int n = 0; n < 8; ++n) acc[2][n] = MFMA16(bfr[n], af0, acc[2][n]);
; #pragma unroll
;     for (int n = 0; n < 8; ++n) acc[3][n] = MFMA16(bfr[n], af1, acc[3][n]);
;     __builtin_amdgcn_sched_barrier(0);
;     if (ROWSS) {
;       float v[8];
;       unpack8(*(const uint4*)(smem + (t & 3) * 32768 + ptid * 16), v);
; #pragma unroll
;       for (int j = 0; j < 8; ++j) ss0 += v[j] * v[j];
;       unpack8(*(const uint4*)(smem + (t & 3) * 32768 + ptid * 16 + 8192), v);
; #pragma unroll
;       for (int j = 0; j < 8; ++j) ss1 += v[j] * v[j];
;     }
;     ...
;   if (ROWSS) {
;     ss0 += __shfl_xor(ss0, 1); ss0 += __shfl_xor(ss0, 2);
;     ss1 += __shfl_xor(ss1, 1); ss1 += __shfl_xor(ss1, 2);
;     if ((lane & 3) == 0) { rowss[Rb] = ss0; rowss[Rb + 128] = ss1; }
;   }
	ds_read_b128 v[190:193], v11 offset:16384
	ds_read_b128 v[194:197], v11 offset:17408
	ds_read_b128 v[198:201], v11 offset:18432
	ds_read_b128 v[206:209], v11 offset:19456
	ds_read_b128 v[210:213], v11 offset:20480
	ds_read_b128 v[214:217], v11 offset:21504
	ds_read_b128 v[218:221], v11 offset:22528
	ds_read_b128 v[222:225], v11 offset:23552
	ds_read_b128 v[30:33], v66
	ds_read_b128 v[226:229], v66 offset:1024
	s_waitcnt lgkmcnt(0)
	v_lshlrev_b32_e32 v10, 16, v6
	v_lshlrev_b32_e32 v19, 16, v12
	v_and_b32_e32 v6, 0xffff0000, v6
	v_and_b32_e32 v12, 0xffff0000, v12
	v_fmac_f32_e32 v136, v19, v19
	v_fmac_f32_e32 v135, v10, v10
	v_lshlrev_b32_e32 v16, 16, v7
	v_lshlrev_b32_e32 v20, 16, v13
	v_fmac_f32_e32 v136, v12, v12
	v_fmac_f32_e32 v135, v6, v6
	v_and_b32_e32 v7, 0xffff0000, v7
	v_and_b32_e32 v13, 0xffff0000, v13
	v_fmac_f32_e32 v136, v20, v20
	v_fmac_f32_e32 v135, v16, v16
	v_lshlrev_b32_e32 v17, 16, v8
	v_lshlrev_b32_e32 v21, 16, v14
	v_fmac_f32_e32 v136, v13, v13
	v_fmac_f32_e32 v135, v7, v7
	v_and_b32_e32 v8, 0xffff0000, v8
	v_and_b32_e32 v14, 0xffff0000, v14
	v_fmac_f32_e32 v136, v21, v21
	v_fmac_f32_e32 v135, v17, v17
	v_lshlrev_b32_e32 v18, 16, v9
	v_lshlrev_b32_e32 v22, 16, v15
	v_fmac_f32_e32 v136, v14, v14
	v_fmac_f32_e32 v135, v8, v8
	v_and_b32_e32 v9, 0xffff0000, v9
	v_and_b32_e32 v15, 0xffff0000, v15
	v_fmac_f32_e32 v136, v22, v22
	v_fmac_f32_e32 v135, v18, v18
	v_fmac_f32_e32 v136, v15, v15
	v_fmac_f32_e32 v135, v9, v9
	v_mfma_f32_16x16x32_bf16 v[2:5], v[190:193], v[30:33], v[2:5]
	v_mfma_f32_16x16x32_bf16 v[6:9], v[194:197], v[30:33], v[50:53]
	v_mfma_f32_16x16x32_bf16 v[10:13], v[198:201], v[30:33], v[54:57]
	v_mfma_f32_16x16x32_bf16 v[14:17], v[206:209], v[30:33], v[58:61]
	v_mfma_f32_16x16x32_bf16 v[18:21], v[210:213], v[30:33], v[62:65]
	v_mfma_f32_16x16x32_bf16 v[22:25], v[214:217], v[30:33], v[68:71]
	v_mfma_f32_16x16x32_bf16 v[26:29], v[218:221], v[30:33], v[72:75]
	v_mfma_f32_16x16x32_bf16 v[30:33], v[222:225], v[30:33], v[42:45]
	v_mfma_f32_16x16x32_bf16 v[34:37], v[190:193], v[226:229], v[76:79]
	v_mfma_f32_16x16x32_bf16 v[38:41], v[194:197], v[226:229], v[80:83]
	v_mfma_f32_16x16x32_bf16 v[42:45], v[198:201], v[226:229], v[84:87]
	v_mfma_f32_16x16x32_bf16 v[46:49], v[206:209], v[226:229], v[88:91]
	v_mfma_f32_16x16x32_bf16 v[50:53], v[210:213], v[226:229], v[92:95]
	v_mfma_f32_16x16x32_bf16 v[54:57], v[214:217], v[226:229], v[96:99]
	v_mfma_f32_16x16x32_bf16 v[58:61], v[218:221], v[226:229], v[100:103]
	v_mfma_f32_16x16x32_bf16 v[62:65], v[222:225], v[226:229], v[186:189]
	s_nop 0
	ds_read_b128 v[94:97], v66 offset:2048
	s_nop 0
	ds_read_b128 v[186:189], v66 offset:3072
	s_waitcnt lgkmcnt(0)
	v_mfma_f32_16x16x32_bf16 v[66:69], v[190:193], v[94:97], v[116:119]
	v_mfma_f32_16x16x32_bf16 v[70:73], v[194:197], v[94:97], v[120:123]
	v_mfma_f32_16x16x32_bf16 v[74:77], v[198:201], v[94:97], v[124:127]
	v_mfma_f32_16x16x32_bf16 v[78:81], v[206:209], v[94:97], v[138:141]
	v_mfma_f32_16x16x32_bf16 v[82:85], v[210:213], v[94:97], v[150:153]
	v_mfma_f32_16x16x32_bf16 v[86:89], v[214:217], v[94:97], v[154:157]
	v_mfma_f32_16x16x32_bf16 v[90:93], v[218:221], v[94:97], v[158:161]
	v_mfma_f32_16x16x32_bf16 v[94:97], v[222:225], v[94:97], v[104:107]
	v_mfma_f32_16x16x32_bf16 v[98:101], v[190:193], v[186:189], v[108:111]
	v_mfma_f32_16x16x32_bf16 v[102:105], v[194:197], v[186:189], v[112:115]
	v_mfma_f32_16x16x32_bf16 v[106:109], v[198:201], v[186:189], v[162:165]
	v_mfma_f32_16x16x32_bf16 v[110:113], v[206:209], v[186:189], v[166:169]
	v_mfma_f32_16x16x32_bf16 v[114:117], v[210:213], v[186:189], v[170:173]
	v_mfma_f32_16x16x32_bf16 v[118:121], v[214:217], v[186:189], v[174:177]
	v_mfma_f32_16x16x32_bf16 v[122:125], v[218:221], v[186:189], v[178:181]
	v_mfma_f32_16x16x32_bf16 v[126:129], v[222:225], v[186:189], v[182:185]
	ds_read_b128 v[138:141], v137
	ds_read_b128 v[150:153], v137 offset:8192
	v_cmp_lt_i32_e32 vcc, v146, v147
	s_waitcnt vmcnt(0) lgkmcnt(0)
	s_barrier
	v_lshlrev_b32_e32 v137, 16, v138
	v_and_b32_e32 v138, 0xffff0000, v138
	v_fmac_f32_e32 v135, v137, v137
	v_lshlrev_b32_e32 v142, 16, v139
	v_fmac_f32_e32 v135, v138, v138
	v_and_b32_e32 v139, 0xffff0000, v139
	v_fmac_f32_e32 v135, v142, v142
	v_lshlrev_b32_e32 v143, 16, v140
	v_fmac_f32_e32 v135, v139, v139
	v_and_b32_e32 v140, 0xffff0000, v140
	v_lshlrev_b32_e32 v154, 16, v150
	v_fmac_f32_e32 v135, v143, v143
	v_lshlrev_b32_e32 v149, 16, v141
	v_and_b32_e32 v150, 0xffff0000, v150
	v_fmac_f32_e32 v136, v154, v154
	v_fmac_f32_e32 v135, v140, v140
	v_and_b32_e32 v141, 0xffff0000, v141
	v_lshlrev_b32_e32 v155, 16, v151
	v_fmac_f32_e32 v136, v150, v150
	v_fmac_f32_e32 v135, v149, v149
	v_cndmask_b32_e32 v137, v145, v146, vcc
	v_and_b32_e32 v151, 0xffff0000, v151
	v_fmac_f32_e32 v136, v155, v155
	v_fmac_f32_e32 v135, v141, v141
	v_lshlrev_b32_e32 v137, 2, v137
	v_lshlrev_b32_e32 v156, 16, v152
	v_fmac_f32_e32 v136, v151, v151
	ds_bpermute_b32 v138, v137, v135
	v_and_b32_e32 v152, 0xffff0000, v152
	v_fmac_f32_e32 v136, v156, v156
	v_lshlrev_b32_e32 v157, 16, v153
	v_fmac_f32_e32 v136, v152, v152
	v_and_b32_e32 v153, 0xffff0000, v153
	v_fmac_f32_e32 v136, v157, v157
	v_fmac_f32_e32 v136, v153, v153
	s_waitcnt lgkmcnt(0)
	v_add_f32_e32 v135, v135, v138
	ds_bpermute_b32 v138, v137, v136
	v_cmp_lt_i32_e32 vcc, v148, v147
	s_waitcnt lgkmcnt(0)
	v_add_f32_e32 v136, v136, v138
	v_cndmask_b32_e32 v137, v145, v148, vcc
	v_lshlrev_b32_e32 v139, 2, v137
	ds_bpermute_b32 v137, v139, v135
	ds_bpermute_b32 v138, v139, v136
	v_and_b32_e32 v139, 3, v130
	v_cmp_eq_u32_e32 vcc, 0, v139
	s_and_saveexec_b64 s[0:1], vcc
	s_cbranch_execz .LBB0_1302
	v_lshl_add_u32 v134, v134, 2, 0
	v_add_u32_e32 v134, 0x21000, v134
	s_waitcnt lgkmcnt(1)
	v_add_f32_e32 v135, v135, v137
	s_waitcnt lgkmcnt(0)
	v_add_f32_e32 v136, v136, v138
	ds_write2st64_b32 v134, v135, v136 offset1:2
